# A/B: all s_setprio removed from the K-loop MFMA segments (on top of v47 edits)
# baseline (speedup 1.0000x reference)
; #define PG8_STAGE(bufoff, gbase, voff) do { _Pragma("unroll") for (int _i = 0; _i < 2; ++_i) \
;         __builtin_amdgcn_global_load_lds((const unsigned*)((const char*)(gbase) + (voff)[_i]), (PG8_LAS unsigned*)(lds + (bufoff) + ldsw + _i * 8192), 16, 0, 0); } while (0)
; #define PG8_LDA(dst, b, h) do { _Pragma("unroll") for (int m = 0; m < 4; ++m) _Pragma("unroll") for (int k = 0; k < 2; ++k) dst[m][k] = *(const PG8_LAS bf16x8*)(lds + PG8_SA(b, h) + aoff + m * 2048 + k * 1024); } while (0)
; #define PG8_LDB(dst, b, h) do { _Pragma("unroll") for (int n = 0; n < 2; ++n) _Pragma("unroll") for (int k = 0; k < 2; ++k) dst[n][k] = *(const PG8_LAS bf16x8*)(lds + PG8_SB(b, h) + boff + n * 2048 + k * 1024); } while (0)
; #define PG8_MMA(ai, bj, At, Bt) do { __builtin_amdgcn_s_setprio(1); _Pragma("unroll") for (int m = 0; m < 4; ++m) _Pragma("unroll") for (int n = 0; n < 2; ++n) _Pragma("unroll") for (int k = 0; k < 2; ++k) \
;         acc[ai][bj][m][n] = __builtin_amdgcn_mfma_f32_16x16x32_bf16(Bt[n][k], At[m][k], acc[ai][bj][m][n], 0, 0, 0); __builtin_amdgcn_s_setprio(0); } while (0)
; #define PG8_WAIT_V(n) asm volatile("s_waitcnt vmcnt(" #n ")" ::: "memory")
; #define PG8_WAIT_L(n) asm volatile("s_waitcnt lgkmcnt(" #n ")" ::: "memory")
; template <class Epi, class Sched, bool ALIGN_EPI = false, bool SP2 = false>
; __device__ __forceinline__ void gemm_phase(PG8_LAS unsigned char* lds, const Gemm g, const Sched& S, const Epi& E) {
;     ...
;             const bool last = (t == nt - 2);
;             const char* a1 = cA + (size_t)(t + 1) * kstep;
;             const char* a2 = last ? nA : cA + (size_t)(t + 2) * kstep; const char* b2 = last ? nB : cB + (size_t)(t + 2) * kstep;
;             const char* a3 = a2 + kstep; const char* b3 = b2 + kstep;
;             if (last && has_next) S.a_ready(nxt);
;             if constexpr (SP2) {
;             PG8_LDB(B0, 0, 0); PG8_LDB(B1, 0, 1); PG8_SCHED; PG8_LDA(At, 0, 0); PG8_STAGE(PG8_SA(1, 1), a1 + hstep, voffA);
;             PG8_WAIT_V(8); PG8_WAIT_L(0); PG8_BAR; PG8_MMA(0, 0, At, B0); PG8_MMA(0, 1, At, B1); PG8_BAR; PG8_SCHED;
;             PG8_LDA(At, 0, 1); PG8_STAGE(PG8_SB(0, 0), b2, voffB); PG8_STAGE(PG8_SB(0, 1), b2 + hstep, voffB); PG8_STAGE(PG8_SA(0, 0), a2, voffA);
;             PG8_WAIT_V(8); PG8_WAIT_L(0); PG8_BAR; PG8_MMA(1, 0, At, B0); PG8_MMA(1, 1, At, B1); PG8_BAR; PG8_SCHED;
.Labo_peel:
	ds_read_b128 v[68:71], v254
	ds_read_b128 v[72:75], v254 offset:1024
	ds_read_b128 v[76:79], v254 offset:2048
	ds_read_b128 v[80:83], v254 offset:3072
	ds_read_b128 v[174:177], v254 offset:16384
	ds_read_b128 v[182:185], v254 offset:17408
	ds_read_b128 v[186:189], v254 offset:18432
	ds_read_b128 v[210:213], v254 offset:19456
	s_add_u32 s2, s0, 0xfffc0080
	s_addc_u32 s3, s1, -1
	s_cmp_eq_u32 s56, 12
	s_cselect_b32 s5, s27, s3
	s_cselect_b32 s4, s52, s2
	s_cselect_b32 s3, s25, s55
	s_cselect_b32 s2, s53, s54
	s_add_i32 m0, s29, 0xc000
	ds_read_b128 v[214:217], v179
	ds_read_b128 v[218:221], v179 offset:1024
	ds_read_b128 v[222:225], v179 offset:2048
	ds_read_b128 v[226:229], v179 offset:3072
	ds_read_b128 v[230:233], v179 offset:4096
	ds_read_b128 v[234:237], v179 offset:5120
	ds_read_b128 v[238:241], v179 offset:6144
	ds_read_b128 v[242:245], v179 offset:7168
	global_load_lds_dwordx4 v170, s[0:1]
	s_add_i32 m0, s29, 0xe000
	s_nop 0
	global_load_lds_dwordx4 v172, s[0:1]
	s_waitcnt vmcnt(8)
	s_waitcnt lgkmcnt(0)
	s_barrier
	v_mfma_f32_16x16x32_bf16 v[140:143], v[68:71], v[214:217], 0
	v_mfma_f32_16x16x32_bf16 v[136:139], v[76:79], v[214:217], 0
	v_mfma_f32_16x16x32_bf16 v[124:127], v[68:71], v[222:225], 0
	v_mfma_f32_16x16x32_bf16 v[120:123], v[76:79], v[222:225], 0
	v_mfma_f32_16x16x32_bf16 v[108:111], v[68:71], v[230:233], 0
	v_mfma_f32_16x16x32_bf16 v[104:107], v[76:79], v[230:233], 0
	v_mfma_f32_16x16x32_bf16 v[92:95], v[68:71], v[238:241], 0
	v_mfma_f32_16x16x32_bf16 v[88:91], v[76:79], v[238:241], 0
	v_mfma_f32_16x16x32_bf16 v[140:143], v[72:75], v[218:221], v[140:143]
	v_mfma_f32_16x16x32_bf16 v[136:139], v[80:83], v[218:221], v[136:139]
	v_mfma_f32_16x16x32_bf16 v[124:127], v[72:75], v[226:229], v[124:127]
	v_mfma_f32_16x16x32_bf16 v[120:123], v[80:83], v[226:229], v[120:123]
	v_mfma_f32_16x16x32_bf16 v[108:111], v[72:75], v[234:237], v[108:111]
	v_mfma_f32_16x16x32_bf16 v[104:107], v[80:83], v[234:237], v[104:107]
	v_mfma_f32_16x16x32_bf16 v[92:95], v[72:75], v[242:245], v[92:95]
	v_mfma_f32_16x16x32_bf16 v[88:91], v[80:83], v[242:245], v[88:91]
	v_mfma_f32_16x16x32_bf16 v[132:135], v[174:177], v[214:217], 0
	v_mfma_f32_16x16x32_bf16 v[128:131], v[186:189], v[214:217], 0
	v_mfma_f32_16x16x32_bf16 v[116:119], v[174:177], v[222:225], 0
	v_mfma_f32_16x16x32_bf16 v[112:115], v[186:189], v[222:225], 0
	v_mfma_f32_16x16x32_bf16 v[100:103], v[174:177], v[230:233], 0
	v_mfma_f32_16x16x32_bf16 v[96:99], v[186:189], v[230:233], 0
	v_mfma_f32_16x16x32_bf16 v[84:87], v[174:177], v[238:241], 0
	v_mfma_f32_16x16x32_bf16 v[64:67], v[186:189], v[238:241], 0
	v_mfma_f32_16x16x32_bf16 v[132:135], v[182:185], v[218:221], v[132:135]
	v_mfma_f32_16x16x32_bf16 v[128:131], v[210:213], v[218:221], v[128:131]
	v_mfma_f32_16x16x32_bf16 v[116:119], v[182:185], v[226:229], v[116:119]
	v_mfma_f32_16x16x32_bf16 v[112:115], v[210:213], v[226:229], v[112:115]
	v_mfma_f32_16x16x32_bf16 v[100:103], v[182:185], v[234:237], v[100:103]
	v_mfma_f32_16x16x32_bf16 v[96:99], v[210:213], v[234:237], v[96:99]
	v_mfma_f32_16x16x32_bf16 v[84:87], v[182:185], v[242:245], v[84:87]
	v_mfma_f32_16x16x32_bf16 v[64:67], v[210:213], v[242:245], v[64:67]
	s_barrier
	s_mov_b32 m0, s30
	s_add_u32 s58, s2, 0x40000
	s_addc_u32 s59, s3, 0
	ds_read_b128 v[214:217], v179 offset:16384
	ds_read_b128 v[218:221], v179 offset:17408
	ds_read_b128 v[222:225], v179 offset:18432
	ds_read_b128 v[226:229], v179 offset:19456
	ds_read_b128 v[230:233], v179 offset:20480
	ds_read_b128 v[234:237], v179 offset:21504
	ds_read_b128 v[238:241], v179 offset:22528
	ds_read_b128 v[242:245], v179 offset:23552
	global_load_lds_dwordx4 v166, s[2:3]
	s_mov_b32 m0, s31
	s_nop 0
	global_load_lds_dwordx4 v162, s[2:3]
	s_mov_b32 m0, s33
	s_nop 0
	global_load_lds_dwordx4 v166, s[58:59]
	s_mov_b32 m0, s34
	s_nop 0
	global_load_lds_dwordx4 v162, s[58:59]
	s_mov_b32 m0, s29
	s_nop 0
	global_load_lds_dwordx4 v168, s[4:5]
	s_mov_b32 m0, s35
	s_nop 0
	global_load_lds_dwordx4 v164, s[4:5]
	s_waitcnt vmcnt(8)
	s_waitcnt lgkmcnt(0)
	s_barrier
	v_mfma_f32_16x16x32_bf16 v[60:63], v[68:71], v[214:217], 0
	v_mfma_f32_16x16x32_bf16 v[56:59], v[76:79], v[214:217], 0
	v_mfma_f32_16x16x32_bf16 v[44:47], v[68:71], v[222:225], 0
	v_mfma_f32_16x16x32_bf16 v[40:43], v[76:79], v[222:225], 0
	v_mfma_f32_16x16x32_bf16 v[28:31], v[68:71], v[230:233], 0
	v_mfma_f32_16x16x32_bf16 v[24:27], v[76:79], v[230:233], 0
	v_mfma_f32_16x16x32_bf16 v[12:15], v[68:71], v[238:241], 0
	v_mfma_f32_16x16x32_bf16 v[8:11], v[76:79], v[238:241], 0
	v_mfma_f32_16x16x32_bf16 v[60:63], v[72:75], v[218:221], v[60:63]
	v_mfma_f32_16x16x32_bf16 v[56:59], v[80:83], v[218:221], v[56:59]
	v_mfma_f32_16x16x32_bf16 v[44:47], v[72:75], v[226:229], v[44:47]
	v_mfma_f32_16x16x32_bf16 v[40:43], v[80:83], v[226:229], v[40:43]
	v_mfma_f32_16x16x32_bf16 v[28:31], v[72:75], v[234:237], v[28:31]
	v_mfma_f32_16x16x32_bf16 v[24:27], v[80:83], v[234:237], v[24:27]
	v_mfma_f32_16x16x32_bf16 v[12:15], v[72:75], v[242:245], v[12:15]
	v_mfma_f32_16x16x32_bf16 v[8:11], v[80:83], v[242:245], v[8:11]
	v_mfma_f32_16x16x32_bf16 v[52:55], v[174:177], v[214:217], 0
	v_mfma_f32_16x16x32_bf16 v[48:51], v[186:189], v[214:217], 0
	v_mfma_f32_16x16x32_bf16 v[36:39], v[174:177], v[222:225], 0
	v_mfma_f32_16x16x32_bf16 v[32:35], v[186:189], v[222:225], 0
	v_mfma_f32_16x16x32_bf16 v[20:23], v[174:177], v[230:233], 0
	v_mfma_f32_16x16x32_bf16 v[16:19], v[186:189], v[230:233], 0
	v_mfma_f32_16x16x32_bf16 v[4:7], v[174:177], v[238:241], 0
	v_mfma_f32_16x16x32_bf16 v[0:3], v[186:189], v[238:241], 0
	v_mfma_f32_16x16x32_bf16 v[52:55], v[182:185], v[218:221], v[52:55]
	v_mfma_f32_16x16x32_bf16 v[48:51], v[210:213], v[218:221], v[48:51]
	v_mfma_f32_16x16x32_bf16 v[36:39], v[182:185], v[226:229], v[36:39]
	v_mfma_f32_16x16x32_bf16 v[32:35], v[210:213], v[226:229], v[32:35]
	v_mfma_f32_16x16x32_bf16 v[20:23], v[182:185], v[234:237], v[20:23]
	v_mfma_f32_16x16x32_bf16 v[16:19], v[210:213], v[234:237], v[16:19]
	v_mfma_f32_16x16x32_bf16 v[4:7], v[182:185], v[242:245], v[4:7]
	v_mfma_f32_16x16x32_bf16 v[0:3], v[210:213], v[242:245], v[0:3]
	s_barrier
; #define PG8_STAGE(bufoff, gbase, voff) do { _Pragma("unroll") for (int _i = 0; _i < 2; ++_i) \
;         __builtin_amdgcn_global_load_lds((const unsigned*)((const char*)(gbase) + (voff)[_i]), (PG8_LAS unsigned*)(lds + (bufoff) + ldsw + _i * 8192), 16, 0, 0); } while (0)
; #define PG8_LDA(dst, b, h) do { _Pragma("unroll") for (int m = 0; m < 4; ++m) _Pragma("unroll") for (int k = 0; k < 2; ++k) dst[m][k] = *(const PG8_LAS bf16x8*)(lds + PG8_SA(b, h) + aoff + m * 2048 + k * 1024); } while (0)
; #define PG8_LDB(dst, b, h) do { _Pragma("unroll") for (int n = 0; n < 2; ++n) _Pragma("unroll") for (int k = 0; k < 2; ++k) dst[n][k] = *(const PG8_LAS bf16x8*)(lds + PG8_SB(b, h) + boff + n * 2048 + k * 1024); } while (0)
; #define PG8_MMA(ai, bj, At, Bt) do { __builtin_amdgcn_s_setprio(1); _Pragma("unroll") for (int m = 0; m < 4; ++m) _Pragma("unroll") for (int n = 0; n < 2; ++n) _Pragma("unroll") for (int k = 0; k < 2; ++k) \
;         acc[ai][bj][m][n] = __builtin_amdgcn_mfma_f32_16x16x32_bf16(Bt[n][k], At[m][k], acc[ai][bj][m][n], 0, 0, 0); __builtin_amdgcn_s_setprio(0); } while (0)
; #define PG8_WAIT_V(n) asm volatile("s_waitcnt vmcnt(" #n ")" ::: "memory")
; #define PG8_WAIT_L(n) asm volatile("s_waitcnt lgkmcnt(" #n ")" ::: "memory")
; #define PG8_BAR __builtin_amdgcn_s_barrier()
; #define PG8_SCHED __builtin_amdgcn_sched_barrier(0)
; template <class Epi, class Sched, bool ALIGN_EPI = false, bool SP2 = false>
; __device__ __forceinline__ void gemm_phase(PG8_LAS unsigned char* lds, const Gemm g, const Sched& S, const Epi& E) {
;     ...
;         for (int t = 0; t < nt; t += 2) {
;     ...
;             PG8_LDB(B0, 1, 0); PG8_LDB(B1, 1, 1); PG8_SCHED; PG8_LDA(At, 1, 0); PG8_STAGE(PG8_SA(0, 1), a2 + hstep, voffA);
;             PG8_WAIT_V(8); PG8_WAIT_L(0); PG8_BAR; PG8_MMA(0, 0, At, B0); PG8_MMA(0, 1, At, B1); PG8_BAR; PG8_SCHED;
;             PG8_LDA(At, 1, 1); PG8_STAGE(PG8_SB(1, 0), b3, voffB); PG8_STAGE(PG8_SB(1, 1), b3 + hstep, voffB); PG8_STAGE(PG8_SA(1, 0), a3, voffA);
;             PG8_WAIT_V(8); PG8_WAIT_L(0); PG8_BAR; PG8_MMA(1, 0, At, B0); PG8_MMA(1, 1, At, B1); PG8_BAR; PG8_SCHED;
	ds_read_b128 v[68:71], v254 offset:32768
	ds_read_b128 v[72:75], v254 offset:33792
	ds_read_b128 v[76:79], v254 offset:34816
	ds_read_b128 v[80:83], v254 offset:35840
	ds_read_b128 v[174:177], v254 offset:49152
	ds_read_b128 v[182:185], v254 offset:50176
	ds_read_b128 v[186:189], v254 offset:51200
	ds_read_b128 v[210:213], v254 offset:52224
	s_add_u32 s4, s4, 0x40000
	s_addc_u32 s5, s5, 0
	s_mov_b32 m0, s40
	ds_read_b128 v[214:217], v179 offset:32768
	ds_read_b128 v[218:221], v179 offset:33792
	ds_read_b128 v[222:225], v179 offset:34816
	ds_read_b128 v[226:229], v179 offset:35840
	ds_read_b128 v[230:233], v179 offset:36864
	ds_read_b128 v[234:237], v179 offset:37888
	ds_read_b128 v[238:241], v179 offset:38912
	ds_read_b128 v[242:245], v179 offset:39936
	global_load_lds_dwordx4 v168, s[4:5]
	s_mov_b32 m0, s41
	s_nop 0
	global_load_lds_dwordx4 v164, s[4:5]
	s_waitcnt vmcnt(8)
	s_waitcnt lgkmcnt(0)
	s_barrier
	v_mfma_f32_16x16x32_bf16 v[140:143], v[68:71], v[214:217], v[140:143]
	v_mfma_f32_16x16x32_bf16 v[136:139], v[76:79], v[214:217], v[136:139]
	v_mfma_f32_16x16x32_bf16 v[124:127], v[68:71], v[222:225], v[124:127]
	v_mfma_f32_16x16x32_bf16 v[120:123], v[76:79], v[222:225], v[120:123]
	v_mfma_f32_16x16x32_bf16 v[108:111], v[68:71], v[230:233], v[108:111]
	v_mfma_f32_16x16x32_bf16 v[104:107], v[76:79], v[230:233], v[104:107]
	v_mfma_f32_16x16x32_bf16 v[92:95], v[68:71], v[238:241], v[92:95]
	v_mfma_f32_16x16x32_bf16 v[88:91], v[76:79], v[238:241], v[88:91]
	v_mfma_f32_16x16x32_bf16 v[140:143], v[72:75], v[218:221], v[140:143]
	v_mfma_f32_16x16x32_bf16 v[136:139], v[80:83], v[218:221], v[136:139]
	v_mfma_f32_16x16x32_bf16 v[124:127], v[72:75], v[226:229], v[124:127]
	v_mfma_f32_16x16x32_bf16 v[120:123], v[80:83], v[226:229], v[120:123]
	v_mfma_f32_16x16x32_bf16 v[108:111], v[72:75], v[234:237], v[108:111]
	v_mfma_f32_16x16x32_bf16 v[104:107], v[80:83], v[234:237], v[104:107]
	v_mfma_f32_16x16x32_bf16 v[92:95], v[72:75], v[242:245], v[92:95]
	v_mfma_f32_16x16x32_bf16 v[88:91], v[80:83], v[242:245], v[88:91]
	v_mfma_f32_16x16x32_bf16 v[132:135], v[174:177], v[214:217], v[132:135]
	v_mfma_f32_16x16x32_bf16 v[128:131], v[186:189], v[214:217], v[128:131]
	v_mfma_f32_16x16x32_bf16 v[116:119], v[174:177], v[222:225], v[116:119]
	v_mfma_f32_16x16x32_bf16 v[112:115], v[186:189], v[222:225], v[112:115]
	v_mfma_f32_16x16x32_bf16 v[100:103], v[174:177], v[230:233], v[100:103]
	v_mfma_f32_16x16x32_bf16 v[96:99], v[186:189], v[230:233], v[96:99]
	v_mfma_f32_16x16x32_bf16 v[84:87], v[174:177], v[238:241], v[84:87]
	v_mfma_f32_16x16x32_bf16 v[64:67], v[186:189], v[238:241], v[64:67]
	v_mfma_f32_16x16x32_bf16 v[132:135], v[182:185], v[218:221], v[132:135]
	v_mfma_f32_16x16x32_bf16 v[128:131], v[210:213], v[218:221], v[128:131]
	v_mfma_f32_16x16x32_bf16 v[116:119], v[182:185], v[226:229], v[116:119]
	v_mfma_f32_16x16x32_bf16 v[112:115], v[210:213], v[226:229], v[112:115]
	v_mfma_f32_16x16x32_bf16 v[100:103], v[182:185], v[234:237], v[100:103]
	v_mfma_f32_16x16x32_bf16 v[96:99], v[210:213], v[234:237], v[96:99]
	v_mfma_f32_16x16x32_bf16 v[84:87], v[182:185], v[242:245], v[84:87]
	v_mfma_f32_16x16x32_bf16 v[64:67], v[210:213], v[242:245], v[64:67]
	s_barrier
	s_mov_b32 m0, s45
	s_add_u32 s2, s2, 0x40080
	s_addc_u32 s3, s3, 0
	ds_read_b128 v[214:217], v179 offset:49152
	ds_read_b128 v[218:221], v179 offset:50176
	ds_read_b128 v[222:225], v179 offset:51200
	ds_read_b128 v[226:229], v179 offset:52224
	ds_read_b128 v[230:233], v179 offset:53248
	ds_read_b128 v[234:237], v179 offset:54272
	ds_read_b128 v[238:241], v179 offset:55296
	ds_read_b128 v[242:245], v179 offset:56320
	s_add_u32 s98, s2, 0xfffc0000
	s_addc_u32 s99, s3, -1
	global_load_lds_dwordx4 v166, s[98:99]
	s_mov_b32 m0, s46
	s_nop 0
	global_load_lds_dwordx4 v162, s[98:99]
	s_mov_b32 m0, s49
	s_nop 0
	global_load_lds_dwordx4 v166, s[2:3]
	s_mov_b32 m0, s50
	s_nop 0
	global_load_lds_dwordx4 v162, s[2:3]
	s_mov_b32 m0, s47
	s_nop 0
	s_add_u32 s100, s4, 0xfffc0080
	s_addc_u32 s101, s5, -1
	global_load_lds_dwordx4 v168, s[100:101]
	s_mov_b32 m0, s48
	s_nop 0
	global_load_lds_dwordx4 v164, s[100:101]
	s_waitcnt vmcnt(8)
	s_waitcnt lgkmcnt(0)
	s_barrier
	v_mfma_f32_16x16x32_bf16 v[60:63], v[68:71], v[214:217], v[60:63]
	v_mfma_f32_16x16x32_bf16 v[56:59], v[76:79], v[214:217], v[56:59]
	v_mfma_f32_16x16x32_bf16 v[44:47], v[68:71], v[222:225], v[44:47]
	v_mfma_f32_16x16x32_bf16 v[40:43], v[76:79], v[222:225], v[40:43]
	v_mfma_f32_16x16x32_bf16 v[28:31], v[68:71], v[230:233], v[28:31]
	v_mfma_f32_16x16x32_bf16 v[24:27], v[76:79], v[230:233], v[24:27]
	v_mfma_f32_16x16x32_bf16 v[12:15], v[68:71], v[238:241], v[12:15]
	v_mfma_f32_16x16x32_bf16 v[8:11], v[76:79], v[238:241], v[8:11]
	v_mfma_f32_16x16x32_bf16 v[60:63], v[72:75], v[218:221], v[60:63]
	v_mfma_f32_16x16x32_bf16 v[56:59], v[80:83], v[218:221], v[56:59]
	v_mfma_f32_16x16x32_bf16 v[44:47], v[72:75], v[226:229], v[44:47]
	v_mfma_f32_16x16x32_bf16 v[40:43], v[80:83], v[226:229], v[40:43]
	v_mfma_f32_16x16x32_bf16 v[28:31], v[72:75], v[234:237], v[28:31]
	v_mfma_f32_16x16x32_bf16 v[24:27], v[80:83], v[234:237], v[24:27]
	v_mfma_f32_16x16x32_bf16 v[12:15], v[72:75], v[242:245], v[12:15]
	v_mfma_f32_16x16x32_bf16 v[8:11], v[80:83], v[242:245], v[8:11]
	v_mfma_f32_16x16x32_bf16 v[52:55], v[174:177], v[214:217], v[52:55]
	v_mfma_f32_16x16x32_bf16 v[48:51], v[186:189], v[214:217], v[48:51]
	v_mfma_f32_16x16x32_bf16 v[36:39], v[174:177], v[222:225], v[36:39]
	v_mfma_f32_16x16x32_bf16 v[32:35], v[186:189], v[222:225], v[32:35]
	v_mfma_f32_16x16x32_bf16 v[20:23], v[174:177], v[230:233], v[20:23]
	v_mfma_f32_16x16x32_bf16 v[16:19], v[186:189], v[230:233], v[16:19]
	v_mfma_f32_16x16x32_bf16 v[4:7], v[174:177], v[238:241], v[4:7]
	v_mfma_f32_16x16x32_bf16 v[0:3], v[186:189], v[238:241], v[0:3]
	v_mfma_f32_16x16x32_bf16 v[52:55], v[182:185], v[218:221], v[52:55]
	v_mfma_f32_16x16x32_bf16 v[48:51], v[210:213], v[218:221], v[48:51]
	v_mfma_f32_16x16x32_bf16 v[36:39], v[182:185], v[226:229], v[36:39]
	v_mfma_f32_16x16x32_bf16 v[32:35], v[210:213], v[226:229], v[32:35]
	v_mfma_f32_16x16x32_bf16 v[20:23], v[182:185], v[234:237], v[20:23]
	v_mfma_f32_16x16x32_bf16 v[16:19], v[210:213], v[234:237], v[16:19]
	v_mfma_f32_16x16x32_bf16 v[4:7], v[182:185], v[242:245], v[4:7]
	v_mfma_f32_16x16x32_bf16 v[0:3], v[210:213], v[242:245], v[0:3]
	s_barrier
	s_add_i32 s56, s56, 2
	s_add_u32 s0, s0, 0x100
	s_addc_u32 s1, s1, 0
	s_add_u32 s54, s54, 0x100
	s_addc_u32 s55, s55, 0
	s_cmp_gt_u32 s56, 13
; #define PG8_STAGE(bufoff, gbase, voff) do { _Pragma("unroll") for (int _i = 0; _i < 2; ++_i) \
;         __builtin_amdgcn_global_load_lds((const unsigned*)((const char*)(gbase) + (voff)[_i]), (PG8_LAS unsigned*)(lds + (bufoff) + ldsw + _i * 8192), 16, 0, 0); } while (0)
; #define PG8_LDA(dst, b, h) do { _Pragma("unroll") for (int m = 0; m < 4; ++m) _Pragma("unroll") for (int k = 0; k < 2; ++k) dst[m][k] = *(const PG8_LAS bf16x8*)(lds + PG8_SA(b, h) + aoff + m * 2048 + k * 1024); } while (0)
; #define PG8_LDB(dst, b, h) do { _Pragma("unroll") for (int n = 0; n < 2; ++n) _Pragma("unroll") for (int k = 0; k < 2; ++k) dst[n][k] = *(const PG8_LAS bf16x8*)(lds + PG8_SB(b, h) + boff + n * 2048 + k * 1024); } while (0)
; #define PG8_MMA(ai, bj, At, Bt) do { __builtin_amdgcn_s_setprio(1); _Pragma("unroll") for (int m = 0; m < 4; ++m) _Pragma("unroll") for (int n = 0; n < 2; ++n) _Pragma("unroll") for (int k = 0; k < 2; ++k) \
;         acc[ai][bj][m][n] = __builtin_amdgcn_mfma_f32_16x16x32_bf16(Bt[n][k], At[m][k], acc[ai][bj][m][n], 0, 0, 0); __builtin_amdgcn_s_setprio(0); } while (0)
; #define PG8_WAIT_V(n) asm volatile("s_waitcnt vmcnt(" #n ")" ::: "memory")
; #define PG8_WAIT_L(n) asm volatile("s_waitcnt lgkmcnt(" #n ")" ::: "memory")
; template <class Epi, class Sched, bool ALIGN_EPI = false, bool SP2 = false>
; __device__ __forceinline__ void gemm_phase(PG8_LAS unsigned char* lds, const Gemm g, const Sched& S, const Epi& E) {
;     ...
;             const bool last = (t == nt - 2);
;             const char* a1 = cA + (size_t)(t + 1) * kstep;
;             const char* a2 = last ? nA : cA + (size_t)(t + 2) * kstep; const char* b2 = last ? nB : cB + (size_t)(t + 2) * kstep;
;             const char* a3 = a2 + kstep; const char* b3 = b2 + kstep;
;             if (last && has_next) S.a_ready(nxt);
;             if constexpr (SP2) {
;             PG8_LDB(B0, 0, 0); PG8_LDB(B1, 0, 1); PG8_SCHED; PG8_LDA(At, 0, 0); PG8_STAGE(PG8_SA(1, 1), a1 + hstep, voffA);
;             PG8_WAIT_V(8); PG8_WAIT_L(0); PG8_BAR; PG8_MMA(0, 0, At, B0); PG8_MMA(0, 1, At, B1); PG8_BAR; PG8_SCHED;
;             PG8_LDA(At, 0, 1); PG8_STAGE(PG8_SB(0, 0), b2, voffB); PG8_STAGE(PG8_SB(0, 1), b2 + hstep, voffB); PG8_STAGE(PG8_SA(0, 0), a2, voffA);
;             PG8_WAIT_V(8); PG8_WAIT_L(0); PG8_BAR; PG8_MMA(1, 0, At, B0); PG8_MMA(1, 1, At, B1); PG8_BAR; PG8_SCHED;
.LBB0_327:
	ds_read_b128 v[68:71], v254
	ds_read_b128 v[72:75], v254 offset:1024
	ds_read_b128 v[76:79], v254 offset:2048
	ds_read_b128 v[80:83], v254 offset:3072
	ds_read_b128 v[174:177], v254 offset:16384
	ds_read_b128 v[182:185], v254 offset:17408
	ds_read_b128 v[186:189], v254 offset:18432
	ds_read_b128 v[210:213], v254 offset:19456
	s_add_u32 s2, s0, 0xfffc0080
	s_addc_u32 s3, s1, -1
	s_cmp_eq_u32 s56, 12
	s_cselect_b32 s5, s27, s3
	s_cselect_b32 s4, s52, s2
	s_cselect_b32 s3, s25, s55
	s_cselect_b32 s2, s53, s54
	s_add_i32 m0, s29, 0xc000
	ds_read_b128 v[214:217], v179
	ds_read_b128 v[218:221], v179 offset:1024
	ds_read_b128 v[222:225], v179 offset:2048
	ds_read_b128 v[226:229], v179 offset:3072
	ds_read_b128 v[230:233], v179 offset:4096
	ds_read_b128 v[234:237], v179 offset:5120
	ds_read_b128 v[238:241], v179 offset:6144
	ds_read_b128 v[242:245], v179 offset:7168
	global_load_lds_dwordx4 v170, s[0:1]
	s_add_i32 m0, s29, 0xe000
	s_nop 0
	global_load_lds_dwordx4 v172, s[0:1]
	s_waitcnt vmcnt(8)
	s_waitcnt lgkmcnt(0)
	s_barrier
	v_mfma_f32_16x16x32_bf16 v[140:143], v[68:71], v[214:217], v[140:143]
	v_mfma_f32_16x16x32_bf16 v[136:139], v[76:79], v[214:217], v[136:139]
	v_mfma_f32_16x16x32_bf16 v[124:127], v[68:71], v[222:225], v[124:127]
	v_mfma_f32_16x16x32_bf16 v[120:123], v[76:79], v[222:225], v[120:123]
	v_mfma_f32_16x16x32_bf16 v[108:111], v[68:71], v[230:233], v[108:111]
	v_mfma_f32_16x16x32_bf16 v[104:107], v[76:79], v[230:233], v[104:107]
	v_mfma_f32_16x16x32_bf16 v[92:95], v[68:71], v[238:241], v[92:95]
	v_mfma_f32_16x16x32_bf16 v[88:91], v[76:79], v[238:241], v[88:91]
	v_mfma_f32_16x16x32_bf16 v[140:143], v[72:75], v[218:221], v[140:143]
	v_mfma_f32_16x16x32_bf16 v[136:139], v[80:83], v[218:221], v[136:139]
	v_mfma_f32_16x16x32_bf16 v[124:127], v[72:75], v[226:229], v[124:127]
	v_mfma_f32_16x16x32_bf16 v[120:123], v[80:83], v[226:229], v[120:123]
	v_mfma_f32_16x16x32_bf16 v[108:111], v[72:75], v[234:237], v[108:111]
	v_mfma_f32_16x16x32_bf16 v[104:107], v[80:83], v[234:237], v[104:107]
	v_mfma_f32_16x16x32_bf16 v[92:95], v[72:75], v[242:245], v[92:95]
	v_mfma_f32_16x16x32_bf16 v[88:91], v[80:83], v[242:245], v[88:91]
	v_mfma_f32_16x16x32_bf16 v[132:135], v[174:177], v[214:217], v[132:135]
	v_mfma_f32_16x16x32_bf16 v[128:131], v[186:189], v[214:217], v[128:131]
	v_mfma_f32_16x16x32_bf16 v[116:119], v[174:177], v[222:225], v[116:119]
	v_mfma_f32_16x16x32_bf16 v[112:115], v[186:189], v[222:225], v[112:115]
	v_mfma_f32_16x16x32_bf16 v[100:103], v[174:177], v[230:233], v[100:103]
	v_mfma_f32_16x16x32_bf16 v[96:99], v[186:189], v[230:233], v[96:99]
	v_mfma_f32_16x16x32_bf16 v[84:87], v[174:177], v[238:241], v[84:87]
	v_mfma_f32_16x16x32_bf16 v[64:67], v[186:189], v[238:241], v[64:67]
	v_mfma_f32_16x16x32_bf16 v[132:135], v[182:185], v[218:221], v[132:135]
	v_mfma_f32_16x16x32_bf16 v[128:131], v[210:213], v[218:221], v[128:131]
	v_mfma_f32_16x16x32_bf16 v[116:119], v[182:185], v[226:229], v[116:119]
	v_mfma_f32_16x16x32_bf16 v[112:115], v[210:213], v[226:229], v[112:115]
	v_mfma_f32_16x16x32_bf16 v[100:103], v[182:185], v[234:237], v[100:103]
	v_mfma_f32_16x16x32_bf16 v[96:99], v[210:213], v[234:237], v[96:99]
	v_mfma_f32_16x16x32_bf16 v[84:87], v[182:185], v[242:245], v[84:87]
	v_mfma_f32_16x16x32_bf16 v[64:67], v[210:213], v[242:245], v[64:67]
	s_barrier
	s_mov_b32 m0, s30
	s_add_u32 s58, s2, 0x40000
	s_addc_u32 s59, s3, 0
	ds_read_b128 v[214:217], v179 offset:16384
	ds_read_b128 v[218:221], v179 offset:17408
	ds_read_b128 v[222:225], v179 offset:18432
	ds_read_b128 v[226:229], v179 offset:19456
	ds_read_b128 v[230:233], v179 offset:20480
	ds_read_b128 v[234:237], v179 offset:21504
	ds_read_b128 v[238:241], v179 offset:22528
	ds_read_b128 v[242:245], v179 offset:23552
	global_load_lds_dwordx4 v166, s[2:3]
	s_mov_b32 m0, s31
	s_nop 0
	global_load_lds_dwordx4 v162, s[2:3]
	s_mov_b32 m0, s33
	s_nop 0
	global_load_lds_dwordx4 v166, s[58:59]
	s_mov_b32 m0, s34
	s_nop 0
	global_load_lds_dwordx4 v162, s[58:59]
	s_mov_b32 m0, s29
	s_nop 0
	global_load_lds_dwordx4 v168, s[4:5]
	s_mov_b32 m0, s35
	s_nop 0
	global_load_lds_dwordx4 v164, s[4:5]
	s_waitcnt vmcnt(8)
	s_waitcnt lgkmcnt(0)
	s_barrier
	v_mfma_f32_16x16x32_bf16 v[60:63], v[68:71], v[214:217], v[60:63]
	v_mfma_f32_16x16x32_bf16 v[56:59], v[76:79], v[214:217], v[56:59]
	v_mfma_f32_16x16x32_bf16 v[44:47], v[68:71], v[222:225], v[44:47]
	v_mfma_f32_16x16x32_bf16 v[40:43], v[76:79], v[222:225], v[40:43]
	v_mfma_f32_16x16x32_bf16 v[28:31], v[68:71], v[230:233], v[28:31]
	v_mfma_f32_16x16x32_bf16 v[24:27], v[76:79], v[230:233], v[24:27]
	v_mfma_f32_16x16x32_bf16 v[12:15], v[68:71], v[238:241], v[12:15]
	v_mfma_f32_16x16x32_bf16 v[8:11], v[76:79], v[238:241], v[8:11]
	v_mfma_f32_16x16x32_bf16 v[60:63], v[72:75], v[218:221], v[60:63]
	v_mfma_f32_16x16x32_bf16 v[56:59], v[80:83], v[218:221], v[56:59]
	v_mfma_f32_16x16x32_bf16 v[44:47], v[72:75], v[226:229], v[44:47]
	v_mfma_f32_16x16x32_bf16 v[40:43], v[80:83], v[226:229], v[40:43]
	v_mfma_f32_16x16x32_bf16 v[28:31], v[72:75], v[234:237], v[28:31]
	v_mfma_f32_16x16x32_bf16 v[24:27], v[80:83], v[234:237], v[24:27]
	v_mfma_f32_16x16x32_bf16 v[12:15], v[72:75], v[242:245], v[12:15]
	v_mfma_f32_16x16x32_bf16 v[8:11], v[80:83], v[242:245], v[8:11]
	v_mfma_f32_16x16x32_bf16 v[52:55], v[174:177], v[214:217], v[52:55]
	v_mfma_f32_16x16x32_bf16 v[48:51], v[186:189], v[214:217], v[48:51]
	v_mfma_f32_16x16x32_bf16 v[36:39], v[174:177], v[222:225], v[36:39]
	v_mfma_f32_16x16x32_bf16 v[32:35], v[186:189], v[222:225], v[32:35]
	v_mfma_f32_16x16x32_bf16 v[20:23], v[174:177], v[230:233], v[20:23]
	v_mfma_f32_16x16x32_bf16 v[16:19], v[186:189], v[230:233], v[16:19]
	v_mfma_f32_16x16x32_bf16 v[4:7], v[174:177], v[238:241], v[4:7]
	v_mfma_f32_16x16x32_bf16 v[0:3], v[186:189], v[238:241], v[0:3]
	v_mfma_f32_16x16x32_bf16 v[52:55], v[182:185], v[218:221], v[52:55]
	v_mfma_f32_16x16x32_bf16 v[48:51], v[210:213], v[218:221], v[48:51]
	v_mfma_f32_16x16x32_bf16 v[36:39], v[182:185], v[226:229], v[36:39]
	v_mfma_f32_16x16x32_bf16 v[32:35], v[210:213], v[226:229], v[32:35]
	v_mfma_f32_16x16x32_bf16 v[20:23], v[182:185], v[234:237], v[20:23]
	v_mfma_f32_16x16x32_bf16 v[16:19], v[210:213], v[234:237], v[16:19]
	v_mfma_f32_16x16x32_bf16 v[4:7], v[182:185], v[242:245], v[4:7]
	v_mfma_f32_16x16x32_bf16 v[0:3], v[210:213], v[242:245], v[0:3]
	s_barrier
; #define PG8_STAGE(bufoff, gbase, voff) do { _Pragma("unroll") for (int _i = 0; _i < 2; ++_i) \
;         __builtin_amdgcn_global_load_lds((const unsigned*)((const char*)(gbase) + (voff)[_i]), (PG8_LAS unsigned*)(lds + (bufoff) + ldsw + _i * 8192), 16, 0, 0); } while (0)
; #define PG8_LDA(dst, b, h) do { _Pragma("unroll") for (int m = 0; m < 4; ++m) _Pragma("unroll") for (int k = 0; k < 2; ++k) dst[m][k] = *(const PG8_LAS bf16x8*)(lds + PG8_SA(b, h) + aoff + m * 2048 + k * 1024); } while (0)
; #define PG8_LDB(dst, b, h) do { _Pragma("unroll") for (int n = 0; n < 2; ++n) _Pragma("unroll") for (int k = 0; k < 2; ++k) dst[n][k] = *(const PG8_LAS bf16x8*)(lds + PG8_SB(b, h) + boff + n * 2048 + k * 1024); } while (0)
; #define PG8_MMA(ai, bj, At, Bt) do { __builtin_amdgcn_s_setprio(1); _Pragma("unroll") for (int m = 0; m < 4; ++m) _Pragma("unroll") for (int n = 0; n < 2; ++n) _Pragma("unroll") for (int k = 0; k < 2; ++k) \
;         acc[ai][bj][m][n] = __builtin_amdgcn_mfma_f32_16x16x32_bf16(Bt[n][k], At[m][k], acc[ai][bj][m][n], 0, 0, 0); __builtin_amdgcn_s_setprio(0); } while (0)
; template <class Epi, class Sched, bool ALIGN_EPI = false, bool SP2 = false>
; __device__ __forceinline__ void gemm_phase(PG8_LAS unsigned char* lds, const Gemm g, const Sched& S, const Epi& E) {
;     ...
;         for (int t = 0; t < nt; t += 2) {
;             const bool last = (t == nt - 2);
;             const char* a1 = cA + (size_t)(t + 1) * kstep;
;             const char* a2 = last ? nA : cA + (size_t)(t + 2) * kstep; const char* b2 = last ? nB : cB + (size_t)(t + 2) * kstep;
;             const char* a3 = a2 + kstep; const char* b3 = b2 + kstep;
;             if (last && has_next) S.a_ready(nxt);
;     ...
;             PG8_LDB(B0, 1, 0); PG8_LDB(B1, 1, 1); PG8_SCHED; PG8_LDA(At, 1, 0); PG8_STAGE(PG8_SA(0, 1), a2 + hstep, voffA);
;             PG8_WAIT_V(8); PG8_WAIT_L(0); PG8_BAR; PG8_MMA(0, 0, At, B0); PG8_MMA(0, 1, At, B1); PG8_BAR; PG8_SCHED;
;             PG8_LDA(At, 1, 1); PG8_STAGE(PG8_SB(1, 0), b3, voffB); PG8_STAGE(PG8_SB(1, 1), b3 + hstep, voffB); PG8_STAGE(PG8_SA(1, 0), a3, voffA);
;             PG8_WAIT_V(8); PG8_WAIT_L(0); PG8_BAR; PG8_MMA(1, 0, At, B0); PG8_MMA(1, 1, At, B1); PG8_BAR; PG8_SCHED;
;     ...
;         if constexpr (ALIGN_EPI) { if (wr == 0) PG8_BAR; }
;         if constexpr (!Epi::AFTER_DRAIN) { E(acc, cur, ui, wr, wc, fr, fq); S.done(cur); }
;         if (!has_next) break;
	ds_read_b128 v[68:71], v254 offset:32768
	ds_read_b128 v[72:75], v254 offset:33792
	ds_read_b128 v[76:79], v254 offset:34816
	ds_read_b128 v[80:83], v254 offset:35840
	ds_read_b128 v[174:177], v254 offset:49152
	ds_read_b128 v[182:185], v254 offset:50176
	ds_read_b128 v[186:189], v254 offset:51200
	ds_read_b128 v[210:213], v254 offset:52224
	s_add_u32 s4, s4, 0x40000
	s_addc_u32 s5, s5, 0
	s_mov_b32 m0, s40
	ds_read_b128 v[214:217], v179 offset:32768
	ds_read_b128 v[218:221], v179 offset:33792
	ds_read_b128 v[222:225], v179 offset:34816
	ds_read_b128 v[226:229], v179 offset:35840
	ds_read_b128 v[230:233], v179 offset:36864
	ds_read_b128 v[234:237], v179 offset:37888
	ds_read_b128 v[238:241], v179 offset:38912
	ds_read_b128 v[242:245], v179 offset:39936
	global_load_lds_dwordx4 v168, s[4:5]
	s_mov_b32 m0, s41
	s_nop 0
	global_load_lds_dwordx4 v164, s[4:5]
	s_waitcnt vmcnt(8)
	s_waitcnt lgkmcnt(0)
	s_barrier
	v_mfma_f32_16x16x32_bf16 v[140:143], v[68:71], v[214:217], v[140:143]
	v_mfma_f32_16x16x32_bf16 v[136:139], v[76:79], v[214:217], v[136:139]
	v_mfma_f32_16x16x32_bf16 v[124:127], v[68:71], v[222:225], v[124:127]
	v_mfma_f32_16x16x32_bf16 v[120:123], v[76:79], v[222:225], v[120:123]
	v_mfma_f32_16x16x32_bf16 v[108:111], v[68:71], v[230:233], v[108:111]
	v_mfma_f32_16x16x32_bf16 v[104:107], v[76:79], v[230:233], v[104:107]
	v_mfma_f32_16x16x32_bf16 v[92:95], v[68:71], v[238:241], v[92:95]
	v_mfma_f32_16x16x32_bf16 v[88:91], v[76:79], v[238:241], v[88:91]
	v_mfma_f32_16x16x32_bf16 v[140:143], v[72:75], v[218:221], v[140:143]
	v_mfma_f32_16x16x32_bf16 v[136:139], v[80:83], v[218:221], v[136:139]
	v_mfma_f32_16x16x32_bf16 v[124:127], v[72:75], v[226:229], v[124:127]
	v_mfma_f32_16x16x32_bf16 v[120:123], v[80:83], v[226:229], v[120:123]
	v_mfma_f32_16x16x32_bf16 v[108:111], v[72:75], v[234:237], v[108:111]
	v_mfma_f32_16x16x32_bf16 v[104:107], v[80:83], v[234:237], v[104:107]
	v_mfma_f32_16x16x32_bf16 v[92:95], v[72:75], v[242:245], v[92:95]
	v_mfma_f32_16x16x32_bf16 v[88:91], v[80:83], v[242:245], v[88:91]
	v_mfma_f32_16x16x32_bf16 v[132:135], v[174:177], v[214:217], v[132:135]
	v_mfma_f32_16x16x32_bf16 v[128:131], v[186:189], v[214:217], v[128:131]
	v_mfma_f32_16x16x32_bf16 v[116:119], v[174:177], v[222:225], v[116:119]
	v_mfma_f32_16x16x32_bf16 v[112:115], v[186:189], v[222:225], v[112:115]
	v_mfma_f32_16x16x32_bf16 v[100:103], v[174:177], v[230:233], v[100:103]
	v_mfma_f32_16x16x32_bf16 v[96:99], v[186:189], v[230:233], v[96:99]
	v_mfma_f32_16x16x32_bf16 v[84:87], v[174:177], v[238:241], v[84:87]
	v_mfma_f32_16x16x32_bf16 v[64:67], v[186:189], v[238:241], v[64:67]
	v_mfma_f32_16x16x32_bf16 v[132:135], v[182:185], v[218:221], v[132:135]
	v_mfma_f32_16x16x32_bf16 v[128:131], v[210:213], v[218:221], v[128:131]
	v_mfma_f32_16x16x32_bf16 v[116:119], v[182:185], v[226:229], v[116:119]
	v_mfma_f32_16x16x32_bf16 v[112:115], v[210:213], v[226:229], v[112:115]
	v_mfma_f32_16x16x32_bf16 v[100:103], v[182:185], v[234:237], v[100:103]
	v_mfma_f32_16x16x32_bf16 v[96:99], v[210:213], v[234:237], v[96:99]
	v_mfma_f32_16x16x32_bf16 v[84:87], v[182:185], v[242:245], v[84:87]
	v_mfma_f32_16x16x32_bf16 v[64:67], v[210:213], v[242:245], v[64:67]
	s_barrier
	s_mov_b32 m0, s45
	s_add_u32 s2, s2, 0x40080
	s_addc_u32 s3, s3, 0
	ds_read_b128 v[214:217], v179 offset:49152
	ds_read_b128 v[218:221], v179 offset:50176
	ds_read_b128 v[222:225], v179 offset:51200
	ds_read_b128 v[226:229], v179 offset:52224
	ds_read_b128 v[230:233], v179 offset:53248
	ds_read_b128 v[234:237], v179 offset:54272
	ds_read_b128 v[238:241], v179 offset:55296
	ds_read_b128 v[242:245], v179 offset:56320
	s_add_u32 s98, s2, 0xfffc0000
	s_addc_u32 s99, s3, -1
	global_load_lds_dwordx4 v166, s[98:99]
	s_mov_b32 m0, s46
	s_nop 0
	global_load_lds_dwordx4 v162, s[98:99]
	s_mov_b32 m0, s49
	s_nop 0
	global_load_lds_dwordx4 v166, s[2:3]
	s_mov_b32 m0, s50
	s_nop 0
	global_load_lds_dwordx4 v162, s[2:3]
	s_mov_b32 m0, s47
	s_nop 0
	s_add_u32 s100, s4, 0xfffc0080
	s_addc_u32 s101, s5, -1
	global_load_lds_dwordx4 v168, s[100:101]
	s_mov_b32 m0, s48
	s_nop 0
	global_load_lds_dwordx4 v164, s[100:101]
	s_waitcnt vmcnt(8)
	s_waitcnt lgkmcnt(0)
	s_barrier
	v_mfma_f32_16x16x32_bf16 v[60:63], v[68:71], v[214:217], v[60:63]
	v_mfma_f32_16x16x32_bf16 v[56:59], v[76:79], v[214:217], v[56:59]
	v_mfma_f32_16x16x32_bf16 v[44:47], v[68:71], v[222:225], v[44:47]
	v_mfma_f32_16x16x32_bf16 v[40:43], v[76:79], v[222:225], v[40:43]
	v_mfma_f32_16x16x32_bf16 v[28:31], v[68:71], v[230:233], v[28:31]
	v_mfma_f32_16x16x32_bf16 v[24:27], v[76:79], v[230:233], v[24:27]
	v_mfma_f32_16x16x32_bf16 v[12:15], v[68:71], v[238:241], v[12:15]
	v_mfma_f32_16x16x32_bf16 v[8:11], v[76:79], v[238:241], v[8:11]
	v_mfma_f32_16x16x32_bf16 v[60:63], v[72:75], v[218:221], v[60:63]
	v_mfma_f32_16x16x32_bf16 v[56:59], v[80:83], v[218:221], v[56:59]
	v_mfma_f32_16x16x32_bf16 v[44:47], v[72:75], v[226:229], v[44:47]
	v_mfma_f32_16x16x32_bf16 v[40:43], v[80:83], v[226:229], v[40:43]
	v_mfma_f32_16x16x32_bf16 v[28:31], v[72:75], v[234:237], v[28:31]
	v_mfma_f32_16x16x32_bf16 v[24:27], v[80:83], v[234:237], v[24:27]
	v_mfma_f32_16x16x32_bf16 v[12:15], v[72:75], v[242:245], v[12:15]
	v_mfma_f32_16x16x32_bf16 v[8:11], v[80:83], v[242:245], v[8:11]
	v_mfma_f32_16x16x32_bf16 v[52:55], v[174:177], v[214:217], v[52:55]
	v_mfma_f32_16x16x32_bf16 v[48:51], v[186:189], v[214:217], v[48:51]
	v_mfma_f32_16x16x32_bf16 v[36:39], v[174:177], v[222:225], v[36:39]
	v_mfma_f32_16x16x32_bf16 v[32:35], v[186:189], v[222:225], v[32:35]
	v_mfma_f32_16x16x32_bf16 v[20:23], v[174:177], v[230:233], v[20:23]
	v_mfma_f32_16x16x32_bf16 v[16:19], v[186:189], v[230:233], v[16:19]
	v_mfma_f32_16x16x32_bf16 v[4:7], v[174:177], v[238:241], v[4:7]
	v_mfma_f32_16x16x32_bf16 v[0:3], v[186:189], v[238:241], v[0:3]
	v_mfma_f32_16x16x32_bf16 v[52:55], v[182:185], v[218:221], v[52:55]
	v_mfma_f32_16x16x32_bf16 v[48:51], v[210:213], v[218:221], v[48:51]
	v_mfma_f32_16x16x32_bf16 v[36:39], v[182:185], v[226:229], v[36:39]
	v_mfma_f32_16x16x32_bf16 v[32:35], v[210:213], v[226:229], v[32:35]
	v_mfma_f32_16x16x32_bf16 v[20:23], v[182:185], v[234:237], v[20:23]
	v_mfma_f32_16x16x32_bf16 v[16:19], v[210:213], v[234:237], v[16:19]
	v_mfma_f32_16x16x32_bf16 v[4:7], v[182:185], v[242:245], v[4:7]
	v_mfma_f32_16x16x32_bf16 v[0:3], v[210:213], v[242:245], v[0:3]
	s_barrier
	s_add_i32 s56, s56, 2
	s_add_u32 s0, s0, 0x100
	s_addc_u32 s1, s1, 0
	s_add_u32 s54, s54, 0x100
	s_addc_u32 s55, s55, 0
	s_cmp_gt_u32 s56, 13
	s_cbranch_scc0 .LBB0_327
	s_and_b64 vcc, exec, s[22:23]
	s_cbranch_vccz .LBB0_330
	s_barrier

; #define PG8_STAGE(bufoff, gbase, voff) do { _Pragma("unroll") for (int _i = 0; _i < 2; ++_i) \
;         __builtin_amdgcn_global_load_lds((const unsigned*)((const char*)(gbase) + (voff)[_i]), (PG8_LAS unsigned*)(lds + (bufoff) + ldsw + _i * 8192), 16, 0, 0); } while (0)
; #define PG8_LDA(dst, b, h) do { _Pragma("unroll") for (int m = 0; m < 4; ++m) _Pragma("unroll") for (int k = 0; k < 2; ++k) dst[m][k] = *(const PG8_LAS bf16x8*)(lds + PG8_SA(b, h) + aoff + m * 2048 + k * 1024); } while (0)
; #define PG8_LDB(dst, b, h) do { _Pragma("unroll") for (int n = 0; n < 2; ++n) _Pragma("unroll") for (int k = 0; k < 2; ++k) dst[n][k] = *(const PG8_LAS bf16x8*)(lds + PG8_SB(b, h) + boff + n * 2048 + k * 1024); } while (0)
; #define PG8_MMA(ai, bj, At, Bt) do { __builtin_amdgcn_s_setprio(1); _Pragma("unroll") for (int m = 0; m < 4; ++m) _Pragma("unroll") for (int n = 0; n < 2; ++n) _Pragma("unroll") for (int k = 0; k < 2; ++k) \
;         acc[ai][bj][m][n] = __builtin_amdgcn_mfma_f32_16x16x32_bf16(Bt[n][k], At[m][k], acc[ai][bj][m][n], 0, 0, 0); __builtin_amdgcn_s_setprio(0); } while (0)
; #define PG8_WAIT_V(n) asm volatile("s_waitcnt vmcnt(" #n ")" ::: "memory")
; #define PG8_WAIT_L(n) asm volatile("s_waitcnt lgkmcnt(" #n ")" ::: "memory")
; template <class Epi, class Sched, bool ALIGN_EPI = false, bool SP2 = false>
; __device__ __forceinline__ void gemm_phase(PG8_LAS unsigned char* lds, const Gemm g, const Sched& S, const Epi& E) {
;     ...
;             const bool last = (t == nt - 2);
;             const char* a1 = cA + (size_t)(t + 1) * kstep;
;             const char* a2 = last ? nA : cA + (size_t)(t + 2) * kstep; const char* b2 = last ? nB : cB + (size_t)(t + 2) * kstep;
;             const char* a3 = a2 + kstep; const char* b3 = b2 + kstep;
;             if (last && has_next) S.a_ready(nxt);
;             if constexpr (SP2) {
;             PG8_LDB(B0, 0, 0); PG8_LDB(B1, 0, 1); PG8_SCHED; PG8_LDA(At, 0, 0); PG8_STAGE(PG8_SA(1, 1), a1 + hstep, voffA);
;             PG8_WAIT_V(8); PG8_WAIT_L(0); PG8_BAR; PG8_MMA(0, 0, At, B0); PG8_MMA(0, 1, At, B1); PG8_BAR; PG8_SCHED;
;             PG8_LDA(At, 0, 1); PG8_STAGE(PG8_SB(0, 0), b2, voffB); PG8_STAGE(PG8_SB(0, 1), b2 + hstep, voffB); PG8_STAGE(PG8_SA(0, 0), a2, voffA);
;             PG8_WAIT_V(8); PG8_WAIT_L(0); PG8_BAR; PG8_MMA(1, 0, At, B0); PG8_MMA(1, 1, At, B1); PG8_BAR; PG8_SCHED;
.Lup_peel:
	ds_read_b128 v[140:143], v254
	ds_read_b128 v[168:171], v254 offset:1024
	ds_read_b128 v[172:175], v254 offset:2048
	ds_read_b128 v[176:179], v254 offset:3072
	ds_read_b128 v[180:183], v254 offset:16384
	ds_read_b128 v[184:187], v254 offset:17408
	ds_read_b128 v[188:191], v254 offset:18432
	ds_read_b128 v[210:213], v254 offset:19456
	s_add_u32 s16, s14, 0xfffc0080
	s_addc_u32 s17, s15, -1
	s_cmp_eq_u32 s53, 12
	s_cselect_b32 s19, s7, s17
	s_cselect_b32 s18, s49, s16
	s_cselect_b32 s17, s5, s52
	s_cselect_b32 s16, s50, s51
	s_mov_b32 m0, s43
	ds_read_b128 v[214:217], v165
	ds_read_b128 v[218:221], v165 offset:1024
	ds_read_b128 v[222:225], v165 offset:2048
	ds_read_b128 v[226:229], v165 offset:3072
	ds_read_b128 v[230:233], v165 offset:4096
	ds_read_b128 v[234:237], v165 offset:5120
	ds_read_b128 v[238:241], v165 offset:6144
	ds_read_b128 v[242:245], v165 offset:7168
	global_load_lds_dwordx4 v136, s[14:15]
	s_mov_b32 m0, s44
	s_nop 0
	global_load_lds_dwordx4 v138, s[14:15]
	s_waitcnt vmcnt(8)
	s_waitcnt lgkmcnt(0)
	s_barrier
	v_mfma_f32_16x16x32_bf16 v[124:127], v[140:143], v[214:217], 0
	v_mfma_f32_16x16x32_bf16 v[116:119], v[172:175], v[214:217], 0
	v_mfma_f32_16x16x32_bf16 v[108:111], v[140:143], v[222:225], 0
	v_mfma_f32_16x16x32_bf16 v[100:103], v[172:175], v[222:225], 0
	v_mfma_f32_16x16x32_bf16 v[92:95], v[140:143], v[230:233], 0
	v_mfma_f32_16x16x32_bf16 v[84:87], v[172:175], v[230:233], 0
	v_mfma_f32_16x16x32_bf16 v[76:79], v[140:143], v[238:241], 0
	v_mfma_f32_16x16x32_bf16 v[68:71], v[172:175], v[238:241], 0
	v_mfma_f32_16x16x32_bf16 v[124:127], v[168:171], v[218:221], v[124:127]
	v_mfma_f32_16x16x32_bf16 v[116:119], v[176:179], v[218:221], v[116:119]
	v_mfma_f32_16x16x32_bf16 v[108:111], v[168:171], v[226:229], v[108:111]
	v_mfma_f32_16x16x32_bf16 v[100:103], v[176:179], v[226:229], v[100:103]
	v_mfma_f32_16x16x32_bf16 v[92:95], v[168:171], v[234:237], v[92:95]
	v_mfma_f32_16x16x32_bf16 v[84:87], v[176:179], v[234:237], v[84:87]
	v_mfma_f32_16x16x32_bf16 v[76:79], v[168:171], v[242:245], v[76:79]
	v_mfma_f32_16x16x32_bf16 v[68:71], v[176:179], v[242:245], v[68:71]
	v_mfma_f32_16x16x32_bf16 v[120:123], v[180:183], v[214:217], 0
	v_mfma_f32_16x16x32_bf16 v[112:115], v[188:191], v[214:217], 0
	v_mfma_f32_16x16x32_bf16 v[104:107], v[180:183], v[222:225], 0
	v_mfma_f32_16x16x32_bf16 v[96:99], v[188:191], v[222:225], 0
	v_mfma_f32_16x16x32_bf16 v[88:91], v[180:183], v[230:233], 0
	v_mfma_f32_16x16x32_bf16 v[80:83], v[188:191], v[230:233], 0
	v_mfma_f32_16x16x32_bf16 v[72:75], v[180:183], v[238:241], 0
	v_mfma_f32_16x16x32_bf16 v[64:67], v[188:191], v[238:241], 0
	v_mfma_f32_16x16x32_bf16 v[120:123], v[184:187], v[218:221], v[120:123]
	v_mfma_f32_16x16x32_bf16 v[112:115], v[210:213], v[218:221], v[112:115]
	v_mfma_f32_16x16x32_bf16 v[104:107], v[184:187], v[226:229], v[104:107]
	v_mfma_f32_16x16x32_bf16 v[96:99], v[210:213], v[226:229], v[96:99]
	v_mfma_f32_16x16x32_bf16 v[88:91], v[184:187], v[234:237], v[88:91]
	v_mfma_f32_16x16x32_bf16 v[80:83], v[210:213], v[234:237], v[80:83]
	v_mfma_f32_16x16x32_bf16 v[72:75], v[184:187], v[242:245], v[72:75]
	v_mfma_f32_16x16x32_bf16 v[64:67], v[210:213], v[242:245], v[64:67]
	s_barrier
	s_mov_b32 m0, s27
	s_add_u32 s54, s16, 0x40000
	s_addc_u32 s55, s17, 0
	ds_read_b128 v[214:217], v165 offset:16384
	ds_read_b128 v[218:221], v165 offset:17408
	ds_read_b128 v[222:225], v165 offset:18432
	ds_read_b128 v[226:229], v165 offset:19456
	ds_read_b128 v[230:233], v165 offset:20480
	ds_read_b128 v[234:237], v165 offset:21504
	ds_read_b128 v[238:241], v165 offset:22528
	ds_read_b128 v[242:245], v165 offset:23552
	global_load_lds_dwordx4 v132, s[16:17]
	s_mov_b32 m0, s28
	s_nop 0
	global_load_lds_dwordx4 v128, s[16:17]
	s_mov_b32 m0, s29
	s_nop 0
	global_load_lds_dwordx4 v132, s[54:55]
	s_mov_b32 m0, s30
	s_nop 0
	global_load_lds_dwordx4 v128, s[54:55]
	s_mov_b32 m0, s22
	s_nop 0
	global_load_lds_dwordx4 v134, s[18:19]
	s_mov_b32 m0, s31
	s_nop 0
	global_load_lds_dwordx4 v130, s[18:19]
	s_waitcnt vmcnt(8)
	s_waitcnt lgkmcnt(0)
	s_barrier
	v_mfma_f32_16x16x32_bf16 v[60:63], v[140:143], v[214:217], 0
	v_mfma_f32_16x16x32_bf16 v[52:55], v[172:175], v[214:217], 0
	v_mfma_f32_16x16x32_bf16 v[44:47], v[140:143], v[222:225], 0
	v_mfma_f32_16x16x32_bf16 v[36:39], v[172:175], v[222:225], 0
	v_mfma_f32_16x16x32_bf16 v[28:31], v[140:143], v[230:233], 0
	v_mfma_f32_16x16x32_bf16 v[20:23], v[172:175], v[230:233], 0
	v_mfma_f32_16x16x32_bf16 v[12:15], v[140:143], v[238:241], 0
	v_mfma_f32_16x16x32_bf16 v[4:7], v[172:175], v[238:241], 0
	v_mfma_f32_16x16x32_bf16 v[60:63], v[168:171], v[218:221], v[60:63]
	v_mfma_f32_16x16x32_bf16 v[52:55], v[176:179], v[218:221], v[52:55]
	v_mfma_f32_16x16x32_bf16 v[44:47], v[168:171], v[226:229], v[44:47]
	v_mfma_f32_16x16x32_bf16 v[36:39], v[176:179], v[226:229], v[36:39]
	v_mfma_f32_16x16x32_bf16 v[28:31], v[168:171], v[234:237], v[28:31]
	v_mfma_f32_16x16x32_bf16 v[20:23], v[176:179], v[234:237], v[20:23]
	v_mfma_f32_16x16x32_bf16 v[12:15], v[168:171], v[242:245], v[12:15]
	v_mfma_f32_16x16x32_bf16 v[4:7], v[176:179], v[242:245], v[4:7]
	v_mfma_f32_16x16x32_bf16 v[56:59], v[180:183], v[214:217], 0
	v_mfma_f32_16x16x32_bf16 v[48:51], v[188:191], v[214:217], 0
	v_mfma_f32_16x16x32_bf16 v[40:43], v[180:183], v[222:225], 0
	v_mfma_f32_16x16x32_bf16 v[32:35], v[188:191], v[222:225], 0
	v_mfma_f32_16x16x32_bf16 v[24:27], v[180:183], v[230:233], 0
	v_mfma_f32_16x16x32_bf16 v[16:19], v[188:191], v[230:233], 0
	v_mfma_f32_16x16x32_bf16 v[8:11], v[180:183], v[238:241], 0
	v_mfma_f32_16x16x32_bf16 v[0:3], v[188:191], v[238:241], 0
	v_mfma_f32_16x16x32_bf16 v[56:59], v[184:187], v[218:221], v[56:59]
	v_mfma_f32_16x16x32_bf16 v[48:51], v[210:213], v[218:221], v[48:51]
	v_mfma_f32_16x16x32_bf16 v[40:43], v[184:187], v[226:229], v[40:43]
	v_mfma_f32_16x16x32_bf16 v[32:35], v[210:213], v[226:229], v[32:35]
	v_mfma_f32_16x16x32_bf16 v[24:27], v[184:187], v[234:237], v[24:27]
	v_mfma_f32_16x16x32_bf16 v[16:19], v[210:213], v[234:237], v[16:19]
	v_mfma_f32_16x16x32_bf16 v[8:11], v[184:187], v[242:245], v[8:11]
	v_mfma_f32_16x16x32_bf16 v[0:3], v[210:213], v[242:245], v[0:3]
	s_barrier
; #define PG8_STAGE(bufoff, gbase, voff) do { _Pragma("unroll") for (int _i = 0; _i < 2; ++_i) \
;         __builtin_amdgcn_global_load_lds((const unsigned*)((const char*)(gbase) + (voff)[_i]), (PG8_LAS unsigned*)(lds + (bufoff) + ldsw + _i * 8192), 16, 0, 0); } while (0)
; #define PG8_LDA(dst, b, h) do { _Pragma("unroll") for (int m = 0; m < 4; ++m) _Pragma("unroll") for (int k = 0; k < 2; ++k) dst[m][k] = *(const PG8_LAS bf16x8*)(lds + PG8_SA(b, h) + aoff + m * 2048 + k * 1024); } while (0)
; #define PG8_LDB(dst, b, h) do { _Pragma("unroll") for (int n = 0; n < 2; ++n) _Pragma("unroll") for (int k = 0; k < 2; ++k) dst[n][k] = *(const PG8_LAS bf16x8*)(lds + PG8_SB(b, h) + boff + n * 2048 + k * 1024); } while (0)
; #define PG8_MMA(ai, bj, At, Bt) do { __builtin_amdgcn_s_setprio(1); _Pragma("unroll") for (int m = 0; m < 4; ++m) _Pragma("unroll") for (int n = 0; n < 2; ++n) _Pragma("unroll") for (int k = 0; k < 2; ++k) \
;         acc[ai][bj][m][n] = __builtin_amdgcn_mfma_f32_16x16x32_bf16(Bt[n][k], At[m][k], acc[ai][bj][m][n], 0, 0, 0); __builtin_amdgcn_s_setprio(0); } while (0)
; #define PG8_WAIT_V(n) asm volatile("s_waitcnt vmcnt(" #n ")" ::: "memory")
; #define PG8_WAIT_L(n) asm volatile("s_waitcnt lgkmcnt(" #n ")" ::: "memory")
; #define PG8_BAR __builtin_amdgcn_s_barrier()
; #define PG8_SCHED __builtin_amdgcn_sched_barrier(0)
; template <class Epi, class Sched, bool ALIGN_EPI = false, bool SP2 = false>
; __device__ __forceinline__ void gemm_phase(PG8_LAS unsigned char* lds, const Gemm g, const Sched& S, const Epi& E) {
;     ...
;         for (int t = 0; t < nt; t += 2) {
;     ...
;             PG8_LDB(B0, 1, 0); PG8_LDB(B1, 1, 1); PG8_SCHED; PG8_LDA(At, 1, 0); PG8_STAGE(PG8_SA(0, 1), a2 + hstep, voffA);
;             PG8_WAIT_V(8); PG8_WAIT_L(0); PG8_BAR; PG8_MMA(0, 0, At, B0); PG8_MMA(0, 1, At, B1); PG8_BAR; PG8_SCHED;
;             PG8_LDA(At, 1, 1); PG8_STAGE(PG8_SB(1, 0), b3, voffB); PG8_STAGE(PG8_SB(1, 1), b3 + hstep, voffB); PG8_STAGE(PG8_SA(1, 0), a3, voffA);
;             PG8_WAIT_V(8); PG8_WAIT_L(0); PG8_BAR; PG8_MMA(1, 0, At, B0); PG8_MMA(1, 1, At, B1); PG8_BAR; PG8_SCHED;
	ds_read_b128 v[140:143], v254 offset:32768
	ds_read_b128 v[168:171], v254 offset:33792
	ds_read_b128 v[172:175], v254 offset:34816
	ds_read_b128 v[176:179], v254 offset:35840
	ds_read_b128 v[180:183], v254 offset:49152
	ds_read_b128 v[184:187], v254 offset:50176
	ds_read_b128 v[188:191], v254 offset:51200
	ds_read_b128 v[210:213], v254 offset:52224
	s_add_u32 s18, s18, 0x40000
	s_addc_u32 s19, s19, 0
	s_mov_b32 m0, s33
	ds_read_b128 v[214:217], v165 offset:32768
	ds_read_b128 v[218:221], v165 offset:33792
	ds_read_b128 v[222:225], v165 offset:34816
	ds_read_b128 v[226:229], v165 offset:35840
	ds_read_b128 v[230:233], v165 offset:36864
	ds_read_b128 v[234:237], v165 offset:37888
	ds_read_b128 v[238:241], v165 offset:38912
	ds_read_b128 v[242:245], v165 offset:39936
	global_load_lds_dwordx4 v134, s[18:19]
	s_mov_b32 m0, s34
	s_nop 0
	global_load_lds_dwordx4 v130, s[18:19]
	s_waitcnt vmcnt(8)
	s_waitcnt lgkmcnt(0)
	s_barrier
	v_mfma_f32_16x16x32_bf16 v[124:127], v[140:143], v[214:217], v[124:127]
	v_mfma_f32_16x16x32_bf16 v[116:119], v[172:175], v[214:217], v[116:119]
	v_mfma_f32_16x16x32_bf16 v[108:111], v[140:143], v[222:225], v[108:111]
	v_mfma_f32_16x16x32_bf16 v[100:103], v[172:175], v[222:225], v[100:103]
	v_mfma_f32_16x16x32_bf16 v[92:95], v[140:143], v[230:233], v[92:95]
	v_mfma_f32_16x16x32_bf16 v[84:87], v[172:175], v[230:233], v[84:87]
	v_mfma_f32_16x16x32_bf16 v[76:79], v[140:143], v[238:241], v[76:79]
	v_mfma_f32_16x16x32_bf16 v[68:71], v[172:175], v[238:241], v[68:71]
	v_mfma_f32_16x16x32_bf16 v[124:127], v[168:171], v[218:221], v[124:127]
	v_mfma_f32_16x16x32_bf16 v[116:119], v[176:179], v[218:221], v[116:119]
	v_mfma_f32_16x16x32_bf16 v[108:111], v[168:171], v[226:229], v[108:111]
	v_mfma_f32_16x16x32_bf16 v[100:103], v[176:179], v[226:229], v[100:103]
	v_mfma_f32_16x16x32_bf16 v[92:95], v[168:171], v[234:237], v[92:95]
	v_mfma_f32_16x16x32_bf16 v[84:87], v[176:179], v[234:237], v[84:87]
	v_mfma_f32_16x16x32_bf16 v[76:79], v[168:171], v[242:245], v[76:79]
	v_mfma_f32_16x16x32_bf16 v[68:71], v[176:179], v[242:245], v[68:71]
	v_mfma_f32_16x16x32_bf16 v[120:123], v[180:183], v[214:217], v[120:123]
	v_mfma_f32_16x16x32_bf16 v[112:115], v[188:191], v[214:217], v[112:115]
	v_mfma_f32_16x16x32_bf16 v[104:107], v[180:183], v[222:225], v[104:107]
	v_mfma_f32_16x16x32_bf16 v[96:99], v[188:191], v[222:225], v[96:99]
	v_mfma_f32_16x16x32_bf16 v[88:91], v[180:183], v[230:233], v[88:91]
	v_mfma_f32_16x16x32_bf16 v[80:83], v[188:191], v[230:233], v[80:83]
	v_mfma_f32_16x16x32_bf16 v[72:75], v[180:183], v[238:241], v[72:75]
	v_mfma_f32_16x16x32_bf16 v[64:67], v[188:191], v[238:241], v[64:67]
	v_mfma_f32_16x16x32_bf16 v[120:123], v[184:187], v[218:221], v[120:123]
	v_mfma_f32_16x16x32_bf16 v[112:115], v[210:213], v[218:221], v[112:115]
	v_mfma_f32_16x16x32_bf16 v[104:107], v[184:187], v[226:229], v[104:107]
	v_mfma_f32_16x16x32_bf16 v[96:99], v[210:213], v[226:229], v[96:99]
	v_mfma_f32_16x16x32_bf16 v[88:91], v[184:187], v[234:237], v[88:91]
	v_mfma_f32_16x16x32_bf16 v[80:83], v[210:213], v[234:237], v[80:83]
	v_mfma_f32_16x16x32_bf16 v[72:75], v[184:187], v[242:245], v[72:75]
	v_mfma_f32_16x16x32_bf16 v[64:67], v[210:213], v[242:245], v[64:67]
	s_barrier
	s_mov_b32 m0, s37
	s_add_u32 s16, s16, 0x40080
	s_addc_u32 s17, s17, 0
	ds_read_b128 v[214:217], v165 offset:49152
	ds_read_b128 v[218:221], v165 offset:50176
	ds_read_b128 v[222:225], v165 offset:51200
	ds_read_b128 v[226:229], v165 offset:52224
	ds_read_b128 v[230:233], v165 offset:53248
	ds_read_b128 v[234:237], v165 offset:54272
	ds_read_b128 v[238:241], v165 offset:55296
	ds_read_b128 v[242:245], v165 offset:56320
	s_add_u32 s98, s16, 0xfffc0000
	s_addc_u32 s99, s17, -1
	global_load_lds_dwordx4 v132, s[98:99]
	s_mov_b32 m0, s38
	s_nop 0
	global_load_lds_dwordx4 v128, s[98:99]
	s_mov_b32 m0, s41
	s_nop 0
	global_load_lds_dwordx4 v132, s[16:17]
	s_mov_b32 m0, s42
	s_nop 0
	global_load_lds_dwordx4 v128, s[16:17]
	s_mov_b32 m0, s39
	s_nop 0
	s_add_u32 s100, s18, 0xfffc0080
	s_addc_u32 s101, s19, -1
	global_load_lds_dwordx4 v134, s[100:101]
	s_mov_b32 m0, s40
	s_nop 0
	global_load_lds_dwordx4 v130, s[100:101]
	s_waitcnt vmcnt(8)
	s_waitcnt lgkmcnt(0)
	s_barrier
	v_mfma_f32_16x16x32_bf16 v[60:63], v[140:143], v[214:217], v[60:63]
	v_mfma_f32_16x16x32_bf16 v[52:55], v[172:175], v[214:217], v[52:55]
	v_mfma_f32_16x16x32_bf16 v[44:47], v[140:143], v[222:225], v[44:47]
	v_mfma_f32_16x16x32_bf16 v[36:39], v[172:175], v[222:225], v[36:39]
	v_mfma_f32_16x16x32_bf16 v[28:31], v[140:143], v[230:233], v[28:31]
	v_mfma_f32_16x16x32_bf16 v[20:23], v[172:175], v[230:233], v[20:23]
	v_mfma_f32_16x16x32_bf16 v[12:15], v[140:143], v[238:241], v[12:15]
	v_mfma_f32_16x16x32_bf16 v[4:7], v[172:175], v[238:241], v[4:7]
	v_mfma_f32_16x16x32_bf16 v[60:63], v[168:171], v[218:221], v[60:63]
	v_mfma_f32_16x16x32_bf16 v[52:55], v[176:179], v[218:221], v[52:55]
	v_mfma_f32_16x16x32_bf16 v[44:47], v[168:171], v[226:229], v[44:47]
	v_mfma_f32_16x16x32_bf16 v[36:39], v[176:179], v[226:229], v[36:39]
	v_mfma_f32_16x16x32_bf16 v[28:31], v[168:171], v[234:237], v[28:31]
	v_mfma_f32_16x16x32_bf16 v[20:23], v[176:179], v[234:237], v[20:23]
	v_mfma_f32_16x16x32_bf16 v[12:15], v[168:171], v[242:245], v[12:15]
	v_mfma_f32_16x16x32_bf16 v[4:7], v[176:179], v[242:245], v[4:7]
	v_mfma_f32_16x16x32_bf16 v[56:59], v[180:183], v[214:217], v[56:59]
	v_mfma_f32_16x16x32_bf16 v[48:51], v[188:191], v[214:217], v[48:51]
	v_mfma_f32_16x16x32_bf16 v[40:43], v[180:183], v[222:225], v[40:43]
	v_mfma_f32_16x16x32_bf16 v[32:35], v[188:191], v[222:225], v[32:35]
	v_mfma_f32_16x16x32_bf16 v[24:27], v[180:183], v[230:233], v[24:27]
	v_mfma_f32_16x16x32_bf16 v[16:19], v[188:191], v[230:233], v[16:19]
	v_mfma_f32_16x16x32_bf16 v[8:11], v[180:183], v[238:241], v[8:11]
	v_mfma_f32_16x16x32_bf16 v[0:3], v[188:191], v[238:241], v[0:3]
	v_mfma_f32_16x16x32_bf16 v[56:59], v[184:187], v[218:221], v[56:59]
	v_mfma_f32_16x16x32_bf16 v[48:51], v[210:213], v[218:221], v[48:51]
	v_mfma_f32_16x16x32_bf16 v[40:43], v[184:187], v[226:229], v[40:43]
	v_mfma_f32_16x16x32_bf16 v[32:35], v[210:213], v[226:229], v[32:35]
	v_mfma_f32_16x16x32_bf16 v[24:27], v[184:187], v[234:237], v[24:27]
	v_mfma_f32_16x16x32_bf16 v[16:19], v[210:213], v[234:237], v[16:19]
	v_mfma_f32_16x16x32_bf16 v[8:11], v[184:187], v[242:245], v[8:11]
	v_mfma_f32_16x16x32_bf16 v[0:3], v[210:213], v[242:245], v[0:3]
	s_barrier
	s_add_i32 s53, s53, 2
	s_add_u32 s14, s14, 0x100
	s_addc_u32 s15, s15, 0
	s_add_u32 s51, s51, 0x100
	s_addc_u32 s52, s52, 0
	s_cmp_gt_u32 s53, 13
; #define PG8_STAGE(bufoff, gbase, voff) do { _Pragma("unroll") for (int _i = 0; _i < 2; ++_i) \
;         __builtin_amdgcn_global_load_lds((const unsigned*)((const char*)(gbase) + (voff)[_i]), (PG8_LAS unsigned*)(lds + (bufoff) + ldsw + _i * 8192), 16, 0, 0); } while (0)
; #define PG8_LDA(dst, b, h) do { _Pragma("unroll") for (int m = 0; m < 4; ++m) _Pragma("unroll") for (int k = 0; k < 2; ++k) dst[m][k] = *(const PG8_LAS bf16x8*)(lds + PG8_SA(b, h) + aoff + m * 2048 + k * 1024); } while (0)
; #define PG8_LDB(dst, b, h) do { _Pragma("unroll") for (int n = 0; n < 2; ++n) _Pragma("unroll") for (int k = 0; k < 2; ++k) dst[n][k] = *(const PG8_LAS bf16x8*)(lds + PG8_SB(b, h) + boff + n * 2048 + k * 1024); } while (0)
; #define PG8_MMA(ai, bj, At, Bt) do { __builtin_amdgcn_s_setprio(1); _Pragma("unroll") for (int m = 0; m < 4; ++m) _Pragma("unroll") for (int n = 0; n < 2; ++n) _Pragma("unroll") for (int k = 0; k < 2; ++k) \
;         acc[ai][bj][m][n] = __builtin_amdgcn_mfma_f32_16x16x32_bf16(Bt[n][k], At[m][k], acc[ai][bj][m][n], 0, 0, 0); __builtin_amdgcn_s_setprio(0); } while (0)
; #define PG8_WAIT_V(n) asm volatile("s_waitcnt vmcnt(" #n ")" ::: "memory")
; #define PG8_WAIT_L(n) asm volatile("s_waitcnt lgkmcnt(" #n ")" ::: "memory")
; template <class Epi, class Sched, bool ALIGN_EPI = false, bool SP2 = false>
; __device__ __forceinline__ void gemm_phase(PG8_LAS unsigned char* lds, const Gemm g, const Sched& S, const Epi& E) {
;     ...
;             const bool last = (t == nt - 2);
;             const char* a1 = cA + (size_t)(t + 1) * kstep;
;             const char* a2 = last ? nA : cA + (size_t)(t + 2) * kstep; const char* b2 = last ? nB : cB + (size_t)(t + 2) * kstep;
;             const char* a3 = a2 + kstep; const char* b3 = b2 + kstep;
;             if (last && has_next) S.a_ready(nxt);
;             if constexpr (SP2) {
;             PG8_LDB(B0, 0, 0); PG8_LDB(B1, 0, 1); PG8_SCHED; PG8_LDA(At, 0, 0); PG8_STAGE(PG8_SA(1, 1), a1 + hstep, voffA);
;             PG8_WAIT_V(8); PG8_WAIT_L(0); PG8_BAR; PG8_MMA(0, 0, At, B0); PG8_MMA(0, 1, At, B1); PG8_BAR; PG8_SCHED;
;             PG8_LDA(At, 0, 1); PG8_STAGE(PG8_SB(0, 0), b2, voffB); PG8_STAGE(PG8_SB(0, 1), b2 + hstep, voffB); PG8_STAGE(PG8_SA(0, 0), a2, voffA);
;             PG8_WAIT_V(8); PG8_WAIT_L(0); PG8_BAR; PG8_MMA(1, 0, At, B0); PG8_MMA(1, 1, At, B1); PG8_BAR; PG8_SCHED;
.LBB0_446:
	ds_read_b128 v[140:143], v254
	ds_read_b128 v[168:171], v254 offset:1024
	ds_read_b128 v[172:175], v254 offset:2048
	ds_read_b128 v[176:179], v254 offset:3072
	ds_read_b128 v[180:183], v254 offset:16384
	ds_read_b128 v[184:187], v254 offset:17408
	ds_read_b128 v[188:191], v254 offset:18432
	ds_read_b128 v[210:213], v254 offset:19456
	s_add_u32 s16, s14, 0xfffc0080
	s_addc_u32 s17, s15, -1
	s_cmp_eq_u32 s53, 12
	s_cselect_b32 s19, s7, s17
	s_cselect_b32 s18, s49, s16
	s_cselect_b32 s17, s5, s52
	s_cselect_b32 s16, s50, s51
	s_mov_b32 m0, s43
	ds_read_b128 v[214:217], v165
	ds_read_b128 v[218:221], v165 offset:1024
	ds_read_b128 v[222:225], v165 offset:2048
	ds_read_b128 v[226:229], v165 offset:3072
	ds_read_b128 v[230:233], v165 offset:4096
	ds_read_b128 v[234:237], v165 offset:5120
	ds_read_b128 v[238:241], v165 offset:6144
	ds_read_b128 v[242:245], v165 offset:7168
	global_load_lds_dwordx4 v136, s[14:15]
	s_mov_b32 m0, s44
	s_nop 0
	global_load_lds_dwordx4 v138, s[14:15]
	s_waitcnt vmcnt(8)
	s_waitcnt lgkmcnt(0)
	s_barrier
	v_mfma_f32_16x16x32_bf16 v[124:127], v[140:143], v[214:217], v[124:127]
	v_mfma_f32_16x16x32_bf16 v[116:119], v[172:175], v[214:217], v[116:119]
	v_mfma_f32_16x16x32_bf16 v[108:111], v[140:143], v[222:225], v[108:111]
	v_mfma_f32_16x16x32_bf16 v[100:103], v[172:175], v[222:225], v[100:103]
	v_mfma_f32_16x16x32_bf16 v[92:95], v[140:143], v[230:233], v[92:95]
	v_mfma_f32_16x16x32_bf16 v[84:87], v[172:175], v[230:233], v[84:87]
	v_mfma_f32_16x16x32_bf16 v[76:79], v[140:143], v[238:241], v[76:79]
	v_mfma_f32_16x16x32_bf16 v[68:71], v[172:175], v[238:241], v[68:71]
	v_mfma_f32_16x16x32_bf16 v[124:127], v[168:171], v[218:221], v[124:127]
	v_mfma_f32_16x16x32_bf16 v[116:119], v[176:179], v[218:221], v[116:119]
	v_mfma_f32_16x16x32_bf16 v[108:111], v[168:171], v[226:229], v[108:111]
	v_mfma_f32_16x16x32_bf16 v[100:103], v[176:179], v[226:229], v[100:103]
	v_mfma_f32_16x16x32_bf16 v[92:95], v[168:171], v[234:237], v[92:95]
	v_mfma_f32_16x16x32_bf16 v[84:87], v[176:179], v[234:237], v[84:87]
	v_mfma_f32_16x16x32_bf16 v[76:79], v[168:171], v[242:245], v[76:79]
	v_mfma_f32_16x16x32_bf16 v[68:71], v[176:179], v[242:245], v[68:71]
	v_mfma_f32_16x16x32_bf16 v[120:123], v[180:183], v[214:217], v[120:123]
	v_mfma_f32_16x16x32_bf16 v[112:115], v[188:191], v[214:217], v[112:115]
	v_mfma_f32_16x16x32_bf16 v[104:107], v[180:183], v[222:225], v[104:107]
	v_mfma_f32_16x16x32_bf16 v[96:99], v[188:191], v[222:225], v[96:99]
	v_mfma_f32_16x16x32_bf16 v[88:91], v[180:183], v[230:233], v[88:91]
	v_mfma_f32_16x16x32_bf16 v[80:83], v[188:191], v[230:233], v[80:83]
	v_mfma_f32_16x16x32_bf16 v[72:75], v[180:183], v[238:241], v[72:75]
	v_mfma_f32_16x16x32_bf16 v[64:67], v[188:191], v[238:241], v[64:67]
	v_mfma_f32_16x16x32_bf16 v[120:123], v[184:187], v[218:221], v[120:123]
	v_mfma_f32_16x16x32_bf16 v[112:115], v[210:213], v[218:221], v[112:115]
	v_mfma_f32_16x16x32_bf16 v[104:107], v[184:187], v[226:229], v[104:107]
	v_mfma_f32_16x16x32_bf16 v[96:99], v[210:213], v[226:229], v[96:99]
	v_mfma_f32_16x16x32_bf16 v[88:91], v[184:187], v[234:237], v[88:91]
	v_mfma_f32_16x16x32_bf16 v[80:83], v[210:213], v[234:237], v[80:83]
	v_mfma_f32_16x16x32_bf16 v[72:75], v[184:187], v[242:245], v[72:75]
	v_mfma_f32_16x16x32_bf16 v[64:67], v[210:213], v[242:245], v[64:67]
	s_barrier
	s_mov_b32 m0, s27
	s_add_u32 s54, s16, 0x40000
	s_addc_u32 s55, s17, 0
	ds_read_b128 v[214:217], v165 offset:16384
	ds_read_b128 v[218:221], v165 offset:17408
	ds_read_b128 v[222:225], v165 offset:18432
	ds_read_b128 v[226:229], v165 offset:19456
	ds_read_b128 v[230:233], v165 offset:20480
	ds_read_b128 v[234:237], v165 offset:21504
	ds_read_b128 v[238:241], v165 offset:22528
	ds_read_b128 v[242:245], v165 offset:23552
	global_load_lds_dwordx4 v132, s[16:17]
	s_mov_b32 m0, s28
	s_nop 0
	global_load_lds_dwordx4 v128, s[16:17]
	s_mov_b32 m0, s29
	s_nop 0
	global_load_lds_dwordx4 v132, s[54:55]
	s_mov_b32 m0, s30
	s_nop 0
	global_load_lds_dwordx4 v128, s[54:55]
	s_mov_b32 m0, s22
	s_nop 0
	global_load_lds_dwordx4 v134, s[18:19]
	s_mov_b32 m0, s31
	s_nop 0
	global_load_lds_dwordx4 v130, s[18:19]
	s_waitcnt vmcnt(8)
	s_waitcnt lgkmcnt(0)
	s_barrier
	v_mfma_f32_16x16x32_bf16 v[60:63], v[140:143], v[214:217], v[60:63]
	v_mfma_f32_16x16x32_bf16 v[52:55], v[172:175], v[214:217], v[52:55]
	v_mfma_f32_16x16x32_bf16 v[44:47], v[140:143], v[222:225], v[44:47]
	v_mfma_f32_16x16x32_bf16 v[36:39], v[172:175], v[222:225], v[36:39]
	v_mfma_f32_16x16x32_bf16 v[28:31], v[140:143], v[230:233], v[28:31]
	v_mfma_f32_16x16x32_bf16 v[20:23], v[172:175], v[230:233], v[20:23]
	v_mfma_f32_16x16x32_bf16 v[12:15], v[140:143], v[238:241], v[12:15]
	v_mfma_f32_16x16x32_bf16 v[4:7], v[172:175], v[238:241], v[4:7]
	v_mfma_f32_16x16x32_bf16 v[60:63], v[168:171], v[218:221], v[60:63]
	v_mfma_f32_16x16x32_bf16 v[52:55], v[176:179], v[218:221], v[52:55]
	v_mfma_f32_16x16x32_bf16 v[44:47], v[168:171], v[226:229], v[44:47]
	v_mfma_f32_16x16x32_bf16 v[36:39], v[176:179], v[226:229], v[36:39]
	v_mfma_f32_16x16x32_bf16 v[28:31], v[168:171], v[234:237], v[28:31]
	v_mfma_f32_16x16x32_bf16 v[20:23], v[176:179], v[234:237], v[20:23]
	v_mfma_f32_16x16x32_bf16 v[12:15], v[168:171], v[242:245], v[12:15]
	v_mfma_f32_16x16x32_bf16 v[4:7], v[176:179], v[242:245], v[4:7]
	v_mfma_f32_16x16x32_bf16 v[56:59], v[180:183], v[214:217], v[56:59]
	v_mfma_f32_16x16x32_bf16 v[48:51], v[188:191], v[214:217], v[48:51]
	v_mfma_f32_16x16x32_bf16 v[40:43], v[180:183], v[222:225], v[40:43]
	v_mfma_f32_16x16x32_bf16 v[32:35], v[188:191], v[222:225], v[32:35]
	v_mfma_f32_16x16x32_bf16 v[24:27], v[180:183], v[230:233], v[24:27]
	v_mfma_f32_16x16x32_bf16 v[16:19], v[188:191], v[230:233], v[16:19]
	v_mfma_f32_16x16x32_bf16 v[8:11], v[180:183], v[238:241], v[8:11]
	v_mfma_f32_16x16x32_bf16 v[0:3], v[188:191], v[238:241], v[0:3]
	v_mfma_f32_16x16x32_bf16 v[56:59], v[184:187], v[218:221], v[56:59]
	v_mfma_f32_16x16x32_bf16 v[48:51], v[210:213], v[218:221], v[48:51]
	v_mfma_f32_16x16x32_bf16 v[40:43], v[184:187], v[226:229], v[40:43]
	v_mfma_f32_16x16x32_bf16 v[32:35], v[210:213], v[226:229], v[32:35]
	v_mfma_f32_16x16x32_bf16 v[24:27], v[184:187], v[234:237], v[24:27]
	v_mfma_f32_16x16x32_bf16 v[16:19], v[210:213], v[234:237], v[16:19]
	v_mfma_f32_16x16x32_bf16 v[8:11], v[184:187], v[242:245], v[8:11]
	v_mfma_f32_16x16x32_bf16 v[0:3], v[210:213], v[242:245], v[0:3]
	s_barrier
; #define PG8_STAGE(bufoff, gbase, voff) do { _Pragma("unroll") for (int _i = 0; _i < 2; ++_i) \
;         __builtin_amdgcn_global_load_lds((const unsigned*)((const char*)(gbase) + (voff)[_i]), (PG8_LAS unsigned*)(lds + (bufoff) + ldsw + _i * 8192), 16, 0, 0); } while (0)
; #define PG8_LDA(dst, b, h) do { _Pragma("unroll") for (int m = 0; m < 4; ++m) _Pragma("unroll") for (int k = 0; k < 2; ++k) dst[m][k] = *(const PG8_LAS bf16x8*)(lds + PG8_SA(b, h) + aoff + m * 2048 + k * 1024); } while (0)
; #define PG8_LDB(dst, b, h) do { _Pragma("unroll") for (int n = 0; n < 2; ++n) _Pragma("unroll") for (int k = 0; k < 2; ++k) dst[n][k] = *(const PG8_LAS bf16x8*)(lds + PG8_SB(b, h) + boff + n * 2048 + k * 1024); } while (0)
; #define PG8_MMA(ai, bj, At, Bt) do { __builtin_amdgcn_s_setprio(1); _Pragma("unroll") for (int m = 0; m < 4; ++m) _Pragma("unroll") for (int n = 0; n < 2; ++n) _Pragma("unroll") for (int k = 0; k < 2; ++k) \
;         acc[ai][bj][m][n] = __builtin_amdgcn_mfma_f32_16x16x32_bf16(Bt[n][k], At[m][k], acc[ai][bj][m][n], 0, 0, 0); __builtin_amdgcn_s_setprio(0); } while (0)
; template <class Epi, class Sched, bool ALIGN_EPI = false, bool SP2 = false>
; __device__ __forceinline__ void gemm_phase(PG8_LAS unsigned char* lds, const Gemm g, const Sched& S, const Epi& E) {
;     ...
;         for (int t = 0; t < nt; t += 2) {
;             const bool last = (t == nt - 2);
;             const char* a1 = cA + (size_t)(t + 1) * kstep;
;             const char* a2 = last ? nA : cA + (size_t)(t + 2) * kstep; const char* b2 = last ? nB : cB + (size_t)(t + 2) * kstep;
;             const char* a3 = a2 + kstep; const char* b3 = b2 + kstep;
;             if (last && has_next) S.a_ready(nxt);
;     ...
;             PG8_LDB(B0, 1, 0); PG8_LDB(B1, 1, 1); PG8_SCHED; PG8_LDA(At, 1, 0); PG8_STAGE(PG8_SA(0, 1), a2 + hstep, voffA);
;             PG8_WAIT_V(8); PG8_WAIT_L(0); PG8_BAR; PG8_MMA(0, 0, At, B0); PG8_MMA(0, 1, At, B1); PG8_BAR; PG8_SCHED;
;             PG8_LDA(At, 1, 1); PG8_STAGE(PG8_SB(1, 0), b3, voffB); PG8_STAGE(PG8_SB(1, 1), b3 + hstep, voffB); PG8_STAGE(PG8_SA(1, 0), a3, voffA);
;             PG8_WAIT_V(8); PG8_WAIT_L(0); PG8_BAR; PG8_MMA(1, 0, At, B0); PG8_MMA(1, 1, At, B1); PG8_BAR; PG8_SCHED;
;     ...
;         if constexpr (ALIGN_EPI) { if (wr == 0) PG8_BAR; }
;         if constexpr (!Epi::AFTER_DRAIN) { E(acc, cur, ui, wr, wc, fr, fq); S.done(cur); }
;         if (!has_next) break;
	ds_read_b128 v[140:143], v254 offset:32768
	ds_read_b128 v[168:171], v254 offset:33792
	ds_read_b128 v[172:175], v254 offset:34816
	ds_read_b128 v[176:179], v254 offset:35840
	ds_read_b128 v[180:183], v254 offset:49152
	ds_read_b128 v[184:187], v254 offset:50176
	ds_read_b128 v[188:191], v254 offset:51200
	ds_read_b128 v[210:213], v254 offset:52224
	s_add_u32 s18, s18, 0x40000
	s_addc_u32 s19, s19, 0
	s_mov_b32 m0, s33
	ds_read_b128 v[214:217], v165 offset:32768
	ds_read_b128 v[218:221], v165 offset:33792
	ds_read_b128 v[222:225], v165 offset:34816
	ds_read_b128 v[226:229], v165 offset:35840
	ds_read_b128 v[230:233], v165 offset:36864
	ds_read_b128 v[234:237], v165 offset:37888
	ds_read_b128 v[238:241], v165 offset:38912
	ds_read_b128 v[242:245], v165 offset:39936
	global_load_lds_dwordx4 v134, s[18:19]
	s_mov_b32 m0, s34
	s_nop 0
	global_load_lds_dwordx4 v130, s[18:19]
	s_waitcnt vmcnt(8)
	s_waitcnt lgkmcnt(0)
	s_barrier
	v_mfma_f32_16x16x32_bf16 v[124:127], v[140:143], v[214:217], v[124:127]
	v_mfma_f32_16x16x32_bf16 v[116:119], v[172:175], v[214:217], v[116:119]
	v_mfma_f32_16x16x32_bf16 v[108:111], v[140:143], v[222:225], v[108:111]
	v_mfma_f32_16x16x32_bf16 v[100:103], v[172:175], v[222:225], v[100:103]
	v_mfma_f32_16x16x32_bf16 v[92:95], v[140:143], v[230:233], v[92:95]
	v_mfma_f32_16x16x32_bf16 v[84:87], v[172:175], v[230:233], v[84:87]
	v_mfma_f32_16x16x32_bf16 v[76:79], v[140:143], v[238:241], v[76:79]
	v_mfma_f32_16x16x32_bf16 v[68:71], v[172:175], v[238:241], v[68:71]
	v_mfma_f32_16x16x32_bf16 v[124:127], v[168:171], v[218:221], v[124:127]
	v_mfma_f32_16x16x32_bf16 v[116:119], v[176:179], v[218:221], v[116:119]
	v_mfma_f32_16x16x32_bf16 v[108:111], v[168:171], v[226:229], v[108:111]
	v_mfma_f32_16x16x32_bf16 v[100:103], v[176:179], v[226:229], v[100:103]
	v_mfma_f32_16x16x32_bf16 v[92:95], v[168:171], v[234:237], v[92:95]
	v_mfma_f32_16x16x32_bf16 v[84:87], v[176:179], v[234:237], v[84:87]
	v_mfma_f32_16x16x32_bf16 v[76:79], v[168:171], v[242:245], v[76:79]
	v_mfma_f32_16x16x32_bf16 v[68:71], v[176:179], v[242:245], v[68:71]
	v_mfma_f32_16x16x32_bf16 v[120:123], v[180:183], v[214:217], v[120:123]
	v_mfma_f32_16x16x32_bf16 v[112:115], v[188:191], v[214:217], v[112:115]
	v_mfma_f32_16x16x32_bf16 v[104:107], v[180:183], v[222:225], v[104:107]
	v_mfma_f32_16x16x32_bf16 v[96:99], v[188:191], v[222:225], v[96:99]
	v_mfma_f32_16x16x32_bf16 v[88:91], v[180:183], v[230:233], v[88:91]
	v_mfma_f32_16x16x32_bf16 v[80:83], v[188:191], v[230:233], v[80:83]
	v_mfma_f32_16x16x32_bf16 v[72:75], v[180:183], v[238:241], v[72:75]
	v_mfma_f32_16x16x32_bf16 v[64:67], v[188:191], v[238:241], v[64:67]
	v_mfma_f32_16x16x32_bf16 v[120:123], v[184:187], v[218:221], v[120:123]
	v_mfma_f32_16x16x32_bf16 v[112:115], v[210:213], v[218:221], v[112:115]
	v_mfma_f32_16x16x32_bf16 v[104:107], v[184:187], v[226:229], v[104:107]
	v_mfma_f32_16x16x32_bf16 v[96:99], v[210:213], v[226:229], v[96:99]
	v_mfma_f32_16x16x32_bf16 v[88:91], v[184:187], v[234:237], v[88:91]
	v_mfma_f32_16x16x32_bf16 v[80:83], v[210:213], v[234:237], v[80:83]
	v_mfma_f32_16x16x32_bf16 v[72:75], v[184:187], v[242:245], v[72:75]
	v_mfma_f32_16x16x32_bf16 v[64:67], v[210:213], v[242:245], v[64:67]
	s_barrier
	s_mov_b32 m0, s37
	s_add_u32 s16, s16, 0x40080
	s_addc_u32 s17, s17, 0
	ds_read_b128 v[214:217], v165 offset:49152
	ds_read_b128 v[218:221], v165 offset:50176
	ds_read_b128 v[222:225], v165 offset:51200
	ds_read_b128 v[226:229], v165 offset:52224
	ds_read_b128 v[230:233], v165 offset:53248
	ds_read_b128 v[234:237], v165 offset:54272
	ds_read_b128 v[238:241], v165 offset:55296
	ds_read_b128 v[242:245], v165 offset:56320
	s_add_u32 s98, s16, 0xfffc0000
	s_addc_u32 s99, s17, -1
	global_load_lds_dwordx4 v132, s[98:99]
	s_mov_b32 m0, s38
	s_nop 0
	global_load_lds_dwordx4 v128, s[98:99]
	s_mov_b32 m0, s41
	s_nop 0
	global_load_lds_dwordx4 v132, s[16:17]
	s_mov_b32 m0, s42
	s_nop 0
	global_load_lds_dwordx4 v128, s[16:17]
	s_mov_b32 m0, s39
	s_nop 0
	s_add_u32 s100, s18, 0xfffc0080
	s_addc_u32 s101, s19, -1
	global_load_lds_dwordx4 v134, s[100:101]
	s_mov_b32 m0, s40
	s_nop 0
	global_load_lds_dwordx4 v130, s[100:101]
	s_waitcnt vmcnt(8)
	s_waitcnt lgkmcnt(0)
	s_barrier
	v_mfma_f32_16x16x32_bf16 v[60:63], v[140:143], v[214:217], v[60:63]
	v_mfma_f32_16x16x32_bf16 v[52:55], v[172:175], v[214:217], v[52:55]
	v_mfma_f32_16x16x32_bf16 v[44:47], v[140:143], v[222:225], v[44:47]
	v_mfma_f32_16x16x32_bf16 v[36:39], v[172:175], v[222:225], v[36:39]
	v_mfma_f32_16x16x32_bf16 v[28:31], v[140:143], v[230:233], v[28:31]
	v_mfma_f32_16x16x32_bf16 v[20:23], v[172:175], v[230:233], v[20:23]
	v_mfma_f32_16x16x32_bf16 v[12:15], v[140:143], v[238:241], v[12:15]
	v_mfma_f32_16x16x32_bf16 v[4:7], v[172:175], v[238:241], v[4:7]
	v_mfma_f32_16x16x32_bf16 v[60:63], v[168:171], v[218:221], v[60:63]
	v_mfma_f32_16x16x32_bf16 v[52:55], v[176:179], v[218:221], v[52:55]
	v_mfma_f32_16x16x32_bf16 v[44:47], v[168:171], v[226:229], v[44:47]
	v_mfma_f32_16x16x32_bf16 v[36:39], v[176:179], v[226:229], v[36:39]
	v_mfma_f32_16x16x32_bf16 v[28:31], v[168:171], v[234:237], v[28:31]
	v_mfma_f32_16x16x32_bf16 v[20:23], v[176:179], v[234:237], v[20:23]
	v_mfma_f32_16x16x32_bf16 v[12:15], v[168:171], v[242:245], v[12:15]
	v_mfma_f32_16x16x32_bf16 v[4:7], v[176:179], v[242:245], v[4:7]
	v_mfma_f32_16x16x32_bf16 v[56:59], v[180:183], v[214:217], v[56:59]
	v_mfma_f32_16x16x32_bf16 v[48:51], v[188:191], v[214:217], v[48:51]
	v_mfma_f32_16x16x32_bf16 v[40:43], v[180:183], v[222:225], v[40:43]
	v_mfma_f32_16x16x32_bf16 v[32:35], v[188:191], v[222:225], v[32:35]
	v_mfma_f32_16x16x32_bf16 v[24:27], v[180:183], v[230:233], v[24:27]
	v_mfma_f32_16x16x32_bf16 v[16:19], v[188:191], v[230:233], v[16:19]
	v_mfma_f32_16x16x32_bf16 v[8:11], v[180:183], v[238:241], v[8:11]
	v_mfma_f32_16x16x32_bf16 v[0:3], v[188:191], v[238:241], v[0:3]
	v_mfma_f32_16x16x32_bf16 v[56:59], v[184:187], v[218:221], v[56:59]
	v_mfma_f32_16x16x32_bf16 v[48:51], v[210:213], v[218:221], v[48:51]
	v_mfma_f32_16x16x32_bf16 v[40:43], v[184:187], v[226:229], v[40:43]
	v_mfma_f32_16x16x32_bf16 v[32:35], v[210:213], v[226:229], v[32:35]
	v_mfma_f32_16x16x32_bf16 v[24:27], v[184:187], v[234:237], v[24:27]
	v_mfma_f32_16x16x32_bf16 v[16:19], v[210:213], v[234:237], v[16:19]
	v_mfma_f32_16x16x32_bf16 v[8:11], v[184:187], v[242:245], v[8:11]
	v_mfma_f32_16x16x32_bf16 v[0:3], v[210:213], v[242:245], v[0:3]
	s_barrier
	s_add_i32 s53, s53, 2
	s_add_u32 s14, s14, 0x100
	s_addc_u32 s15, s15, 0
	s_add_u32 s51, s51, 0x100
	s_addc_u32 s52, s52, 0
	s_cmp_gt_u32 s53, 13
	s_cbranch_scc0 .LBB0_446
	s_and_b64 vcc, exec, s[2:3]
	s_cbranch_vccz .LBB0_449
	s_barrier

; #define PG8_STAGE(bufoff, gbase, voff) do { _Pragma("unroll") for (int _i = 0; _i < 2; ++_i) \
;         __builtin_amdgcn_global_load_lds((const unsigned*)((const char*)(gbase) + (voff)[_i]), (PG8_LAS unsigned*)(lds + (bufoff) + ldsw + _i * 8192), 16, 0, 0); } while (0)
; #define PG8_LDA(dst, b, h) do { _Pragma("unroll") for (int m = 0; m < 4; ++m) _Pragma("unroll") for (int k = 0; k < 2; ++k) dst[m][k] = *(const PG8_LAS bf16x8*)(lds + PG8_SA(b, h) + aoff + m * 2048 + k * 1024); } while (0)
; #define PG8_LDB(dst, b, h) do { _Pragma("unroll") for (int n = 0; n < 2; ++n) _Pragma("unroll") for (int k = 0; k < 2; ++k) dst[n][k] = *(const PG8_LAS bf16x8*)(lds + PG8_SB(b, h) + boff + n * 2048 + k * 1024); } while (0)
; #define PG8_MMA(ai, bj, At, Bt) do { __builtin_amdgcn_s_setprio(1); _Pragma("unroll") for (int m = 0; m < 4; ++m) _Pragma("unroll") for (int n = 0; n < 2; ++n) _Pragma("unroll") for (int k = 0; k < 2; ++k) \
;         acc[ai][bj][m][n] = __builtin_amdgcn_mfma_f32_16x16x32_bf16(Bt[n][k], At[m][k], acc[ai][bj][m][n], 0, 0, 0); __builtin_amdgcn_s_setprio(0); } while (0)
; #define PG8_WAIT_V(n) asm volatile("s_waitcnt vmcnt(" #n ")" ::: "memory")
; #define PG8_WAIT_L(n) asm volatile("s_waitcnt lgkmcnt(" #n ")" ::: "memory")
; template <class Epi, class Sched, bool ALIGN_EPI = false, bool SP2 = false>
; __device__ __forceinline__ void gemm_phase(PG8_LAS unsigned char* lds, const Gemm g, const Sched& S, const Epi& E) {
;     ...
;             const bool last = (t == nt - 2);
;             const char* a1 = cA + (size_t)(t + 1) * kstep;
;             const char* a2 = last ? nA : cA + (size_t)(t + 2) * kstep; const char* b2 = last ? nB : cB + (size_t)(t + 2) * kstep;
;             const char* a3 = a2 + kstep; const char* b3 = b2 + kstep;
;             if (last && has_next) S.a_ready(nxt);
;             if constexpr (SP2) {
;             PG8_LDB(B0, 0, 0); PG8_LDB(B1, 0, 1); PG8_SCHED; PG8_LDA(At, 0, 0); PG8_STAGE(PG8_SA(1, 1), a1 + hstep, voffA);
;             PG8_WAIT_V(8); PG8_WAIT_L(0); PG8_BAR; PG8_MMA(0, 0, At, B0); PG8_MMA(0, 1, At, B1); PG8_BAR; PG8_SCHED;
;             PG8_LDA(At, 0, 1); PG8_STAGE(PG8_SB(0, 0), b2, voffB); PG8_STAGE(PG8_SB(0, 1), b2 + hstep, voffB); PG8_STAGE(PG8_SA(0, 0), a2, voffA);
;             PG8_WAIT_V(8); PG8_WAIT_L(0); PG8_BAR; PG8_MMA(1, 0, At, B0); PG8_MMA(1, 1, At, B1); PG8_BAR; PG8_SCHED;
.Ldn_peel:
	ds_read_b128 v[128:131], v254
	ds_read_b128 v[132:135], v254 offset:1024
	ds_read_b128 v[136:139], v254 offset:2048
	ds_read_b128 v[140:143], v254 offset:3072
	ds_read_b128 v[174:177], v254 offset:16384
	ds_read_b128 v[184:187], v254 offset:17408
	ds_read_b128 v[188:191], v254 offset:18432
	ds_read_b128 v[210:213], v254 offset:19456
	s_add_u32 s2, s0, 0x100
	s_addc_u32 s3, s1, 0
	s_cmp_eq_u32 s13, 40
	s_cselect_b32 s7, s27, s3
	s_cselect_b32 s6, s26, s2
	s_cselect_b32 s5, s37, s11
	s_cselect_b32 s4, s36, s10
	s_add_i32 m0, s29, 0xc000
	ds_read_b128 v[214:217], v181
	ds_read_b128 v[218:221], v181 offset:1024
	ds_read_b128 v[222:225], v181 offset:2048
	ds_read_b128 v[226:229], v181 offset:3072
	ds_read_b128 v[230:233], v181 offset:4096
	ds_read_b128 v[234:237], v181 offset:5120
	ds_read_b128 v[238:241], v181 offset:6144
	ds_read_b128 v[242:245], v181 offset:7168
	global_load_lds_dwordx4 v170, s[0:1]
	s_add_i32 m0, s29, 0xe000
	s_nop 0
	global_load_lds_dwordx4 v172, s[0:1]
	s_waitcnt vmcnt(8)
	s_waitcnt lgkmcnt(0)
	s_barrier
	v_mfma_f32_16x16x32_bf16 v[124:127], v[128:131], v[214:217], 0
	v_mfma_f32_16x16x32_bf16 v[120:123], v[136:139], v[214:217], 0
	v_mfma_f32_16x16x32_bf16 v[108:111], v[128:131], v[222:225], 0
	v_mfma_f32_16x16x32_bf16 v[104:107], v[136:139], v[222:225], 0
	v_mfma_f32_16x16x32_bf16 v[92:95], v[128:131], v[230:233], 0
	v_mfma_f32_16x16x32_bf16 v[88:91], v[136:139], v[230:233], 0
	v_mfma_f32_16x16x32_bf16 v[76:79], v[128:131], v[238:241], 0
	v_mfma_f32_16x16x32_bf16 v[72:75], v[136:139], v[238:241], 0
	v_mfma_f32_16x16x32_bf16 v[124:127], v[132:135], v[218:221], v[124:127]
	v_mfma_f32_16x16x32_bf16 v[120:123], v[140:143], v[218:221], v[120:123]
	v_mfma_f32_16x16x32_bf16 v[108:111], v[132:135], v[226:229], v[108:111]
	v_mfma_f32_16x16x32_bf16 v[104:107], v[140:143], v[226:229], v[104:107]
	v_mfma_f32_16x16x32_bf16 v[92:95], v[132:135], v[234:237], v[92:95]
	v_mfma_f32_16x16x32_bf16 v[88:91], v[140:143], v[234:237], v[88:91]
	v_mfma_f32_16x16x32_bf16 v[76:79], v[132:135], v[242:245], v[76:79]
	v_mfma_f32_16x16x32_bf16 v[72:75], v[140:143], v[242:245], v[72:75]
	v_mfma_f32_16x16x32_bf16 v[116:119], v[174:177], v[214:217], 0
	v_mfma_f32_16x16x32_bf16 v[112:115], v[188:191], v[214:217], 0
	v_mfma_f32_16x16x32_bf16 v[100:103], v[174:177], v[222:225], 0
	v_mfma_f32_16x16x32_bf16 v[96:99], v[188:191], v[222:225], 0
	v_mfma_f32_16x16x32_bf16 v[84:87], v[174:177], v[230:233], 0
	v_mfma_f32_16x16x32_bf16 v[80:83], v[188:191], v[230:233], 0
	v_mfma_f32_16x16x32_bf16 v[68:71], v[174:177], v[238:241], 0
	v_mfma_f32_16x16x32_bf16 v[64:67], v[188:191], v[238:241], 0
	v_mfma_f32_16x16x32_bf16 v[116:119], v[184:187], v[218:221], v[116:119]
	v_mfma_f32_16x16x32_bf16 v[112:115], v[210:213], v[218:221], v[112:115]
	v_mfma_f32_16x16x32_bf16 v[100:103], v[184:187], v[226:229], v[100:103]
	v_mfma_f32_16x16x32_bf16 v[96:99], v[210:213], v[226:229], v[96:99]
	v_mfma_f32_16x16x32_bf16 v[84:87], v[184:187], v[234:237], v[84:87]
	v_mfma_f32_16x16x32_bf16 v[80:83], v[210:213], v[234:237], v[80:83]
	v_mfma_f32_16x16x32_bf16 v[68:71], v[184:187], v[242:245], v[68:71]
	v_mfma_f32_16x16x32_bf16 v[64:67], v[210:213], v[242:245], v[64:67]
	s_barrier
	s_mov_b32 m0, s35
	s_add_u32 s0, s4, 0xb0000
	s_addc_u32 s1, s5, 0
	ds_read_b128 v[214:217], v181 offset:16384
	ds_read_b128 v[218:221], v181 offset:17408
	ds_read_b128 v[222:225], v181 offset:18432
	ds_read_b128 v[226:229], v181 offset:19456
	ds_read_b128 v[230:233], v181 offset:20480
	ds_read_b128 v[234:237], v181 offset:21504
	ds_read_b128 v[238:241], v181 offset:22528
	ds_read_b128 v[242:245], v181 offset:23552
	global_load_lds_dwordx4 v166, s[4:5]
	s_mov_b32 m0, s38
	s_nop 0
	global_load_lds_dwordx4 v162, s[4:5]
	s_mov_b32 m0, s39
	s_nop 0
	global_load_lds_dwordx4 v166, s[0:1]
	s_mov_b32 m0, s40
	s_nop 0
	global_load_lds_dwordx4 v162, s[0:1]
	s_mov_b32 m0, s29
	s_nop 0
	global_load_lds_dwordx4 v168, s[6:7]
	s_mov_b32 m0, s41
	s_nop 0
	global_load_lds_dwordx4 v164, s[6:7]
	s_waitcnt vmcnt(8)
	s_waitcnt lgkmcnt(0)
	s_barrier
	v_mfma_f32_16x16x32_bf16 v[60:63], v[128:131], v[214:217], 0
	v_mfma_f32_16x16x32_bf16 v[56:59], v[136:139], v[214:217], 0
	v_mfma_f32_16x16x32_bf16 v[44:47], v[128:131], v[222:225], 0
	v_mfma_f32_16x16x32_bf16 v[40:43], v[136:139], v[222:225], 0
	v_mfma_f32_16x16x32_bf16 v[28:31], v[128:131], v[230:233], 0
	v_mfma_f32_16x16x32_bf16 v[24:27], v[136:139], v[230:233], 0
	v_mfma_f32_16x16x32_bf16 v[12:15], v[128:131], v[238:241], 0
	v_mfma_f32_16x16x32_bf16 v[8:11], v[136:139], v[238:241], 0
	v_mfma_f32_16x16x32_bf16 v[60:63], v[132:135], v[218:221], v[60:63]
	v_mfma_f32_16x16x32_bf16 v[56:59], v[140:143], v[218:221], v[56:59]
	v_mfma_f32_16x16x32_bf16 v[44:47], v[132:135], v[226:229], v[44:47]
	v_mfma_f32_16x16x32_bf16 v[40:43], v[140:143], v[226:229], v[40:43]
	v_mfma_f32_16x16x32_bf16 v[28:31], v[132:135], v[234:237], v[28:31]
	v_mfma_f32_16x16x32_bf16 v[24:27], v[140:143], v[234:237], v[24:27]
	v_mfma_f32_16x16x32_bf16 v[12:15], v[132:135], v[242:245], v[12:15]
	v_mfma_f32_16x16x32_bf16 v[8:11], v[140:143], v[242:245], v[8:11]
	v_mfma_f32_16x16x32_bf16 v[52:55], v[174:177], v[214:217], 0
	v_mfma_f32_16x16x32_bf16 v[48:51], v[188:191], v[214:217], 0
	v_mfma_f32_16x16x32_bf16 v[36:39], v[174:177], v[222:225], 0
	v_mfma_f32_16x16x32_bf16 v[32:35], v[188:191], v[222:225], 0
	v_mfma_f32_16x16x32_bf16 v[20:23], v[174:177], v[230:233], 0
	v_mfma_f32_16x16x32_bf16 v[16:19], v[188:191], v[230:233], 0
	v_mfma_f32_16x16x32_bf16 v[4:7], v[174:177], v[238:241], 0
	v_mfma_f32_16x16x32_bf16 v[0:3], v[188:191], v[238:241], 0
	v_mfma_f32_16x16x32_bf16 v[52:55], v[184:187], v[218:221], v[52:55]
	v_mfma_f32_16x16x32_bf16 v[48:51], v[210:213], v[218:221], v[48:51]
	v_mfma_f32_16x16x32_bf16 v[36:39], v[184:187], v[226:229], v[36:39]
	v_mfma_f32_16x16x32_bf16 v[32:35], v[210:213], v[226:229], v[32:35]
	v_mfma_f32_16x16x32_bf16 v[20:23], v[184:187], v[234:237], v[20:23]
	v_mfma_f32_16x16x32_bf16 v[16:19], v[210:213], v[234:237], v[16:19]
	v_mfma_f32_16x16x32_bf16 v[4:7], v[184:187], v[242:245], v[4:7]
	v_mfma_f32_16x16x32_bf16 v[0:3], v[210:213], v[242:245], v[0:3]
	s_barrier
; #define PG8_STAGE(bufoff, gbase, voff) do { _Pragma("unroll") for (int _i = 0; _i < 2; ++_i) \
;         __builtin_amdgcn_global_load_lds((const unsigned*)((const char*)(gbase) + (voff)[_i]), (PG8_LAS unsigned*)(lds + (bufoff) + ldsw + _i * 8192), 16, 0, 0); } while (0)
; #define PG8_LDA(dst, b, h) do { _Pragma("unroll") for (int m = 0; m < 4; ++m) _Pragma("unroll") for (int k = 0; k < 2; ++k) dst[m][k] = *(const PG8_LAS bf16x8*)(lds + PG8_SA(b, h) + aoff + m * 2048 + k * 1024); } while (0)
; #define PG8_LDB(dst, b, h) do { _Pragma("unroll") for (int n = 0; n < 2; ++n) _Pragma("unroll") for (int k = 0; k < 2; ++k) dst[n][k] = *(const PG8_LAS bf16x8*)(lds + PG8_SB(b, h) + boff + n * 2048 + k * 1024); } while (0)
; #define PG8_MMA(ai, bj, At, Bt) do { __builtin_amdgcn_s_setprio(1); _Pragma("unroll") for (int m = 0; m < 4; ++m) _Pragma("unroll") for (int n = 0; n < 2; ++n) _Pragma("unroll") for (int k = 0; k < 2; ++k) \
;         acc[ai][bj][m][n] = __builtin_amdgcn_mfma_f32_16x16x32_bf16(Bt[n][k], At[m][k], acc[ai][bj][m][n], 0, 0, 0); __builtin_amdgcn_s_setprio(0); } while (0)
; #define PG8_WAIT_V(n) asm volatile("s_waitcnt vmcnt(" #n ")" ::: "memory")
; #define PG8_WAIT_L(n) asm volatile("s_waitcnt lgkmcnt(" #n ")" ::: "memory")
; #define PG8_BAR __builtin_amdgcn_s_barrier()
; #define PG8_SCHED __builtin_amdgcn_sched_barrier(0)
; template <class Epi, class Sched, bool ALIGN_EPI = false, bool SP2 = false>
; __device__ __forceinline__ void gemm_phase(PG8_LAS unsigned char* lds, const Gemm g, const Sched& S, const Epi& E) {
;     ...
;             PG8_LDB(B0, 1, 0); PG8_LDB(B1, 1, 1); PG8_SCHED; PG8_LDA(At, 1, 0); PG8_STAGE(PG8_SA(0, 1), a2 + hstep, voffA);
;             PG8_WAIT_V(8); PG8_WAIT_L(0); PG8_BAR; PG8_MMA(0, 0, At, B0); PG8_MMA(0, 1, At, B1); PG8_BAR; PG8_SCHED;
;             PG8_LDA(At, 1, 1); PG8_STAGE(PG8_SB(1, 0), b3, voffB); PG8_STAGE(PG8_SB(1, 1), b3 + hstep, voffB); PG8_STAGE(PG8_SA(1, 0), a3, voffA);
;             PG8_WAIT_V(8); PG8_WAIT_L(0); PG8_BAR; PG8_MMA(1, 0, At, B0); PG8_MMA(1, 1, At, B1); PG8_BAR; PG8_SCHED;
	ds_read_b128 v[128:131], v254 offset:32768
	ds_read_b128 v[132:135], v254 offset:33792
	ds_read_b128 v[136:139], v254 offset:34816
	ds_read_b128 v[140:143], v254 offset:35840
	ds_read_b128 v[174:177], v254 offset:49152
	ds_read_b128 v[184:187], v254 offset:50176
	ds_read_b128 v[188:191], v254 offset:51200
	ds_read_b128 v[210:213], v254 offset:52224
	s_add_u32 s0, s6, 0xb0000
	s_addc_u32 s1, s7, 0
	s_mov_b32 m0, s42
	ds_read_b128 v[214:217], v181 offset:32768
	ds_read_b128 v[218:221], v181 offset:33792
	ds_read_b128 v[222:225], v181 offset:34816
	ds_read_b128 v[226:229], v181 offset:35840
	ds_read_b128 v[230:233], v181 offset:36864
	ds_read_b128 v[234:237], v181 offset:37888
	ds_read_b128 v[238:241], v181 offset:38912
	ds_read_b128 v[242:245], v181 offset:39936
	global_load_lds_dwordx4 v168, s[0:1]
	s_mov_b32 m0, s43
	s_nop 0
	global_load_lds_dwordx4 v164, s[0:1]
	s_waitcnt vmcnt(8)
	s_waitcnt lgkmcnt(0)
	s_barrier
	v_mfma_f32_16x16x32_bf16 v[124:127], v[128:131], v[214:217], v[124:127]
	v_mfma_f32_16x16x32_bf16 v[120:123], v[136:139], v[214:217], v[120:123]
	v_mfma_f32_16x16x32_bf16 v[108:111], v[128:131], v[222:225], v[108:111]
	v_mfma_f32_16x16x32_bf16 v[104:107], v[136:139], v[222:225], v[104:107]
	v_mfma_f32_16x16x32_bf16 v[92:95], v[128:131], v[230:233], v[92:95]
	v_mfma_f32_16x16x32_bf16 v[88:91], v[136:139], v[230:233], v[88:91]
	v_mfma_f32_16x16x32_bf16 v[76:79], v[128:131], v[238:241], v[76:79]
	v_mfma_f32_16x16x32_bf16 v[72:75], v[136:139], v[238:241], v[72:75]
	v_mfma_f32_16x16x32_bf16 v[124:127], v[132:135], v[218:221], v[124:127]
	v_mfma_f32_16x16x32_bf16 v[120:123], v[140:143], v[218:221], v[120:123]
	v_mfma_f32_16x16x32_bf16 v[108:111], v[132:135], v[226:229], v[108:111]
	v_mfma_f32_16x16x32_bf16 v[104:107], v[140:143], v[226:229], v[104:107]
	v_mfma_f32_16x16x32_bf16 v[92:95], v[132:135], v[234:237], v[92:95]
	v_mfma_f32_16x16x32_bf16 v[88:91], v[140:143], v[234:237], v[88:91]
	v_mfma_f32_16x16x32_bf16 v[76:79], v[132:135], v[242:245], v[76:79]
	v_mfma_f32_16x16x32_bf16 v[72:75], v[140:143], v[242:245], v[72:75]
	v_mfma_f32_16x16x32_bf16 v[116:119], v[174:177], v[214:217], v[116:119]
	v_mfma_f32_16x16x32_bf16 v[112:115], v[188:191], v[214:217], v[112:115]
	v_mfma_f32_16x16x32_bf16 v[100:103], v[174:177], v[222:225], v[100:103]
	v_mfma_f32_16x16x32_bf16 v[96:99], v[188:191], v[222:225], v[96:99]
	v_mfma_f32_16x16x32_bf16 v[84:87], v[174:177], v[230:233], v[84:87]
	v_mfma_f32_16x16x32_bf16 v[80:83], v[188:191], v[230:233], v[80:83]
	v_mfma_f32_16x16x32_bf16 v[68:71], v[174:177], v[238:241], v[68:71]
	v_mfma_f32_16x16x32_bf16 v[64:67], v[188:191], v[238:241], v[64:67]
	v_mfma_f32_16x16x32_bf16 v[116:119], v[184:187], v[218:221], v[116:119]
	v_mfma_f32_16x16x32_bf16 v[112:115], v[210:213], v[218:221], v[112:115]
	v_mfma_f32_16x16x32_bf16 v[100:103], v[184:187], v[226:229], v[100:103]
	v_mfma_f32_16x16x32_bf16 v[96:99], v[210:213], v[226:229], v[96:99]
	v_mfma_f32_16x16x32_bf16 v[84:87], v[184:187], v[234:237], v[84:87]
	v_mfma_f32_16x16x32_bf16 v[80:83], v[210:213], v[234:237], v[80:83]
	v_mfma_f32_16x16x32_bf16 v[68:71], v[184:187], v[242:245], v[68:71]
	v_mfma_f32_16x16x32_bf16 v[64:67], v[210:213], v[242:245], v[64:67]
	s_barrier
	s_mov_b32 m0, s47
	s_add_u32 s0, s4, 0xb0080
	s_addc_u32 s1, s5, 0
	ds_read_b128 v[214:217], v181 offset:49152
	ds_read_b128 v[218:221], v181 offset:50176
	ds_read_b128 v[222:225], v181 offset:51200
	ds_read_b128 v[226:229], v181 offset:52224
	ds_read_b128 v[230:233], v181 offset:53248
	ds_read_b128 v[234:237], v181 offset:54272
	ds_read_b128 v[238:241], v181 offset:55296
	ds_read_b128 v[242:245], v181 offset:56320
	s_add_u32 s98, s4, 0x80
	s_addc_u32 s99, s5, 0
	global_load_lds_dwordx4 v166, s[98:99]
	s_mov_b32 m0, s48
	s_nop 0
	global_load_lds_dwordx4 v162, s[98:99]
	s_mov_b32 m0, s51
	s_nop 0
	global_load_lds_dwordx4 v166, s[0:1]
	s_mov_b32 m0, s52
	s_nop 0
	global_load_lds_dwordx4 v162, s[0:1]
	s_mov_b32 m0, s49
	s_nop 0
	s_add_u32 s100, s6, 0x80
	s_addc_u32 s101, s7, 0
	global_load_lds_dwordx4 v168, s[100:101]
	s_mov_b32 m0, s50
	s_nop 0
	global_load_lds_dwordx4 v164, s[100:101]
	s_waitcnt vmcnt(8)
	s_waitcnt lgkmcnt(0)
	s_barrier
	v_mfma_f32_16x16x32_bf16 v[60:63], v[128:131], v[214:217], v[60:63]
	v_mfma_f32_16x16x32_bf16 v[56:59], v[136:139], v[214:217], v[56:59]
	v_mfma_f32_16x16x32_bf16 v[44:47], v[128:131], v[222:225], v[44:47]
	v_mfma_f32_16x16x32_bf16 v[40:43], v[136:139], v[222:225], v[40:43]
	v_mfma_f32_16x16x32_bf16 v[28:31], v[128:131], v[230:233], v[28:31]
	v_mfma_f32_16x16x32_bf16 v[24:27], v[136:139], v[230:233], v[24:27]
	v_mfma_f32_16x16x32_bf16 v[12:15], v[128:131], v[238:241], v[12:15]
	v_mfma_f32_16x16x32_bf16 v[8:11], v[136:139], v[238:241], v[8:11]
	v_mfma_f32_16x16x32_bf16 v[60:63], v[132:135], v[218:221], v[60:63]
	v_mfma_f32_16x16x32_bf16 v[56:59], v[140:143], v[218:221], v[56:59]
	v_mfma_f32_16x16x32_bf16 v[44:47], v[132:135], v[226:229], v[44:47]
	v_mfma_f32_16x16x32_bf16 v[40:43], v[140:143], v[226:229], v[40:43]
	v_mfma_f32_16x16x32_bf16 v[28:31], v[132:135], v[234:237], v[28:31]
	v_mfma_f32_16x16x32_bf16 v[24:27], v[140:143], v[234:237], v[24:27]
	v_mfma_f32_16x16x32_bf16 v[12:15], v[132:135], v[242:245], v[12:15]
	v_mfma_f32_16x16x32_bf16 v[8:11], v[140:143], v[242:245], v[8:11]
	v_mfma_f32_16x16x32_bf16 v[52:55], v[174:177], v[214:217], v[52:55]
	v_mfma_f32_16x16x32_bf16 v[48:51], v[188:191], v[214:217], v[48:51]
	v_mfma_f32_16x16x32_bf16 v[36:39], v[174:177], v[222:225], v[36:39]
	v_mfma_f32_16x16x32_bf16 v[32:35], v[188:191], v[222:225], v[32:35]
	v_mfma_f32_16x16x32_bf16 v[20:23], v[174:177], v[230:233], v[20:23]
	v_mfma_f32_16x16x32_bf16 v[16:19], v[188:191], v[230:233], v[16:19]
	v_mfma_f32_16x16x32_bf16 v[4:7], v[174:177], v[238:241], v[4:7]
	v_mfma_f32_16x16x32_bf16 v[0:3], v[188:191], v[238:241], v[0:3]
	v_mfma_f32_16x16x32_bf16 v[52:55], v[184:187], v[218:221], v[52:55]
	v_mfma_f32_16x16x32_bf16 v[48:51], v[210:213], v[218:221], v[48:51]
	v_mfma_f32_16x16x32_bf16 v[36:39], v[184:187], v[226:229], v[36:39]
	v_mfma_f32_16x16x32_bf16 v[32:35], v[210:213], v[226:229], v[32:35]
	v_mfma_f32_16x16x32_bf16 v[20:23], v[184:187], v[234:237], v[20:23]
	v_mfma_f32_16x16x32_bf16 v[16:19], v[210:213], v[234:237], v[16:19]
	v_mfma_f32_16x16x32_bf16 v[4:7], v[184:187], v[242:245], v[4:7]
	v_mfma_f32_16x16x32_bf16 v[0:3], v[210:213], v[242:245], v[0:3]
	s_barrier
	s_add_i32 s13, s13, 2
	s_add_u32 s10, s10, 0x100
	s_addc_u32 s11, s11, 0
	s_cmp_gt_u32 s13, 41
	s_mov_b64 s[0:1], s[2:3]
; #define PG8_STAGE(bufoff, gbase, voff) do { _Pragma("unroll") for (int _i = 0; _i < 2; ++_i) \
;         __builtin_amdgcn_global_load_lds((const unsigned*)((const char*)(gbase) + (voff)[_i]), (PG8_LAS unsigned*)(lds + (bufoff) + ldsw + _i * 8192), 16, 0, 0); } while (0)
; #define PG8_LDA(dst, b, h) do { _Pragma("unroll") for (int m = 0; m < 4; ++m) _Pragma("unroll") for (int k = 0; k < 2; ++k) dst[m][k] = *(const PG8_LAS bf16x8*)(lds + PG8_SA(b, h) + aoff + m * 2048 + k * 1024); } while (0)
; #define PG8_LDB(dst, b, h) do { _Pragma("unroll") for (int n = 0; n < 2; ++n) _Pragma("unroll") for (int k = 0; k < 2; ++k) dst[n][k] = *(const PG8_LAS bf16x8*)(lds + PG8_SB(b, h) + boff + n * 2048 + k * 1024); } while (0)
; #define PG8_MMA(ai, bj, At, Bt) do { __builtin_amdgcn_s_setprio(1); _Pragma("unroll") for (int m = 0; m < 4; ++m) _Pragma("unroll") for (int n = 0; n < 2; ++n) _Pragma("unroll") for (int k = 0; k < 2; ++k) \
;         acc[ai][bj][m][n] = __builtin_amdgcn_mfma_f32_16x16x32_bf16(Bt[n][k], At[m][k], acc[ai][bj][m][n], 0, 0, 0); __builtin_amdgcn_s_setprio(0); } while (0)
; #define PG8_WAIT_V(n) asm volatile("s_waitcnt vmcnt(" #n ")" ::: "memory")
; #define PG8_BAR __builtin_amdgcn_s_barrier()
; template <class Epi, class Sched, bool ALIGN_EPI = false, bool SP2 = false>
; __device__ __forceinline__ void gemm_phase(PG8_LAS unsigned char* lds, const Gemm g, const Sched& S, const Epi& E) {
;     ...
;         for (int t = 0; t < nt; t += 2) {
;             const bool last = (t == nt - 2);
;             const char* a1 = cA + (size_t)(t + 1) * kstep;
;             const char* a2 = last ? nA : cA + (size_t)(t + 2) * kstep; const char* b2 = last ? nB : cB + (size_t)(t + 2) * kstep;
;             const char* a3 = a2 + kstep; const char* b3 = b2 + kstep;
;             if (last && has_next) S.a_ready(nxt);
;             if constexpr (SP2) {
;             PG8_LDB(B0, 0, 0); PG8_LDB(B1, 0, 1); PG8_SCHED; PG8_LDA(At, 0, 0); PG8_STAGE(PG8_SA(1, 1), a1 + hstep, voffA);
;             PG8_WAIT_V(8); PG8_WAIT_L(0); PG8_BAR; PG8_MMA(0, 0, At, B0); PG8_MMA(0, 1, At, B1); PG8_BAR; PG8_SCHED;
;             PG8_LDA(At, 0, 1); PG8_STAGE(PG8_SB(0, 0), b2, voffB); PG8_STAGE(PG8_SB(0, 1), b2 + hstep, voffB); PG8_STAGE(PG8_SA(0, 0), a2, voffA);
;             PG8_WAIT_V(8); PG8_WAIT_L(0); PG8_BAR; PG8_MMA(1, 0, At, B0); PG8_MMA(1, 1, At, B1); PG8_BAR; PG8_SCHED;
.LBB0_545:
	ds_read_b128 v[128:131], v254
	ds_read_b128 v[132:135], v254 offset:1024
	ds_read_b128 v[136:139], v254 offset:2048
	ds_read_b128 v[140:143], v254 offset:3072
	ds_read_b128 v[174:177], v254 offset:16384
	ds_read_b128 v[184:187], v254 offset:17408
	ds_read_b128 v[188:191], v254 offset:18432
	ds_read_b128 v[210:213], v254 offset:19456
	s_add_u32 s2, s0, 0x100
	s_addc_u32 s3, s1, 0
	s_cmp_eq_u32 s13, 40
	s_cselect_b32 s7, s27, s3
	s_cselect_b32 s6, s26, s2
	s_cselect_b32 s5, s37, s11
	s_cselect_b32 s4, s36, s10
	s_add_i32 m0, s29, 0xc000
	ds_read_b128 v[214:217], v181
	ds_read_b128 v[218:221], v181 offset:1024
	ds_read_b128 v[222:225], v181 offset:2048
	ds_read_b128 v[226:229], v181 offset:3072
	ds_read_b128 v[230:233], v181 offset:4096
	ds_read_b128 v[234:237], v181 offset:5120
	ds_read_b128 v[238:241], v181 offset:6144
	ds_read_b128 v[242:245], v181 offset:7168
	global_load_lds_dwordx4 v170, s[0:1]
	s_add_i32 m0, s29, 0xe000
	s_nop 0
	global_load_lds_dwordx4 v172, s[0:1]
	s_waitcnt vmcnt(8)
	s_waitcnt lgkmcnt(0)
	s_barrier
	v_mfma_f32_16x16x32_bf16 v[124:127], v[128:131], v[214:217], v[124:127]
	v_mfma_f32_16x16x32_bf16 v[120:123], v[136:139], v[214:217], v[120:123]
	v_mfma_f32_16x16x32_bf16 v[108:111], v[128:131], v[222:225], v[108:111]
	v_mfma_f32_16x16x32_bf16 v[104:107], v[136:139], v[222:225], v[104:107]
	v_mfma_f32_16x16x32_bf16 v[92:95], v[128:131], v[230:233], v[92:95]
	v_mfma_f32_16x16x32_bf16 v[88:91], v[136:139], v[230:233], v[88:91]
	v_mfma_f32_16x16x32_bf16 v[76:79], v[128:131], v[238:241], v[76:79]
	v_mfma_f32_16x16x32_bf16 v[72:75], v[136:139], v[238:241], v[72:75]
	v_mfma_f32_16x16x32_bf16 v[124:127], v[132:135], v[218:221], v[124:127]
	v_mfma_f32_16x16x32_bf16 v[120:123], v[140:143], v[218:221], v[120:123]
	v_mfma_f32_16x16x32_bf16 v[108:111], v[132:135], v[226:229], v[108:111]
	v_mfma_f32_16x16x32_bf16 v[104:107], v[140:143], v[226:229], v[104:107]
	v_mfma_f32_16x16x32_bf16 v[92:95], v[132:135], v[234:237], v[92:95]
	v_mfma_f32_16x16x32_bf16 v[88:91], v[140:143], v[234:237], v[88:91]
	v_mfma_f32_16x16x32_bf16 v[76:79], v[132:135], v[242:245], v[76:79]
	v_mfma_f32_16x16x32_bf16 v[72:75], v[140:143], v[242:245], v[72:75]
	v_mfma_f32_16x16x32_bf16 v[116:119], v[174:177], v[214:217], v[116:119]
	v_mfma_f32_16x16x32_bf16 v[112:115], v[188:191], v[214:217], v[112:115]
	v_mfma_f32_16x16x32_bf16 v[100:103], v[174:177], v[222:225], v[100:103]
	v_mfma_f32_16x16x32_bf16 v[96:99], v[188:191], v[222:225], v[96:99]
	v_mfma_f32_16x16x32_bf16 v[84:87], v[174:177], v[230:233], v[84:87]
	v_mfma_f32_16x16x32_bf16 v[80:83], v[188:191], v[230:233], v[80:83]
	v_mfma_f32_16x16x32_bf16 v[68:71], v[174:177], v[238:241], v[68:71]
	v_mfma_f32_16x16x32_bf16 v[64:67], v[188:191], v[238:241], v[64:67]
	v_mfma_f32_16x16x32_bf16 v[116:119], v[184:187], v[218:221], v[116:119]
	v_mfma_f32_16x16x32_bf16 v[112:115], v[210:213], v[218:221], v[112:115]
	v_mfma_f32_16x16x32_bf16 v[100:103], v[184:187], v[226:229], v[100:103]
	v_mfma_f32_16x16x32_bf16 v[96:99], v[210:213], v[226:229], v[96:99]
	v_mfma_f32_16x16x32_bf16 v[84:87], v[184:187], v[234:237], v[84:87]
	v_mfma_f32_16x16x32_bf16 v[80:83], v[210:213], v[234:237], v[80:83]
	v_mfma_f32_16x16x32_bf16 v[68:71], v[184:187], v[242:245], v[68:71]
	v_mfma_f32_16x16x32_bf16 v[64:67], v[210:213], v[242:245], v[64:67]
	s_barrier
	s_mov_b32 m0, s35
	s_add_u32 s0, s4, 0xb0000
	s_addc_u32 s1, s5, 0
	ds_read_b128 v[214:217], v181 offset:16384
	ds_read_b128 v[218:221], v181 offset:17408
	ds_read_b128 v[222:225], v181 offset:18432
	ds_read_b128 v[226:229], v181 offset:19456
	ds_read_b128 v[230:233], v181 offset:20480
	ds_read_b128 v[234:237], v181 offset:21504
	ds_read_b128 v[238:241], v181 offset:22528
	ds_read_b128 v[242:245], v181 offset:23552
	global_load_lds_dwordx4 v166, s[4:5]
	s_mov_b32 m0, s38
	s_nop 0
	global_load_lds_dwordx4 v162, s[4:5]
	s_mov_b32 m0, s39
	s_nop 0
	global_load_lds_dwordx4 v166, s[0:1]
	s_mov_b32 m0, s40
	s_nop 0
	global_load_lds_dwordx4 v162, s[0:1]
	s_mov_b32 m0, s29
	s_nop 0
	global_load_lds_dwordx4 v168, s[6:7]
	s_mov_b32 m0, s41
	s_nop 0
	global_load_lds_dwordx4 v164, s[6:7]
	s_waitcnt vmcnt(8)
	s_waitcnt lgkmcnt(0)
	s_barrier
	v_mfma_f32_16x16x32_bf16 v[60:63], v[128:131], v[214:217], v[60:63]
	v_mfma_f32_16x16x32_bf16 v[56:59], v[136:139], v[214:217], v[56:59]
	v_mfma_f32_16x16x32_bf16 v[44:47], v[128:131], v[222:225], v[44:47]
	v_mfma_f32_16x16x32_bf16 v[40:43], v[136:139], v[222:225], v[40:43]
	v_mfma_f32_16x16x32_bf16 v[28:31], v[128:131], v[230:233], v[28:31]
	v_mfma_f32_16x16x32_bf16 v[24:27], v[136:139], v[230:233], v[24:27]
	v_mfma_f32_16x16x32_bf16 v[12:15], v[128:131], v[238:241], v[12:15]
	v_mfma_f32_16x16x32_bf16 v[8:11], v[136:139], v[238:241], v[8:11]
	v_mfma_f32_16x16x32_bf16 v[60:63], v[132:135], v[218:221], v[60:63]
	v_mfma_f32_16x16x32_bf16 v[56:59], v[140:143], v[218:221], v[56:59]
	v_mfma_f32_16x16x32_bf16 v[44:47], v[132:135], v[226:229], v[44:47]
	v_mfma_f32_16x16x32_bf16 v[40:43], v[140:143], v[226:229], v[40:43]
	v_mfma_f32_16x16x32_bf16 v[28:31], v[132:135], v[234:237], v[28:31]
	v_mfma_f32_16x16x32_bf16 v[24:27], v[140:143], v[234:237], v[24:27]
	v_mfma_f32_16x16x32_bf16 v[12:15], v[132:135], v[242:245], v[12:15]
	v_mfma_f32_16x16x32_bf16 v[8:11], v[140:143], v[242:245], v[8:11]
	v_mfma_f32_16x16x32_bf16 v[52:55], v[174:177], v[214:217], v[52:55]
	v_mfma_f32_16x16x32_bf16 v[48:51], v[188:191], v[214:217], v[48:51]
	v_mfma_f32_16x16x32_bf16 v[36:39], v[174:177], v[222:225], v[36:39]
	v_mfma_f32_16x16x32_bf16 v[32:35], v[188:191], v[222:225], v[32:35]
	v_mfma_f32_16x16x32_bf16 v[20:23], v[174:177], v[230:233], v[20:23]
	v_mfma_f32_16x16x32_bf16 v[16:19], v[188:191], v[230:233], v[16:19]
	v_mfma_f32_16x16x32_bf16 v[4:7], v[174:177], v[238:241], v[4:7]
	v_mfma_f32_16x16x32_bf16 v[0:3], v[188:191], v[238:241], v[0:3]
	v_mfma_f32_16x16x32_bf16 v[52:55], v[184:187], v[218:221], v[52:55]
	v_mfma_f32_16x16x32_bf16 v[48:51], v[210:213], v[218:221], v[48:51]
	v_mfma_f32_16x16x32_bf16 v[36:39], v[184:187], v[226:229], v[36:39]
	v_mfma_f32_16x16x32_bf16 v[32:35], v[210:213], v[226:229], v[32:35]
	v_mfma_f32_16x16x32_bf16 v[20:23], v[184:187], v[234:237], v[20:23]
	v_mfma_f32_16x16x32_bf16 v[16:19], v[210:213], v[234:237], v[16:19]
	v_mfma_f32_16x16x32_bf16 v[4:7], v[184:187], v[242:245], v[4:7]
	v_mfma_f32_16x16x32_bf16 v[0:3], v[210:213], v[242:245], v[0:3]
	s_barrier
; #define PG8_STAGE(bufoff, gbase, voff) do { _Pragma("unroll") for (int _i = 0; _i < 2; ++_i) \
;         __builtin_amdgcn_global_load_lds((const unsigned*)((const char*)(gbase) + (voff)[_i]), (PG8_LAS unsigned*)(lds + (bufoff) + ldsw + _i * 8192), 16, 0, 0); } while (0)
; #define PG8_BAR __builtin_amdgcn_s_barrier()
; template <class Epi, class Sched, bool ALIGN_EPI = false, bool SP2 = false>
; __device__ __forceinline__ void gemm_phase(PG8_LAS unsigned char* lds, const Gemm g, const Sched& S, const Epi& E) {
;     ...
;             PG8_LDB(B0, 1, 0); PG8_LDB(B1, 1, 1); PG8_SCHED; PG8_LDA(At, 1, 0); PG8_STAGE(PG8_SA(0, 1), a2 + hstep, voffA);
;             PG8_WAIT_V(8); PG8_WAIT_L(0); PG8_BAR; PG8_MMA(0, 0, At, B0); PG8_MMA(0, 1, At, B1); PG8_BAR; PG8_SCHED;
;             PG8_LDA(At, 1, 1); PG8_STAGE(PG8_SB(1, 0), b3, voffB); PG8_STAGE(PG8_SB(1, 1), b3 + hstep, voffB); PG8_STAGE(PG8_SA(1, 0), a3, voffA);
;             PG8_WAIT_V(8); PG8_WAIT_L(0); PG8_BAR; PG8_MMA(1, 0, At, B0); PG8_MMA(1, 1, At, B1); PG8_BAR; PG8_SCHED;
;             } else {
;             PG8_LDB(B0, 0, 0); PG8_SCHED; PG8_LDA(At, 0, 0); PG8_STAGE(PG8_SA(1, 1), a1 + hstep, voffA);
;             PG8_WAIT_L(8); PG8_BAR; PG8_WAIT_L(0); PG8_MMA(0, 0, At, B0); PG8_BAR; PG8_SCHED;
;             PG8_LDB(B1, 0, 1); PG8_STAGE(PG8_SB(0, 0), b2, voffB);
;             PG8_BAR; PG8_WAIT_L(0); PG8_MMA(0, 1, At, B1); PG8_BAR;
;             PG8_LDA(At, 0, 1); PG8_STAGE(PG8_SA(0, 0), a2, voffA);
;             PG8_BAR; PG8_WAIT_L(0); PG8_MMA(1, 0, At, B0); PG8_BAR; PG8_SCHED;
;             PG8_STAGE(PG8_SB(0, 1), b2 + hstep, voffB);
;             PG8_WAIT_V(6); PG8_BAR; PG8_MMA(1, 1, At, B1); PG8_BAR;
;             PG8_LDB(B0, 1, 0); PG8_SCHED; PG8_LDA(At, 1, 0); PG8_STAGE(PG8_SA(0, 1), a2 + hstep, voffA);
;             PG8_WAIT_L(8); PG8_BAR; PG8_WAIT_L(0); PG8_MMA(0, 0, At, B0); PG8_BAR; PG8_SCHED;
;             PG8_LDB(B1, 1, 1); PG8_STAGE(PG8_SB(1, 0), b3, voffB);
;             PG8_BAR; PG8_WAIT_L(0); PG8_MMA(0, 1, At, B1); PG8_BAR;
;             PG8_LDA(At, 1, 1); PG8_STAGE(PG8_SA(1, 0), a3, voffA);
;             PG8_BAR; PG8_WAIT_L(0); PG8_MMA(1, 0, At, B0); PG8_BAR; PG8_SCHED;
;             PG8_STAGE(PG8_SB(1, 1), b3 + hstep, voffB);
;             PG8_WAIT_V(6); PG8_BAR; PG8_MMA(1, 1, At, B1); PG8_BAR;
;             }
;         }
;         if constexpr (ALIGN_EPI) { if (wr == 0) PG8_BAR; }
	ds_read_b128 v[128:131], v254 offset:32768
	ds_read_b128 v[132:135], v254 offset:33792
	ds_read_b128 v[136:139], v254 offset:34816
	ds_read_b128 v[140:143], v254 offset:35840
	ds_read_b128 v[174:177], v254 offset:49152
	ds_read_b128 v[184:187], v254 offset:50176
	ds_read_b128 v[188:191], v254 offset:51200
	ds_read_b128 v[210:213], v254 offset:52224
	s_add_u32 s0, s6, 0xb0000
	s_addc_u32 s1, s7, 0
	s_mov_b32 m0, s42
	ds_read_b128 v[214:217], v181 offset:32768
	ds_read_b128 v[218:221], v181 offset:33792
	ds_read_b128 v[222:225], v181 offset:34816
	ds_read_b128 v[226:229], v181 offset:35840
	ds_read_b128 v[230:233], v181 offset:36864
	ds_read_b128 v[234:237], v181 offset:37888
	ds_read_b128 v[238:241], v181 offset:38912
	ds_read_b128 v[242:245], v181 offset:39936
	global_load_lds_dwordx4 v168, s[0:1]
	s_mov_b32 m0, s43
	s_nop 0
	global_load_lds_dwordx4 v164, s[0:1]
	s_waitcnt vmcnt(8)
	s_waitcnt lgkmcnt(0)
	s_barrier
	v_mfma_f32_16x16x32_bf16 v[124:127], v[128:131], v[214:217], v[124:127]
	v_mfma_f32_16x16x32_bf16 v[120:123], v[136:139], v[214:217], v[120:123]
	v_mfma_f32_16x16x32_bf16 v[108:111], v[128:131], v[222:225], v[108:111]
	v_mfma_f32_16x16x32_bf16 v[104:107], v[136:139], v[222:225], v[104:107]
	v_mfma_f32_16x16x32_bf16 v[92:95], v[128:131], v[230:233], v[92:95]
	v_mfma_f32_16x16x32_bf16 v[88:91], v[136:139], v[230:233], v[88:91]
	v_mfma_f32_16x16x32_bf16 v[76:79], v[128:131], v[238:241], v[76:79]
	v_mfma_f32_16x16x32_bf16 v[72:75], v[136:139], v[238:241], v[72:75]
	v_mfma_f32_16x16x32_bf16 v[124:127], v[132:135], v[218:221], v[124:127]
	v_mfma_f32_16x16x32_bf16 v[120:123], v[140:143], v[218:221], v[120:123]
	v_mfma_f32_16x16x32_bf16 v[108:111], v[132:135], v[226:229], v[108:111]
	v_mfma_f32_16x16x32_bf16 v[104:107], v[140:143], v[226:229], v[104:107]
	v_mfma_f32_16x16x32_bf16 v[92:95], v[132:135], v[234:237], v[92:95]
	v_mfma_f32_16x16x32_bf16 v[88:91], v[140:143], v[234:237], v[88:91]
	v_mfma_f32_16x16x32_bf16 v[76:79], v[132:135], v[242:245], v[76:79]
	v_mfma_f32_16x16x32_bf16 v[72:75], v[140:143], v[242:245], v[72:75]
	v_mfma_f32_16x16x32_bf16 v[116:119], v[174:177], v[214:217], v[116:119]
	v_mfma_f32_16x16x32_bf16 v[112:115], v[188:191], v[214:217], v[112:115]
	v_mfma_f32_16x16x32_bf16 v[100:103], v[174:177], v[222:225], v[100:103]
	v_mfma_f32_16x16x32_bf16 v[96:99], v[188:191], v[222:225], v[96:99]
	v_mfma_f32_16x16x32_bf16 v[84:87], v[174:177], v[230:233], v[84:87]
	v_mfma_f32_16x16x32_bf16 v[80:83], v[188:191], v[230:233], v[80:83]
	v_mfma_f32_16x16x32_bf16 v[68:71], v[174:177], v[238:241], v[68:71]
	v_mfma_f32_16x16x32_bf16 v[64:67], v[188:191], v[238:241], v[64:67]
	v_mfma_f32_16x16x32_bf16 v[116:119], v[184:187], v[218:221], v[116:119]
	v_mfma_f32_16x16x32_bf16 v[112:115], v[210:213], v[218:221], v[112:115]
	v_mfma_f32_16x16x32_bf16 v[100:103], v[184:187], v[226:229], v[100:103]
	v_mfma_f32_16x16x32_bf16 v[96:99], v[210:213], v[226:229], v[96:99]
	v_mfma_f32_16x16x32_bf16 v[84:87], v[184:187], v[234:237], v[84:87]
	v_mfma_f32_16x16x32_bf16 v[80:83], v[210:213], v[234:237], v[80:83]
	v_mfma_f32_16x16x32_bf16 v[68:71], v[184:187], v[242:245], v[68:71]
	v_mfma_f32_16x16x32_bf16 v[64:67], v[210:213], v[242:245], v[64:67]
	s_barrier
	s_mov_b32 m0, s47
	s_add_u32 s0, s4, 0xb0080
	s_addc_u32 s1, s5, 0
	ds_read_b128 v[214:217], v181 offset:49152
	ds_read_b128 v[218:221], v181 offset:50176
	ds_read_b128 v[222:225], v181 offset:51200
	ds_read_b128 v[226:229], v181 offset:52224
	ds_read_b128 v[230:233], v181 offset:53248
	ds_read_b128 v[234:237], v181 offset:54272
	ds_read_b128 v[238:241], v181 offset:55296
	ds_read_b128 v[242:245], v181 offset:56320
	s_add_u32 s98, s4, 0x80
	s_addc_u32 s99, s5, 0
	global_load_lds_dwordx4 v166, s[98:99]
	s_mov_b32 m0, s48
	s_nop 0
	global_load_lds_dwordx4 v162, s[98:99]
	s_mov_b32 m0, s51
	s_nop 0
	global_load_lds_dwordx4 v166, s[0:1]
	s_mov_b32 m0, s52
	s_nop 0
	global_load_lds_dwordx4 v162, s[0:1]
	s_mov_b32 m0, s49
	s_nop 0
	s_add_u32 s100, s6, 0x80
	s_addc_u32 s101, s7, 0
	global_load_lds_dwordx4 v168, s[100:101]
	s_mov_b32 m0, s50
	s_nop 0
	global_load_lds_dwordx4 v164, s[100:101]
	s_waitcnt vmcnt(8)
	s_waitcnt lgkmcnt(0)
	s_barrier
	v_mfma_f32_16x16x32_bf16 v[60:63], v[128:131], v[214:217], v[60:63]
	v_mfma_f32_16x16x32_bf16 v[56:59], v[136:139], v[214:217], v[56:59]
	v_mfma_f32_16x16x32_bf16 v[44:47], v[128:131], v[222:225], v[44:47]
	v_mfma_f32_16x16x32_bf16 v[40:43], v[136:139], v[222:225], v[40:43]
	v_mfma_f32_16x16x32_bf16 v[28:31], v[128:131], v[230:233], v[28:31]
	v_mfma_f32_16x16x32_bf16 v[24:27], v[136:139], v[230:233], v[24:27]
	v_mfma_f32_16x16x32_bf16 v[12:15], v[128:131], v[238:241], v[12:15]
	v_mfma_f32_16x16x32_bf16 v[8:11], v[136:139], v[238:241], v[8:11]
	v_mfma_f32_16x16x32_bf16 v[60:63], v[132:135], v[218:221], v[60:63]
	v_mfma_f32_16x16x32_bf16 v[56:59], v[140:143], v[218:221], v[56:59]
	v_mfma_f32_16x16x32_bf16 v[44:47], v[132:135], v[226:229], v[44:47]
	v_mfma_f32_16x16x32_bf16 v[40:43], v[140:143], v[226:229], v[40:43]
	v_mfma_f32_16x16x32_bf16 v[28:31], v[132:135], v[234:237], v[28:31]
	v_mfma_f32_16x16x32_bf16 v[24:27], v[140:143], v[234:237], v[24:27]
	v_mfma_f32_16x16x32_bf16 v[12:15], v[132:135], v[242:245], v[12:15]
	v_mfma_f32_16x16x32_bf16 v[8:11], v[140:143], v[242:245], v[8:11]
	v_mfma_f32_16x16x32_bf16 v[52:55], v[174:177], v[214:217], v[52:55]
	v_mfma_f32_16x16x32_bf16 v[48:51], v[188:191], v[214:217], v[48:51]
	v_mfma_f32_16x16x32_bf16 v[36:39], v[174:177], v[222:225], v[36:39]
	v_mfma_f32_16x16x32_bf16 v[32:35], v[188:191], v[222:225], v[32:35]
	v_mfma_f32_16x16x32_bf16 v[20:23], v[174:177], v[230:233], v[20:23]
	v_mfma_f32_16x16x32_bf16 v[16:19], v[188:191], v[230:233], v[16:19]
	v_mfma_f32_16x16x32_bf16 v[4:7], v[174:177], v[238:241], v[4:7]
	v_mfma_f32_16x16x32_bf16 v[0:3], v[188:191], v[238:241], v[0:3]
	v_mfma_f32_16x16x32_bf16 v[52:55], v[184:187], v[218:221], v[52:55]
	v_mfma_f32_16x16x32_bf16 v[48:51], v[210:213], v[218:221], v[48:51]
	v_mfma_f32_16x16x32_bf16 v[36:39], v[184:187], v[226:229], v[36:39]
	v_mfma_f32_16x16x32_bf16 v[32:35], v[210:213], v[226:229], v[32:35]
	v_mfma_f32_16x16x32_bf16 v[20:23], v[184:187], v[234:237], v[20:23]
	v_mfma_f32_16x16x32_bf16 v[16:19], v[210:213], v[234:237], v[16:19]
	v_mfma_f32_16x16x32_bf16 v[4:7], v[184:187], v[242:245], v[4:7]
	v_mfma_f32_16x16x32_bf16 v[0:3], v[210:213], v[242:245], v[0:3]
	s_barrier
	s_add_i32 s13, s13, 2
	s_add_u32 s10, s10, 0x100
	s_addc_u32 s11, s11, 0
	s_cmp_gt_u32 s13, 41
	s_mov_b64 s[0:1], s[2:3]
	s_cbranch_scc0 .LBB0_545
	s_and_b64 vcc, exec, s[22:23]
	s_cbranch_vccz .LBB0_548
	s_barrier

; #define PG8_STAGE(bufoff, gbase, voff) do { _Pragma("unroll") for (int _i = 0; _i < 2; ++_i) \
;         __builtin_amdgcn_global_load_lds((const unsigned*)((const char*)(gbase) + (voff)[_i]), (PG8_LAS unsigned*)(lds + (bufoff) + ldsw + _i * 8192), 16, 0, 0); } while (0)
; #define PG8_LDA(dst, b, h) do { _Pragma("unroll") for (int m = 0; m < 4; ++m) _Pragma("unroll") for (int k = 0; k < 2; ++k) dst[m][k] = *(const PG8_LAS bf16x8*)(lds + PG8_SA(b, h) + aoff + m * 2048 + k * 1024); } while (0)
; #define PG8_LDB(dst, b, h) do { _Pragma("unroll") for (int n = 0; n < 2; ++n) _Pragma("unroll") for (int k = 0; k < 2; ++k) dst[n][k] = *(const PG8_LAS bf16x8*)(lds + PG8_SB(b, h) + boff + n * 2048 + k * 1024); } while (0)
; #define PG8_MMA(ai, bj, At, Bt) do { __builtin_amdgcn_s_setprio(1); _Pragma("unroll") for (int m = 0; m < 4; ++m) _Pragma("unroll") for (int n = 0; n < 2; ++n) _Pragma("unroll") for (int k = 0; k < 2; ++k) \
;         acc[ai][bj][m][n] = __builtin_amdgcn_mfma_f32_16x16x32_bf16(Bt[n][k], At[m][k], acc[ai][bj][m][n], 0, 0, 0); __builtin_amdgcn_s_setprio(0); } while (0)
; #define PG8_WAIT_V(n) asm volatile("s_waitcnt vmcnt(" #n ")" ::: "memory")
; #define PG8_BAR __builtin_amdgcn_s_barrier()
; template <class Epi, class Sched, bool ALIGN_EPI = false, bool SP2 = false>
; __device__ __forceinline__ void gemm_phase(PG8_LAS unsigned char* lds, const Gemm g, const Sched& S, const Epi& E) {
;     ...
;         for (int t = 0; t < nt; t += 2) {
;             const bool last = (t == nt - 2);
;             const char* a1 = cA + (size_t)(t + 1) * kstep;
;             const char* a2 = last ? nA : cA + (size_t)(t + 2) * kstep; const char* b2 = last ? nB : cB + (size_t)(t + 2) * kstep;
;             const char* a3 = a2 + kstep; const char* b3 = b2 + kstep;
;             if (last && has_next) S.a_ready(nxt);
;             if constexpr (SP2) {
;             PG8_LDB(B0, 0, 0); PG8_LDB(B1, 0, 1); PG8_SCHED; PG8_LDA(At, 0, 0); PG8_STAGE(PG8_SA(1, 1), a1 + hstep, voffA);
;             PG8_WAIT_V(8); PG8_WAIT_L(0); PG8_BAR; PG8_MMA(0, 0, At, B0); PG8_MMA(0, 1, At, B1); PG8_BAR; PG8_SCHED;
;             PG8_LDA(At, 0, 1); PG8_STAGE(PG8_SB(0, 0), b2, voffB); PG8_STAGE(PG8_SB(0, 1), b2 + hstep, voffB); PG8_STAGE(PG8_SA(0, 0), a2, voffA);
;             PG8_WAIT_V(8); PG8_WAIT_L(0); PG8_BAR; PG8_MMA(1, 0, At, B0); PG8_MMA(1, 1, At, B1); PG8_BAR; PG8_SCHED;
.Lsgi_peel:
	ds_read_b128 v[140:143], v254
	ds_read_b128 v[162:165], v254 offset:1024
	ds_read_b128 v[166:169], v254 offset:2048
	ds_read_b128 v[170:173], v254 offset:3072
	ds_read_b128 v[180:183], v254 offset:16384
	ds_read_b128 v[184:187], v254 offset:17408
	ds_read_b128 v[188:191], v254 offset:18432
	ds_read_b128 v[210:213], v254 offset:19456
	s_add_u32 s2, s0, 0xfffc0080
	s_addc_u32 s3, s1, -1
	s_cmp_eq_u32 s55, 12
	s_cselect_b32 s5, s13, s3
	s_cselect_b32 s4, s25, s2
	s_cselect_b32 s3, s23, s39
	s_cselect_b32 s2, s33, s38
	s_add_i32 m0, s6, 0xc000
	ds_read_b128 v[214:217], v178
	ds_read_b128 v[218:221], v178 offset:1024
	ds_read_b128 v[222:225], v178 offset:2048
	ds_read_b128 v[226:229], v178 offset:3072
	ds_read_b128 v[230:233], v178 offset:4096
	ds_read_b128 v[234:237], v178 offset:5120
	ds_read_b128 v[238:241], v178 offset:6144
	ds_read_b128 v[242:245], v178 offset:7168
	global_load_lds_dwordx4 v136, s[0:1]
	s_add_i32 m0, s6, 0xe000
	s_nop 0
	global_load_lds_dwordx4 v138, s[0:1]
	s_waitcnt vmcnt(8)
	s_waitcnt lgkmcnt(0)
	s_barrier
	v_mfma_f32_16x16x32_bf16 v[124:127], v[140:143], v[214:217], 0
	v_mfma_f32_16x16x32_bf16 v[120:123], v[166:169], v[214:217], 0
	v_mfma_f32_16x16x32_bf16 v[108:111], v[140:143], v[222:225], 0
	v_mfma_f32_16x16x32_bf16 v[104:107], v[166:169], v[222:225], 0
	v_mfma_f32_16x16x32_bf16 v[92:95], v[140:143], v[230:233], 0
	v_mfma_f32_16x16x32_bf16 v[88:91], v[166:169], v[230:233], 0
	v_mfma_f32_16x16x32_bf16 v[76:79], v[140:143], v[238:241], 0
	v_mfma_f32_16x16x32_bf16 v[72:75], v[166:169], v[238:241], 0
	v_mfma_f32_16x16x32_bf16 v[124:127], v[162:165], v[218:221], v[124:127]
	v_mfma_f32_16x16x32_bf16 v[120:123], v[170:173], v[218:221], v[120:123]
	v_mfma_f32_16x16x32_bf16 v[108:111], v[162:165], v[226:229], v[108:111]
	v_mfma_f32_16x16x32_bf16 v[104:107], v[170:173], v[226:229], v[104:107]
	v_mfma_f32_16x16x32_bf16 v[92:95], v[162:165], v[234:237], v[92:95]
	v_mfma_f32_16x16x32_bf16 v[88:91], v[170:173], v[234:237], v[88:91]
	v_mfma_f32_16x16x32_bf16 v[76:79], v[162:165], v[242:245], v[76:79]
	v_mfma_f32_16x16x32_bf16 v[72:75], v[170:173], v[242:245], v[72:75]
	v_mfma_f32_16x16x32_bf16 v[116:119], v[180:183], v[214:217], 0
	v_mfma_f32_16x16x32_bf16 v[112:115], v[188:191], v[214:217], 0
	v_mfma_f32_16x16x32_bf16 v[100:103], v[180:183], v[222:225], 0
	v_mfma_f32_16x16x32_bf16 v[96:99], v[188:191], v[222:225], 0
	v_mfma_f32_16x16x32_bf16 v[84:87], v[180:183], v[230:233], 0
	v_mfma_f32_16x16x32_bf16 v[80:83], v[188:191], v[230:233], 0
	v_mfma_f32_16x16x32_bf16 v[68:71], v[180:183], v[238:241], 0
	v_mfma_f32_16x16x32_bf16 v[64:67], v[188:191], v[238:241], 0
	v_mfma_f32_16x16x32_bf16 v[116:119], v[184:187], v[218:221], v[116:119]
	v_mfma_f32_16x16x32_bf16 v[112:115], v[210:213], v[218:221], v[112:115]
	v_mfma_f32_16x16x32_bf16 v[100:103], v[184:187], v[226:229], v[100:103]
	v_mfma_f32_16x16x32_bf16 v[96:99], v[210:213], v[226:229], v[96:99]
	v_mfma_f32_16x16x32_bf16 v[84:87], v[184:187], v[234:237], v[84:87]
	v_mfma_f32_16x16x32_bf16 v[80:83], v[210:213], v[234:237], v[80:83]
	v_mfma_f32_16x16x32_bf16 v[68:71], v[184:187], v[242:245], v[68:71]
	v_mfma_f32_16x16x32_bf16 v[64:67], v[210:213], v[242:245], v[64:67]
	s_barrier
	s_mov_b32 m0, s31
	s_add_u32 s56, s2, 0x40000
	s_addc_u32 s57, s3, 0
	ds_read_b128 v[214:217], v178 offset:16384
	ds_read_b128 v[218:221], v178 offset:17408
	ds_read_b128 v[222:225], v178 offset:18432
	ds_read_b128 v[226:229], v178 offset:19456
	ds_read_b128 v[230:233], v178 offset:20480
	ds_read_b128 v[234:237], v178 offset:21504
	ds_read_b128 v[238:241], v178 offset:22528
	ds_read_b128 v[242:245], v178 offset:23552
	global_load_lds_dwordx4 v132, s[2:3]
	s_mov_b32 m0, s34
	s_nop 0
	global_load_lds_dwordx4 v128, s[2:3]
	s_mov_b32 m0, s35
	s_nop 0
	global_load_lds_dwordx4 v132, s[56:57]
	s_mov_b32 m0, s40
	s_nop 0
	global_load_lds_dwordx4 v128, s[56:57]
	s_mov_b32 m0, s6
	s_nop 0
	global_load_lds_dwordx4 v134, s[4:5]
	s_mov_b32 m0, s41
	s_nop 0
	global_load_lds_dwordx4 v130, s[4:5]
	s_waitcnt vmcnt(8)
	s_waitcnt lgkmcnt(0)
	s_barrier
	v_mfma_f32_16x16x32_bf16 v[60:63], v[140:143], v[214:217], 0
	v_mfma_f32_16x16x32_bf16 v[56:59], v[166:169], v[214:217], 0
	v_mfma_f32_16x16x32_bf16 v[44:47], v[140:143], v[222:225], 0
	v_mfma_f32_16x16x32_bf16 v[40:43], v[166:169], v[222:225], 0
	v_mfma_f32_16x16x32_bf16 v[28:31], v[140:143], v[230:233], 0
	v_mfma_f32_16x16x32_bf16 v[24:27], v[166:169], v[230:233], 0
	v_mfma_f32_16x16x32_bf16 v[12:15], v[140:143], v[238:241], 0
	v_mfma_f32_16x16x32_bf16 v[8:11], v[166:169], v[238:241], 0
	v_mfma_f32_16x16x32_bf16 v[60:63], v[162:165], v[218:221], v[60:63]
	v_mfma_f32_16x16x32_bf16 v[56:59], v[170:173], v[218:221], v[56:59]
	v_mfma_f32_16x16x32_bf16 v[44:47], v[162:165], v[226:229], v[44:47]
	v_mfma_f32_16x16x32_bf16 v[40:43], v[170:173], v[226:229], v[40:43]
	v_mfma_f32_16x16x32_bf16 v[28:31], v[162:165], v[234:237], v[28:31]
	v_mfma_f32_16x16x32_bf16 v[24:27], v[170:173], v[234:237], v[24:27]
	v_mfma_f32_16x16x32_bf16 v[12:15], v[162:165], v[242:245], v[12:15]
	v_mfma_f32_16x16x32_bf16 v[8:11], v[170:173], v[242:245], v[8:11]
	v_mfma_f32_16x16x32_bf16 v[52:55], v[180:183], v[214:217], 0
	v_mfma_f32_16x16x32_bf16 v[48:51], v[188:191], v[214:217], 0
	v_mfma_f32_16x16x32_bf16 v[36:39], v[180:183], v[222:225], 0
	v_mfma_f32_16x16x32_bf16 v[32:35], v[188:191], v[222:225], 0
	v_mfma_f32_16x16x32_bf16 v[20:23], v[180:183], v[230:233], 0
	v_mfma_f32_16x16x32_bf16 v[16:19], v[188:191], v[230:233], 0
	v_mfma_f32_16x16x32_bf16 v[4:7], v[180:183], v[238:241], 0
	v_mfma_f32_16x16x32_bf16 v[0:3], v[188:191], v[238:241], 0
	v_mfma_f32_16x16x32_bf16 v[52:55], v[184:187], v[218:221], v[52:55]
	v_mfma_f32_16x16x32_bf16 v[48:51], v[210:213], v[218:221], v[48:51]
	v_mfma_f32_16x16x32_bf16 v[36:39], v[184:187], v[226:229], v[36:39]
	v_mfma_f32_16x16x32_bf16 v[32:35], v[210:213], v[226:229], v[32:35]
	v_mfma_f32_16x16x32_bf16 v[20:23], v[184:187], v[234:237], v[20:23]
	v_mfma_f32_16x16x32_bf16 v[16:19], v[210:213], v[234:237], v[16:19]
	v_mfma_f32_16x16x32_bf16 v[4:7], v[184:187], v[242:245], v[4:7]
	v_mfma_f32_16x16x32_bf16 v[0:3], v[210:213], v[242:245], v[0:3]
	s_barrier
; #define PG8_STAGE(bufoff, gbase, voff) do { _Pragma("unroll") for (int _i = 0; _i < 2; ++_i) \
;         __builtin_amdgcn_global_load_lds((const unsigned*)((const char*)(gbase) + (voff)[_i]), (PG8_LAS unsigned*)(lds + (bufoff) + ldsw + _i * 8192), 16, 0, 0); } while (0)
; #define PG8_LDA(dst, b, h) do { _Pragma("unroll") for (int m = 0; m < 4; ++m) _Pragma("unroll") for (int k = 0; k < 2; ++k) dst[m][k] = *(const PG8_LAS bf16x8*)(lds + PG8_SA(b, h) + aoff + m * 2048 + k * 1024); } while (0)
; #define PG8_LDB(dst, b, h) do { _Pragma("unroll") for (int n = 0; n < 2; ++n) _Pragma("unroll") for (int k = 0; k < 2; ++k) dst[n][k] = *(const PG8_LAS bf16x8*)(lds + PG8_SB(b, h) + boff + n * 2048 + k * 1024); } while (0)
; #define PG8_MMA(ai, bj, At, Bt) do { __builtin_amdgcn_s_setprio(1); _Pragma("unroll") for (int m = 0; m < 4; ++m) _Pragma("unroll") for (int n = 0; n < 2; ++n) _Pragma("unroll") for (int k = 0; k < 2; ++k) \
;         acc[ai][bj][m][n] = __builtin_amdgcn_mfma_f32_16x16x32_bf16(Bt[n][k], At[m][k], acc[ai][bj][m][n], 0, 0, 0); __builtin_amdgcn_s_setprio(0); } while (0)
; #define PG8_WAIT_V(n) asm volatile("s_waitcnt vmcnt(" #n ")" ::: "memory")
; #define PG8_WAIT_L(n) asm volatile("s_waitcnt lgkmcnt(" #n ")" ::: "memory")
; #define PG8_BAR __builtin_amdgcn_s_barrier()
; #define PG8_SCHED __builtin_amdgcn_sched_barrier(0)
; template <class Epi, class Sched, bool ALIGN_EPI = false, bool SP2 = false>
; __device__ __forceinline__ void gemm_phase(PG8_LAS unsigned char* lds, const Gemm g, const Sched& S, const Epi& E) {
;     ...
;             PG8_LDB(B0, 1, 0); PG8_LDB(B1, 1, 1); PG8_SCHED; PG8_LDA(At, 1, 0); PG8_STAGE(PG8_SA(0, 1), a2 + hstep, voffA);
;             PG8_WAIT_V(8); PG8_WAIT_L(0); PG8_BAR; PG8_MMA(0, 0, At, B0); PG8_MMA(0, 1, At, B1); PG8_BAR; PG8_SCHED;
;             PG8_LDA(At, 1, 1); PG8_STAGE(PG8_SB(1, 0), b3, voffB); PG8_STAGE(PG8_SB(1, 1), b3 + hstep, voffB); PG8_STAGE(PG8_SA(1, 0), a3, voffA);
;             PG8_WAIT_V(8); PG8_WAIT_L(0); PG8_BAR; PG8_MMA(1, 0, At, B0); PG8_MMA(1, 1, At, B1); PG8_BAR; PG8_SCHED;
	ds_read_b128 v[140:143], v254 offset:32768
	ds_read_b128 v[162:165], v254 offset:33792
	ds_read_b128 v[166:169], v254 offset:34816
	ds_read_b128 v[170:173], v254 offset:35840
	ds_read_b128 v[180:183], v254 offset:49152
	ds_read_b128 v[184:187], v254 offset:50176
	ds_read_b128 v[188:191], v254 offset:51200
	ds_read_b128 v[210:213], v254 offset:52224
	s_add_u32 s4, s4, 0x40000
	s_addc_u32 s5, s5, 0
	s_mov_b32 m0, s42
	ds_read_b128 v[214:217], v178 offset:32768
	ds_read_b128 v[218:221], v178 offset:33792
	ds_read_b128 v[222:225], v178 offset:34816
	ds_read_b128 v[226:229], v178 offset:35840
	ds_read_b128 v[230:233], v178 offset:36864
	ds_read_b128 v[234:237], v178 offset:37888
	ds_read_b128 v[238:241], v178 offset:38912
	ds_read_b128 v[242:245], v178 offset:39936
	global_load_lds_dwordx4 v134, s[4:5]
	s_mov_b32 m0, s43
	s_nop 0
	global_load_lds_dwordx4 v130, s[4:5]
	s_waitcnt vmcnt(8)
	s_waitcnt lgkmcnt(0)
	s_barrier
	v_mfma_f32_16x16x32_bf16 v[124:127], v[140:143], v[214:217], v[124:127]
	v_mfma_f32_16x16x32_bf16 v[120:123], v[166:169], v[214:217], v[120:123]
	v_mfma_f32_16x16x32_bf16 v[108:111], v[140:143], v[222:225], v[108:111]
	v_mfma_f32_16x16x32_bf16 v[104:107], v[166:169], v[222:225], v[104:107]
	v_mfma_f32_16x16x32_bf16 v[92:95], v[140:143], v[230:233], v[92:95]
	v_mfma_f32_16x16x32_bf16 v[88:91], v[166:169], v[230:233], v[88:91]
	v_mfma_f32_16x16x32_bf16 v[76:79], v[140:143], v[238:241], v[76:79]
	v_mfma_f32_16x16x32_bf16 v[72:75], v[166:169], v[238:241], v[72:75]
	v_mfma_f32_16x16x32_bf16 v[124:127], v[162:165], v[218:221], v[124:127]
	v_mfma_f32_16x16x32_bf16 v[120:123], v[170:173], v[218:221], v[120:123]
	v_mfma_f32_16x16x32_bf16 v[108:111], v[162:165], v[226:229], v[108:111]
	v_mfma_f32_16x16x32_bf16 v[104:107], v[170:173], v[226:229], v[104:107]
	v_mfma_f32_16x16x32_bf16 v[92:95], v[162:165], v[234:237], v[92:95]
	v_mfma_f32_16x16x32_bf16 v[88:91], v[170:173], v[234:237], v[88:91]
	v_mfma_f32_16x16x32_bf16 v[76:79], v[162:165], v[242:245], v[76:79]
	v_mfma_f32_16x16x32_bf16 v[72:75], v[170:173], v[242:245], v[72:75]
	v_mfma_f32_16x16x32_bf16 v[116:119], v[180:183], v[214:217], v[116:119]
	v_mfma_f32_16x16x32_bf16 v[112:115], v[188:191], v[214:217], v[112:115]
	v_mfma_f32_16x16x32_bf16 v[100:103], v[180:183], v[222:225], v[100:103]
	v_mfma_f32_16x16x32_bf16 v[96:99], v[188:191], v[222:225], v[96:99]
	v_mfma_f32_16x16x32_bf16 v[84:87], v[180:183], v[230:233], v[84:87]
	v_mfma_f32_16x16x32_bf16 v[80:83], v[188:191], v[230:233], v[80:83]
	v_mfma_f32_16x16x32_bf16 v[68:71], v[180:183], v[238:241], v[68:71]
	v_mfma_f32_16x16x32_bf16 v[64:67], v[188:191], v[238:241], v[64:67]
	v_mfma_f32_16x16x32_bf16 v[116:119], v[184:187], v[218:221], v[116:119]
	v_mfma_f32_16x16x32_bf16 v[112:115], v[210:213], v[218:221], v[112:115]
	v_mfma_f32_16x16x32_bf16 v[100:103], v[184:187], v[226:229], v[100:103]
	v_mfma_f32_16x16x32_bf16 v[96:99], v[210:213], v[226:229], v[96:99]
	v_mfma_f32_16x16x32_bf16 v[84:87], v[184:187], v[234:237], v[84:87]
	v_mfma_f32_16x16x32_bf16 v[80:83], v[210:213], v[234:237], v[80:83]
	v_mfma_f32_16x16x32_bf16 v[68:71], v[184:187], v[242:245], v[68:71]
	v_mfma_f32_16x16x32_bf16 v[64:67], v[210:213], v[242:245], v[64:67]
	s_barrier
	s_mov_b32 m0, s48
	s_add_u32 s2, s2, 0x40080
	s_addc_u32 s3, s3, 0
	ds_read_b128 v[214:217], v178 offset:49152
	ds_read_b128 v[218:221], v178 offset:50176
	ds_read_b128 v[222:225], v178 offset:51200
	ds_read_b128 v[226:229], v178 offset:52224
	ds_read_b128 v[230:233], v178 offset:53248
	ds_read_b128 v[234:237], v178 offset:54272
	ds_read_b128 v[238:241], v178 offset:55296
	ds_read_b128 v[242:245], v178 offset:56320
	s_add_u32 s98, s2, 0xfffc0000
	s_addc_u32 s99, s3, -1
	global_load_lds_dwordx4 v132, s[98:99]
	s_mov_b32 m0, s49
	s_nop 0
	global_load_lds_dwordx4 v128, s[98:99]
	s_mov_b32 m0, s52
	s_nop 0
	global_load_lds_dwordx4 v132, s[2:3]
	s_mov_b32 m0, s53
	s_nop 0
	global_load_lds_dwordx4 v128, s[2:3]
	s_mov_b32 m0, s50
	s_nop 0
	s_add_u32 s100, s4, 0xfffc0080
	s_addc_u32 s101, s5, -1
	global_load_lds_dwordx4 v134, s[100:101]
	s_mov_b32 m0, s51
	s_nop 0
	global_load_lds_dwordx4 v130, s[100:101]
	s_waitcnt vmcnt(8)
	s_waitcnt lgkmcnt(0)
	s_barrier
	v_mfma_f32_16x16x32_bf16 v[60:63], v[140:143], v[214:217], v[60:63]
	v_mfma_f32_16x16x32_bf16 v[56:59], v[166:169], v[214:217], v[56:59]
	v_mfma_f32_16x16x32_bf16 v[44:47], v[140:143], v[222:225], v[44:47]
	v_mfma_f32_16x16x32_bf16 v[40:43], v[166:169], v[222:225], v[40:43]
	v_mfma_f32_16x16x32_bf16 v[28:31], v[140:143], v[230:233], v[28:31]
	v_mfma_f32_16x16x32_bf16 v[24:27], v[166:169], v[230:233], v[24:27]
	v_mfma_f32_16x16x32_bf16 v[12:15], v[140:143], v[238:241], v[12:15]
	v_mfma_f32_16x16x32_bf16 v[8:11], v[166:169], v[238:241], v[8:11]
	v_mfma_f32_16x16x32_bf16 v[60:63], v[162:165], v[218:221], v[60:63]
	v_mfma_f32_16x16x32_bf16 v[56:59], v[170:173], v[218:221], v[56:59]
	v_mfma_f32_16x16x32_bf16 v[44:47], v[162:165], v[226:229], v[44:47]
	v_mfma_f32_16x16x32_bf16 v[40:43], v[170:173], v[226:229], v[40:43]
	v_mfma_f32_16x16x32_bf16 v[28:31], v[162:165], v[234:237], v[28:31]
	v_mfma_f32_16x16x32_bf16 v[24:27], v[170:173], v[234:237], v[24:27]
	v_mfma_f32_16x16x32_bf16 v[12:15], v[162:165], v[242:245], v[12:15]
	v_mfma_f32_16x16x32_bf16 v[8:11], v[170:173], v[242:245], v[8:11]
	v_mfma_f32_16x16x32_bf16 v[52:55], v[180:183], v[214:217], v[52:55]
	v_mfma_f32_16x16x32_bf16 v[48:51], v[188:191], v[214:217], v[48:51]
	v_mfma_f32_16x16x32_bf16 v[36:39], v[180:183], v[222:225], v[36:39]
	v_mfma_f32_16x16x32_bf16 v[32:35], v[188:191], v[222:225], v[32:35]
	v_mfma_f32_16x16x32_bf16 v[20:23], v[180:183], v[230:233], v[20:23]
	v_mfma_f32_16x16x32_bf16 v[16:19], v[188:191], v[230:233], v[16:19]
	v_mfma_f32_16x16x32_bf16 v[4:7], v[180:183], v[238:241], v[4:7]
	v_mfma_f32_16x16x32_bf16 v[0:3], v[188:191], v[238:241], v[0:3]
	v_mfma_f32_16x16x32_bf16 v[52:55], v[184:187], v[218:221], v[52:55]
	v_mfma_f32_16x16x32_bf16 v[48:51], v[210:213], v[218:221], v[48:51]
	v_mfma_f32_16x16x32_bf16 v[36:39], v[184:187], v[226:229], v[36:39]
	v_mfma_f32_16x16x32_bf16 v[32:35], v[210:213], v[226:229], v[32:35]
	v_mfma_f32_16x16x32_bf16 v[20:23], v[184:187], v[234:237], v[20:23]
	v_mfma_f32_16x16x32_bf16 v[16:19], v[210:213], v[234:237], v[16:19]
	v_mfma_f32_16x16x32_bf16 v[4:7], v[184:187], v[242:245], v[4:7]
	v_mfma_f32_16x16x32_bf16 v[0:3], v[210:213], v[242:245], v[0:3]
	s_barrier
	s_add_i32 s55, s55, 2
	s_add_u32 s0, s0, 0x100
	s_addc_u32 s1, s1, 0
	s_add_u32 s38, s38, 0x100
	s_addc_u32 s39, s39, 0
	s_cmp_gt_u32 s55, 13
; #define PG8_STAGE(bufoff, gbase, voff) do { _Pragma("unroll") for (int _i = 0; _i < 2; ++_i) \
;         __builtin_amdgcn_global_load_lds((const unsigned*)((const char*)(gbase) + (voff)[_i]), (PG8_LAS unsigned*)(lds + (bufoff) + ldsw + _i * 8192), 16, 0, 0); } while (0)
; #define PG8_LDA(dst, b, h) do { _Pragma("unroll") for (int m = 0; m < 4; ++m) _Pragma("unroll") for (int k = 0; k < 2; ++k) dst[m][k] = *(const PG8_LAS bf16x8*)(lds + PG8_SA(b, h) + aoff + m * 2048 + k * 1024); } while (0)
; #define PG8_LDB(dst, b, h) do { _Pragma("unroll") for (int n = 0; n < 2; ++n) _Pragma("unroll") for (int k = 0; k < 2; ++k) dst[n][k] = *(const PG8_LAS bf16x8*)(lds + PG8_SB(b, h) + boff + n * 2048 + k * 1024); } while (0)
; #define PG8_MMA(ai, bj, At, Bt) do { __builtin_amdgcn_s_setprio(1); _Pragma("unroll") for (int m = 0; m < 4; ++m) _Pragma("unroll") for (int n = 0; n < 2; ++n) _Pragma("unroll") for (int k = 0; k < 2; ++k) \
;         acc[ai][bj][m][n] = __builtin_amdgcn_mfma_f32_16x16x32_bf16(Bt[n][k], At[m][k], acc[ai][bj][m][n], 0, 0, 0); __builtin_amdgcn_s_setprio(0); } while (0)
; #define PG8_WAIT_V(n) asm volatile("s_waitcnt vmcnt(" #n ")" ::: "memory")
; #define PG8_BAR __builtin_amdgcn_s_barrier()
; template <class Epi, class Sched, bool ALIGN_EPI = false, bool SP2 = false>
; __device__ __forceinline__ void gemm_phase(PG8_LAS unsigned char* lds, const Gemm g, const Sched& S, const Epi& E) {
;     ...
;         for (int t = 0; t < nt; t += 2) {
;             const bool last = (t == nt - 2);
;             const char* a1 = cA + (size_t)(t + 1) * kstep;
;             const char* a2 = last ? nA : cA + (size_t)(t + 2) * kstep; const char* b2 = last ? nB : cB + (size_t)(t + 2) * kstep;
;             const char* a3 = a2 + kstep; const char* b3 = b2 + kstep;
;             if (last && has_next) S.a_ready(nxt);
;             if constexpr (SP2) {
;             PG8_LDB(B0, 0, 0); PG8_LDB(B1, 0, 1); PG8_SCHED; PG8_LDA(At, 0, 0); PG8_STAGE(PG8_SA(1, 1), a1 + hstep, voffA);
;             PG8_WAIT_V(8); PG8_WAIT_L(0); PG8_BAR; PG8_MMA(0, 0, At, B0); PG8_MMA(0, 1, At, B1); PG8_BAR; PG8_SCHED;
;             PG8_LDA(At, 0, 1); PG8_STAGE(PG8_SB(0, 0), b2, voffB); PG8_STAGE(PG8_SB(0, 1), b2 + hstep, voffB); PG8_STAGE(PG8_SA(0, 0), a2, voffA);
;             PG8_WAIT_V(8); PG8_WAIT_L(0); PG8_BAR; PG8_MMA(1, 0, At, B0); PG8_MMA(1, 1, At, B1); PG8_BAR; PG8_SCHED;
.LBB0_749:
	ds_read_b128 v[140:143], v254
	ds_read_b128 v[162:165], v254 offset:1024
	ds_read_b128 v[166:169], v254 offset:2048
	ds_read_b128 v[170:173], v254 offset:3072
	ds_read_b128 v[180:183], v254 offset:16384
	ds_read_b128 v[184:187], v254 offset:17408
	ds_read_b128 v[188:191], v254 offset:18432
	ds_read_b128 v[210:213], v254 offset:19456
	s_add_u32 s2, s0, 0xfffc0080
	s_addc_u32 s3, s1, -1
	s_cmp_eq_u32 s55, 12
	s_cselect_b32 s5, s13, s3
	s_cselect_b32 s4, s25, s2
	s_cselect_b32 s3, s23, s39
	s_cselect_b32 s2, s33, s38
	s_add_i32 m0, s6, 0xc000
	ds_read_b128 v[214:217], v178
	ds_read_b128 v[218:221], v178 offset:1024
	ds_read_b128 v[222:225], v178 offset:2048
	ds_read_b128 v[226:229], v178 offset:3072
	ds_read_b128 v[230:233], v178 offset:4096
	ds_read_b128 v[234:237], v178 offset:5120
	ds_read_b128 v[238:241], v178 offset:6144
	ds_read_b128 v[242:245], v178 offset:7168
	global_load_lds_dwordx4 v136, s[0:1]
	s_add_i32 m0, s6, 0xe000
	s_nop 0
	global_load_lds_dwordx4 v138, s[0:1]
	s_waitcnt vmcnt(8)
	s_waitcnt lgkmcnt(0)
	s_barrier
	v_mfma_f32_16x16x32_bf16 v[124:127], v[140:143], v[214:217], v[124:127]
	v_mfma_f32_16x16x32_bf16 v[120:123], v[166:169], v[214:217], v[120:123]
	v_mfma_f32_16x16x32_bf16 v[108:111], v[140:143], v[222:225], v[108:111]
	v_mfma_f32_16x16x32_bf16 v[104:107], v[166:169], v[222:225], v[104:107]
	v_mfma_f32_16x16x32_bf16 v[92:95], v[140:143], v[230:233], v[92:95]
	v_mfma_f32_16x16x32_bf16 v[88:91], v[166:169], v[230:233], v[88:91]
	v_mfma_f32_16x16x32_bf16 v[76:79], v[140:143], v[238:241], v[76:79]
	v_mfma_f32_16x16x32_bf16 v[72:75], v[166:169], v[238:241], v[72:75]
	v_mfma_f32_16x16x32_bf16 v[124:127], v[162:165], v[218:221], v[124:127]
	v_mfma_f32_16x16x32_bf16 v[120:123], v[170:173], v[218:221], v[120:123]
	v_mfma_f32_16x16x32_bf16 v[108:111], v[162:165], v[226:229], v[108:111]
	v_mfma_f32_16x16x32_bf16 v[104:107], v[170:173], v[226:229], v[104:107]
	v_mfma_f32_16x16x32_bf16 v[92:95], v[162:165], v[234:237], v[92:95]
	v_mfma_f32_16x16x32_bf16 v[88:91], v[170:173], v[234:237], v[88:91]
	v_mfma_f32_16x16x32_bf16 v[76:79], v[162:165], v[242:245], v[76:79]
	v_mfma_f32_16x16x32_bf16 v[72:75], v[170:173], v[242:245], v[72:75]
	v_mfma_f32_16x16x32_bf16 v[116:119], v[180:183], v[214:217], v[116:119]
	v_mfma_f32_16x16x32_bf16 v[112:115], v[188:191], v[214:217], v[112:115]
	v_mfma_f32_16x16x32_bf16 v[100:103], v[180:183], v[222:225], v[100:103]
	v_mfma_f32_16x16x32_bf16 v[96:99], v[188:191], v[222:225], v[96:99]
	v_mfma_f32_16x16x32_bf16 v[84:87], v[180:183], v[230:233], v[84:87]
	v_mfma_f32_16x16x32_bf16 v[80:83], v[188:191], v[230:233], v[80:83]
	v_mfma_f32_16x16x32_bf16 v[68:71], v[180:183], v[238:241], v[68:71]
	v_mfma_f32_16x16x32_bf16 v[64:67], v[188:191], v[238:241], v[64:67]
	v_mfma_f32_16x16x32_bf16 v[116:119], v[184:187], v[218:221], v[116:119]
	v_mfma_f32_16x16x32_bf16 v[112:115], v[210:213], v[218:221], v[112:115]
	v_mfma_f32_16x16x32_bf16 v[100:103], v[184:187], v[226:229], v[100:103]
	v_mfma_f32_16x16x32_bf16 v[96:99], v[210:213], v[226:229], v[96:99]
	v_mfma_f32_16x16x32_bf16 v[84:87], v[184:187], v[234:237], v[84:87]
	v_mfma_f32_16x16x32_bf16 v[80:83], v[210:213], v[234:237], v[80:83]
	v_mfma_f32_16x16x32_bf16 v[68:71], v[184:187], v[242:245], v[68:71]
	v_mfma_f32_16x16x32_bf16 v[64:67], v[210:213], v[242:245], v[64:67]
	s_barrier
	s_mov_b32 m0, s31
	s_add_u32 s56, s2, 0x40000
	s_addc_u32 s57, s3, 0
	ds_read_b128 v[214:217], v178 offset:16384
	ds_read_b128 v[218:221], v178 offset:17408
	ds_read_b128 v[222:225], v178 offset:18432
	ds_read_b128 v[226:229], v178 offset:19456
	ds_read_b128 v[230:233], v178 offset:20480
	ds_read_b128 v[234:237], v178 offset:21504
	ds_read_b128 v[238:241], v178 offset:22528
	ds_read_b128 v[242:245], v178 offset:23552
	global_load_lds_dwordx4 v132, s[2:3]
	s_mov_b32 m0, s34
	s_nop 0
	global_load_lds_dwordx4 v128, s[2:3]
	s_mov_b32 m0, s35
	s_nop 0
	global_load_lds_dwordx4 v132, s[56:57]
	s_mov_b32 m0, s40
	s_nop 0
	global_load_lds_dwordx4 v128, s[56:57]
	s_mov_b32 m0, s6
	s_nop 0
	global_load_lds_dwordx4 v134, s[4:5]
	s_mov_b32 m0, s41
	s_nop 0
	global_load_lds_dwordx4 v130, s[4:5]
	s_waitcnt vmcnt(8)
	s_waitcnt lgkmcnt(0)
	s_barrier
	v_mfma_f32_16x16x32_bf16 v[60:63], v[140:143], v[214:217], v[60:63]
	v_mfma_f32_16x16x32_bf16 v[56:59], v[166:169], v[214:217], v[56:59]
	v_mfma_f32_16x16x32_bf16 v[44:47], v[140:143], v[222:225], v[44:47]
	v_mfma_f32_16x16x32_bf16 v[40:43], v[166:169], v[222:225], v[40:43]
	v_mfma_f32_16x16x32_bf16 v[28:31], v[140:143], v[230:233], v[28:31]
	v_mfma_f32_16x16x32_bf16 v[24:27], v[166:169], v[230:233], v[24:27]
	v_mfma_f32_16x16x32_bf16 v[12:15], v[140:143], v[238:241], v[12:15]
	v_mfma_f32_16x16x32_bf16 v[8:11], v[166:169], v[238:241], v[8:11]
	v_mfma_f32_16x16x32_bf16 v[60:63], v[162:165], v[218:221], v[60:63]
	v_mfma_f32_16x16x32_bf16 v[56:59], v[170:173], v[218:221], v[56:59]
	v_mfma_f32_16x16x32_bf16 v[44:47], v[162:165], v[226:229], v[44:47]
	v_mfma_f32_16x16x32_bf16 v[40:43], v[170:173], v[226:229], v[40:43]
	v_mfma_f32_16x16x32_bf16 v[28:31], v[162:165], v[234:237], v[28:31]
	v_mfma_f32_16x16x32_bf16 v[24:27], v[170:173], v[234:237], v[24:27]
	v_mfma_f32_16x16x32_bf16 v[12:15], v[162:165], v[242:245], v[12:15]
	v_mfma_f32_16x16x32_bf16 v[8:11], v[170:173], v[242:245], v[8:11]
	v_mfma_f32_16x16x32_bf16 v[52:55], v[180:183], v[214:217], v[52:55]
	v_mfma_f32_16x16x32_bf16 v[48:51], v[188:191], v[214:217], v[48:51]
	v_mfma_f32_16x16x32_bf16 v[36:39], v[180:183], v[222:225], v[36:39]
	v_mfma_f32_16x16x32_bf16 v[32:35], v[188:191], v[222:225], v[32:35]
	v_mfma_f32_16x16x32_bf16 v[20:23], v[180:183], v[230:233], v[20:23]
	v_mfma_f32_16x16x32_bf16 v[16:19], v[188:191], v[230:233], v[16:19]
	v_mfma_f32_16x16x32_bf16 v[4:7], v[180:183], v[238:241], v[4:7]
	v_mfma_f32_16x16x32_bf16 v[0:3], v[188:191], v[238:241], v[0:3]
	v_mfma_f32_16x16x32_bf16 v[52:55], v[184:187], v[218:221], v[52:55]
	v_mfma_f32_16x16x32_bf16 v[48:51], v[210:213], v[218:221], v[48:51]
	v_mfma_f32_16x16x32_bf16 v[36:39], v[184:187], v[226:229], v[36:39]
	v_mfma_f32_16x16x32_bf16 v[32:35], v[210:213], v[226:229], v[32:35]
	v_mfma_f32_16x16x32_bf16 v[20:23], v[184:187], v[234:237], v[20:23]
	v_mfma_f32_16x16x32_bf16 v[16:19], v[210:213], v[234:237], v[16:19]
	v_mfma_f32_16x16x32_bf16 v[4:7], v[184:187], v[242:245], v[4:7]
	v_mfma_f32_16x16x32_bf16 v[0:3], v[210:213], v[242:245], v[0:3]
	s_barrier
; #define PG8_STAGE(bufoff, gbase, voff) do { _Pragma("unroll") for (int _i = 0; _i < 2; ++_i) \
;         __builtin_amdgcn_global_load_lds((const unsigned*)((const char*)(gbase) + (voff)[_i]), (PG8_LAS unsigned*)(lds + (bufoff) + ldsw + _i * 8192), 16, 0, 0); } while (0)
; #define PG8_BAR __builtin_amdgcn_s_barrier()
; template <class Epi, class Sched, bool ALIGN_EPI = false, bool SP2 = false>
; __device__ __forceinline__ void gemm_phase(PG8_LAS unsigned char* lds, const Gemm g, const Sched& S, const Epi& E) {
;     ...
;             PG8_LDB(B0, 1, 0); PG8_LDB(B1, 1, 1); PG8_SCHED; PG8_LDA(At, 1, 0); PG8_STAGE(PG8_SA(0, 1), a2 + hstep, voffA);
;             PG8_WAIT_V(8); PG8_WAIT_L(0); PG8_BAR; PG8_MMA(0, 0, At, B0); PG8_MMA(0, 1, At, B1); PG8_BAR; PG8_SCHED;
;             PG8_LDA(At, 1, 1); PG8_STAGE(PG8_SB(1, 0), b3, voffB); PG8_STAGE(PG8_SB(1, 1), b3 + hstep, voffB); PG8_STAGE(PG8_SA(1, 0), a3, voffA);
;             PG8_WAIT_V(8); PG8_WAIT_L(0); PG8_BAR; PG8_MMA(1, 0, At, B0); PG8_MMA(1, 1, At, B1); PG8_BAR; PG8_SCHED;
;             } else {
;             PG8_LDB(B0, 0, 0); PG8_SCHED; PG8_LDA(At, 0, 0); PG8_STAGE(PG8_SA(1, 1), a1 + hstep, voffA);
;             PG8_WAIT_L(8); PG8_BAR; PG8_WAIT_L(0); PG8_MMA(0, 0, At, B0); PG8_BAR; PG8_SCHED;
;             PG8_LDB(B1, 0, 1); PG8_STAGE(PG8_SB(0, 0), b2, voffB);
;             PG8_BAR; PG8_WAIT_L(0); PG8_MMA(0, 1, At, B1); PG8_BAR;
;             PG8_LDA(At, 0, 1); PG8_STAGE(PG8_SA(0, 0), a2, voffA);
;             PG8_BAR; PG8_WAIT_L(0); PG8_MMA(1, 0, At, B0); PG8_BAR; PG8_SCHED;
;             PG8_STAGE(PG8_SB(0, 1), b2 + hstep, voffB);
;             PG8_WAIT_V(6); PG8_BAR; PG8_MMA(1, 1, At, B1); PG8_BAR;
;             PG8_LDB(B0, 1, 0); PG8_SCHED; PG8_LDA(At, 1, 0); PG8_STAGE(PG8_SA(0, 1), a2 + hstep, voffA);
;             PG8_WAIT_L(8); PG8_BAR; PG8_WAIT_L(0); PG8_MMA(0, 0, At, B0); PG8_BAR; PG8_SCHED;
;             PG8_LDB(B1, 1, 1); PG8_STAGE(PG8_SB(1, 0), b3, voffB);
;             PG8_BAR; PG8_WAIT_L(0); PG8_MMA(0, 1, At, B1); PG8_BAR;
;             PG8_LDA(At, 1, 1); PG8_STAGE(PG8_SA(1, 0), a3, voffA);
;             PG8_BAR; PG8_WAIT_L(0); PG8_MMA(1, 0, At, B0); PG8_BAR; PG8_SCHED;
;             PG8_STAGE(PG8_SB(1, 1), b3 + hstep, voffB);
;             PG8_WAIT_V(6); PG8_BAR; PG8_MMA(1, 1, At, B1); PG8_BAR;
;             }
;         }
;         if constexpr (ALIGN_EPI) { if (wr == 0) PG8_BAR; }
	ds_read_b128 v[140:143], v254 offset:32768
	ds_read_b128 v[162:165], v254 offset:33792
	ds_read_b128 v[166:169], v254 offset:34816
	ds_read_b128 v[170:173], v254 offset:35840
	ds_read_b128 v[180:183], v254 offset:49152
	ds_read_b128 v[184:187], v254 offset:50176
	ds_read_b128 v[188:191], v254 offset:51200
	ds_read_b128 v[210:213], v254 offset:52224
	s_add_u32 s4, s4, 0x40000
	s_addc_u32 s5, s5, 0
	s_mov_b32 m0, s42
	ds_read_b128 v[214:217], v178 offset:32768
	ds_read_b128 v[218:221], v178 offset:33792
	ds_read_b128 v[222:225], v178 offset:34816
	ds_read_b128 v[226:229], v178 offset:35840
	ds_read_b128 v[230:233], v178 offset:36864
	ds_read_b128 v[234:237], v178 offset:37888
	ds_read_b128 v[238:241], v178 offset:38912
	ds_read_b128 v[242:245], v178 offset:39936
	global_load_lds_dwordx4 v134, s[4:5]
	s_mov_b32 m0, s43
	s_nop 0
	global_load_lds_dwordx4 v130, s[4:5]
	s_waitcnt vmcnt(8)
	s_waitcnt lgkmcnt(0)
	s_barrier
	v_mfma_f32_16x16x32_bf16 v[124:127], v[140:143], v[214:217], v[124:127]
	v_mfma_f32_16x16x32_bf16 v[120:123], v[166:169], v[214:217], v[120:123]
	v_mfma_f32_16x16x32_bf16 v[108:111], v[140:143], v[222:225], v[108:111]
	v_mfma_f32_16x16x32_bf16 v[104:107], v[166:169], v[222:225], v[104:107]
	v_mfma_f32_16x16x32_bf16 v[92:95], v[140:143], v[230:233], v[92:95]
	v_mfma_f32_16x16x32_bf16 v[88:91], v[166:169], v[230:233], v[88:91]
	v_mfma_f32_16x16x32_bf16 v[76:79], v[140:143], v[238:241], v[76:79]
	v_mfma_f32_16x16x32_bf16 v[72:75], v[166:169], v[238:241], v[72:75]
	v_mfma_f32_16x16x32_bf16 v[124:127], v[162:165], v[218:221], v[124:127]
	v_mfma_f32_16x16x32_bf16 v[120:123], v[170:173], v[218:221], v[120:123]
	v_mfma_f32_16x16x32_bf16 v[108:111], v[162:165], v[226:229], v[108:111]
	v_mfma_f32_16x16x32_bf16 v[104:107], v[170:173], v[226:229], v[104:107]
	v_mfma_f32_16x16x32_bf16 v[92:95], v[162:165], v[234:237], v[92:95]
	v_mfma_f32_16x16x32_bf16 v[88:91], v[170:173], v[234:237], v[88:91]
	v_mfma_f32_16x16x32_bf16 v[76:79], v[162:165], v[242:245], v[76:79]
	v_mfma_f32_16x16x32_bf16 v[72:75], v[170:173], v[242:245], v[72:75]
	v_mfma_f32_16x16x32_bf16 v[116:119], v[180:183], v[214:217], v[116:119]
	v_mfma_f32_16x16x32_bf16 v[112:115], v[188:191], v[214:217], v[112:115]
	v_mfma_f32_16x16x32_bf16 v[100:103], v[180:183], v[222:225], v[100:103]
	v_mfma_f32_16x16x32_bf16 v[96:99], v[188:191], v[222:225], v[96:99]
	v_mfma_f32_16x16x32_bf16 v[84:87], v[180:183], v[230:233], v[84:87]
	v_mfma_f32_16x16x32_bf16 v[80:83], v[188:191], v[230:233], v[80:83]
	v_mfma_f32_16x16x32_bf16 v[68:71], v[180:183], v[238:241], v[68:71]
	v_mfma_f32_16x16x32_bf16 v[64:67], v[188:191], v[238:241], v[64:67]
	v_mfma_f32_16x16x32_bf16 v[116:119], v[184:187], v[218:221], v[116:119]
	v_mfma_f32_16x16x32_bf16 v[112:115], v[210:213], v[218:221], v[112:115]
	v_mfma_f32_16x16x32_bf16 v[100:103], v[184:187], v[226:229], v[100:103]
	v_mfma_f32_16x16x32_bf16 v[96:99], v[210:213], v[226:229], v[96:99]
	v_mfma_f32_16x16x32_bf16 v[84:87], v[184:187], v[234:237], v[84:87]
	v_mfma_f32_16x16x32_bf16 v[80:83], v[210:213], v[234:237], v[80:83]
	v_mfma_f32_16x16x32_bf16 v[68:71], v[184:187], v[242:245], v[68:71]
	v_mfma_f32_16x16x32_bf16 v[64:67], v[210:213], v[242:245], v[64:67]
	s_barrier
	s_mov_b32 m0, s48
	s_add_u32 s2, s2, 0x40080
	s_addc_u32 s3, s3, 0
	ds_read_b128 v[214:217], v178 offset:49152
	ds_read_b128 v[218:221], v178 offset:50176
	ds_read_b128 v[222:225], v178 offset:51200
	ds_read_b128 v[226:229], v178 offset:52224
	ds_read_b128 v[230:233], v178 offset:53248
	ds_read_b128 v[234:237], v178 offset:54272
	ds_read_b128 v[238:241], v178 offset:55296
	ds_read_b128 v[242:245], v178 offset:56320
	s_add_u32 s98, s2, 0xfffc0000
	s_addc_u32 s99, s3, -1
	global_load_lds_dwordx4 v132, s[98:99]
	s_mov_b32 m0, s49
	s_nop 0
	global_load_lds_dwordx4 v128, s[98:99]
	s_mov_b32 m0, s52
	s_nop 0
	global_load_lds_dwordx4 v132, s[2:3]
	s_mov_b32 m0, s53
	s_nop 0
	global_load_lds_dwordx4 v128, s[2:3]
	s_mov_b32 m0, s50
	s_nop 0
	s_add_u32 s100, s4, 0xfffc0080
	s_addc_u32 s101, s5, -1
	global_load_lds_dwordx4 v134, s[100:101]
	s_mov_b32 m0, s51
	s_nop 0
	global_load_lds_dwordx4 v130, s[100:101]
	s_waitcnt vmcnt(8)
	s_waitcnt lgkmcnt(0)
	s_barrier
	v_mfma_f32_16x16x32_bf16 v[60:63], v[140:143], v[214:217], v[60:63]
	v_mfma_f32_16x16x32_bf16 v[56:59], v[166:169], v[214:217], v[56:59]
	v_mfma_f32_16x16x32_bf16 v[44:47], v[140:143], v[222:225], v[44:47]
	v_mfma_f32_16x16x32_bf16 v[40:43], v[166:169], v[222:225], v[40:43]
	v_mfma_f32_16x16x32_bf16 v[28:31], v[140:143], v[230:233], v[28:31]
	v_mfma_f32_16x16x32_bf16 v[24:27], v[166:169], v[230:233], v[24:27]
	v_mfma_f32_16x16x32_bf16 v[12:15], v[140:143], v[238:241], v[12:15]
	v_mfma_f32_16x16x32_bf16 v[8:11], v[166:169], v[238:241], v[8:11]
	v_mfma_f32_16x16x32_bf16 v[60:63], v[162:165], v[218:221], v[60:63]
	v_mfma_f32_16x16x32_bf16 v[56:59], v[170:173], v[218:221], v[56:59]
	v_mfma_f32_16x16x32_bf16 v[44:47], v[162:165], v[226:229], v[44:47]
	v_mfma_f32_16x16x32_bf16 v[40:43], v[170:173], v[226:229], v[40:43]
	v_mfma_f32_16x16x32_bf16 v[28:31], v[162:165], v[234:237], v[28:31]
	v_mfma_f32_16x16x32_bf16 v[24:27], v[170:173], v[234:237], v[24:27]
	v_mfma_f32_16x16x32_bf16 v[12:15], v[162:165], v[242:245], v[12:15]
	v_mfma_f32_16x16x32_bf16 v[8:11], v[170:173], v[242:245], v[8:11]
	v_mfma_f32_16x16x32_bf16 v[52:55], v[180:183], v[214:217], v[52:55]
	v_mfma_f32_16x16x32_bf16 v[48:51], v[188:191], v[214:217], v[48:51]
	v_mfma_f32_16x16x32_bf16 v[36:39], v[180:183], v[222:225], v[36:39]
	v_mfma_f32_16x16x32_bf16 v[32:35], v[188:191], v[222:225], v[32:35]
	v_mfma_f32_16x16x32_bf16 v[20:23], v[180:183], v[230:233], v[20:23]
	v_mfma_f32_16x16x32_bf16 v[16:19], v[188:191], v[230:233], v[16:19]
	v_mfma_f32_16x16x32_bf16 v[4:7], v[180:183], v[238:241], v[4:7]
	v_mfma_f32_16x16x32_bf16 v[0:3], v[188:191], v[238:241], v[0:3]
	v_mfma_f32_16x16x32_bf16 v[52:55], v[184:187], v[218:221], v[52:55]
	v_mfma_f32_16x16x32_bf16 v[48:51], v[210:213], v[218:221], v[48:51]
	v_mfma_f32_16x16x32_bf16 v[36:39], v[184:187], v[226:229], v[36:39]
	v_mfma_f32_16x16x32_bf16 v[32:35], v[210:213], v[226:229], v[32:35]
	v_mfma_f32_16x16x32_bf16 v[20:23], v[184:187], v[234:237], v[20:23]
	v_mfma_f32_16x16x32_bf16 v[16:19], v[210:213], v[234:237], v[16:19]
	v_mfma_f32_16x16x32_bf16 v[4:7], v[184:187], v[242:245], v[4:7]
	v_mfma_f32_16x16x32_bf16 v[0:3], v[210:213], v[242:245], v[0:3]
	s_barrier
	s_add_i32 s55, s55, 2
	s_add_u32 s0, s0, 0x100
	s_addc_u32 s1, s1, 0
	s_add_u32 s38, s38, 0x100
	s_addc_u32 s39, s39, 0
	s_cmp_gt_u32 s55, 13
	s_cbranch_scc0 .LBB0_749
	s_and_b64 vcc, exec, s[18:19]
	s_cbranch_vccz .LBB0_752
	s_barrier

; #define PG8_STAGE(bufoff, gbase, voff) do { _Pragma("unroll") for (int _i = 0; _i < 2; ++_i) \
;         __builtin_amdgcn_global_load_lds((const unsigned*)((const char*)(gbase) + (voff)[_i]), (PG8_LAS unsigned*)(lds + (bufoff) + ldsw + _i * 8192), 16, 0, 0); } while (0)
; #define PG8_LDA(dst, b, h) do { _Pragma("unroll") for (int m = 0; m < 4; ++m) _Pragma("unroll") for (int k = 0; k < 2; ++k) dst[m][k] = *(const PG8_LAS bf16x8*)(lds + PG8_SA(b, h) + aoff + m * 2048 + k * 1024); } while (0)
; #define PG8_LDB(dst, b, h) do { _Pragma("unroll") for (int n = 0; n < 2; ++n) _Pragma("unroll") for (int k = 0; k < 2; ++k) dst[n][k] = *(const PG8_LAS bf16x8*)(lds + PG8_SB(b, h) + boff + n * 2048 + k * 1024); } while (0)
; #define PG8_MMA(ai, bj, At, Bt) do { __builtin_amdgcn_s_setprio(1); _Pragma("unroll") for (int m = 0; m < 4; ++m) _Pragma("unroll") for (int n = 0; n < 2; ++n) _Pragma("unroll") for (int k = 0; k < 2; ++k) \
;         acc[ai][bj][m][n] = __builtin_amdgcn_mfma_f32_16x16x32_bf16(Bt[n][k], At[m][k], acc[ai][bj][m][n], 0, 0, 0); __builtin_amdgcn_s_setprio(0); } while (0)
; #define PG8_WAIT_V(n) asm volatile("s_waitcnt vmcnt(" #n ")" ::: "memory")
; #define PG8_BAR __builtin_amdgcn_s_barrier()
; template <class Epi, class Sched, bool ALIGN_EPI = false, bool SP2 = false>
; __device__ __forceinline__ void gemm_phase(PG8_LAS unsigned char* lds, const Gemm g, const Sched& S, const Epi& E) {
;     ...
;         for (int t = 0; t < nt; t += 2) {
;             const bool last = (t == nt - 2);
;             const char* a1 = cA + (size_t)(t + 1) * kstep;
;             const char* a2 = last ? nA : cA + (size_t)(t + 2) * kstep; const char* b2 = last ? nB : cB + (size_t)(t + 2) * kstep;
;             const char* a3 = a2 + kstep; const char* b3 = b2 + kstep;
;             if (last && has_next) S.a_ready(nxt);
;             if constexpr (SP2) {
;             PG8_LDB(B0, 0, 0); PG8_LDB(B1, 0, 1); PG8_SCHED; PG8_LDA(At, 0, 0); PG8_STAGE(PG8_SA(1, 1), a1 + hstep, voffA);
;             PG8_WAIT_V(8); PG8_WAIT_L(0); PG8_BAR; PG8_MMA(0, 0, At, B0); PG8_MMA(0, 1, At, B1); PG8_BAR; PG8_SCHED;
;             PG8_LDA(At, 0, 1); PG8_STAGE(PG8_SB(0, 0), b2, voffB); PG8_STAGE(PG8_SB(0, 1), b2 + hstep, voffB); PG8_STAGE(PG8_SA(0, 0), a2, voffA);
;             PG8_WAIT_V(8); PG8_WAIT_L(0); PG8_BAR; PG8_MMA(1, 0, At, B0); PG8_MMA(1, 1, At, B1); PG8_BAR; PG8_SCHED;
.Labi_peel:
	s_waitcnt lgkmcnt(0)
	ds_read_b128 v[140:143], v254
	ds_read_b128 v[162:165], v254 offset:1024
	ds_read_b128 v[166:169], v254 offset:2048
	ds_read_b128 v[176:179], v254 offset:3072
	ds_read_b128 v[180:183], v254 offset:16384
	ds_read_b128 v[184:187], v254 offset:17408
	ds_read_b128 v[188:191], v254 offset:18432
	ds_read_b128 v[210:213], v254 offset:19456
	s_add_u32 s2, s0, 0xfffc0080
	s_addc_u32 s3, s1, -1
	s_cmp_eq_u32 s52, 12
	s_cselect_b32 s5, s17, s3
	s_cselect_b32 s4, s48, s2
	s_cselect_b32 s3, s15, s51
	s_cselect_b32 s2, s49, s50
	s_add_i32 m0, s6, 0xc000
	ds_read_b128 v[214:217], v173
	ds_read_b128 v[218:221], v173 offset:1024
	ds_read_b128 v[222:225], v173 offset:2048
	ds_read_b128 v[226:229], v173 offset:3072
	ds_read_b128 v[230:233], v173 offset:4096
	ds_read_b128 v[234:237], v173 offset:5120
	ds_read_b128 v[238:241], v173 offset:6144
	ds_read_b128 v[242:245], v173 offset:7168
	global_load_lds_dwordx4 v136, s[0:1]
	s_add_i32 m0, s6, 0xe000
	s_nop 0
	global_load_lds_dwordx4 v138, s[0:1]
	s_waitcnt vmcnt(8)
	s_waitcnt lgkmcnt(0)
	s_barrier
	v_mfma_f32_16x16x32_bf16 v[124:127], v[140:143], v[214:217], 0
	v_mfma_f32_16x16x32_bf16 v[120:123], v[166:169], v[214:217], 0
	v_mfma_f32_16x16x32_bf16 v[112:115], v[140:143], v[222:225], 0
	v_mfma_f32_16x16x32_bf16 v[104:107], v[166:169], v[222:225], 0
	v_mfma_f32_16x16x32_bf16 v[96:99], v[140:143], v[230:233], 0
	v_mfma_f32_16x16x32_bf16 v[88:91], v[166:169], v[230:233], 0
	v_mfma_f32_16x16x32_bf16 v[80:83], v[140:143], v[238:241], 0
	v_mfma_f32_16x16x32_bf16 v[72:75], v[166:169], v[238:241], 0
	v_mfma_f32_16x16x32_bf16 v[124:127], v[162:165], v[218:221], v[124:127]
	v_mfma_f32_16x16x32_bf16 v[120:123], v[176:179], v[218:221], v[120:123]
	v_mfma_f32_16x16x32_bf16 v[112:115], v[162:165], v[226:229], v[112:115]
	v_mfma_f32_16x16x32_bf16 v[104:107], v[176:179], v[226:229], v[104:107]
	v_mfma_f32_16x16x32_bf16 v[96:99], v[162:165], v[234:237], v[96:99]
	v_mfma_f32_16x16x32_bf16 v[88:91], v[176:179], v[234:237], v[88:91]
	v_mfma_f32_16x16x32_bf16 v[80:83], v[162:165], v[242:245], v[80:83]
	v_mfma_f32_16x16x32_bf16 v[72:75], v[176:179], v[242:245], v[72:75]
	v_mfma_f32_16x16x32_bf16 v[116:119], v[180:183], v[214:217], 0
	v_mfma_f32_16x16x32_bf16 v[108:111], v[188:191], v[214:217], 0
	v_mfma_f32_16x16x32_bf16 v[100:103], v[180:183], v[222:225], 0
	v_mfma_f32_16x16x32_bf16 v[92:95], v[188:191], v[222:225], 0
	v_mfma_f32_16x16x32_bf16 v[84:87], v[180:183], v[230:233], 0
	v_mfma_f32_16x16x32_bf16 v[76:79], v[188:191], v[230:233], 0
	v_mfma_f32_16x16x32_bf16 v[68:71], v[180:183], v[238:241], 0
	v_mfma_f32_16x16x32_bf16 v[64:67], v[188:191], v[238:241], 0
	v_mfma_f32_16x16x32_bf16 v[116:119], v[184:187], v[218:221], v[116:119]
	v_mfma_f32_16x16x32_bf16 v[108:111], v[210:213], v[218:221], v[108:111]
	v_mfma_f32_16x16x32_bf16 v[100:103], v[184:187], v[226:229], v[100:103]
	v_mfma_f32_16x16x32_bf16 v[92:95], v[210:213], v[226:229], v[92:95]
	v_mfma_f32_16x16x32_bf16 v[84:87], v[184:187], v[234:237], v[84:87]
	v_mfma_f32_16x16x32_bf16 v[76:79], v[210:213], v[234:237], v[76:79]
	v_mfma_f32_16x16x32_bf16 v[68:71], v[184:187], v[242:245], v[68:71]
	v_mfma_f32_16x16x32_bf16 v[64:67], v[210:213], v[242:245], v[64:67]
	s_barrier
	s_mov_b32 m0, s27
	s_add_u32 s54, s2, 0x40000
	s_addc_u32 s55, s3, 0
	ds_read_b128 v[214:217], v173 offset:16384
	ds_read_b128 v[218:221], v173 offset:17408
	ds_read_b128 v[222:225], v173 offset:18432
	ds_read_b128 v[226:229], v173 offset:19456
	ds_read_b128 v[230:233], v173 offset:20480
	ds_read_b128 v[234:237], v173 offset:21504
	ds_read_b128 v[238:241], v173 offset:22528
	ds_read_b128 v[242:245], v173 offset:23552
	global_load_lds_dwordx4 v132, s[2:3]
	s_mov_b32 m0, s28
	s_nop 0
	global_load_lds_dwordx4 v128, s[2:3]
	s_mov_b32 m0, s29
	s_nop 0
	global_load_lds_dwordx4 v132, s[54:55]
	s_mov_b32 m0, s30
	s_nop 0
	global_load_lds_dwordx4 v128, s[54:55]
	s_mov_b32 m0, s6
	s_nop 0
	global_load_lds_dwordx4 v134, s[4:5]
	s_mov_b32 m0, s31
	s_nop 0
	global_load_lds_dwordx4 v130, s[4:5]
	s_waitcnt vmcnt(8)
	s_waitcnt lgkmcnt(0)
	s_barrier
	v_mfma_f32_16x16x32_bf16 v[60:63], v[140:143], v[214:217], 0
	v_mfma_f32_16x16x32_bf16 v[56:59], v[166:169], v[214:217], 0
	v_mfma_f32_16x16x32_bf16 v[48:51], v[140:143], v[222:225], 0
	v_mfma_f32_16x16x32_bf16 v[40:43], v[166:169], v[222:225], 0
	v_mfma_f32_16x16x32_bf16 v[32:35], v[140:143], v[230:233], 0
	v_mfma_f32_16x16x32_bf16 v[24:27], v[166:169], v[230:233], 0
	v_mfma_f32_16x16x32_bf16 v[16:19], v[140:143], v[238:241], 0
	v_mfma_f32_16x16x32_bf16 v[8:11], v[166:169], v[238:241], 0
	v_mfma_f32_16x16x32_bf16 v[60:63], v[162:165], v[218:221], v[60:63]
	v_mfma_f32_16x16x32_bf16 v[56:59], v[176:179], v[218:221], v[56:59]
	v_mfma_f32_16x16x32_bf16 v[48:51], v[162:165], v[226:229], v[48:51]
	v_mfma_f32_16x16x32_bf16 v[40:43], v[176:179], v[226:229], v[40:43]
	v_mfma_f32_16x16x32_bf16 v[32:35], v[162:165], v[234:237], v[32:35]
	v_mfma_f32_16x16x32_bf16 v[24:27], v[176:179], v[234:237], v[24:27]
	v_mfma_f32_16x16x32_bf16 v[16:19], v[162:165], v[242:245], v[16:19]
	v_mfma_f32_16x16x32_bf16 v[8:11], v[176:179], v[242:245], v[8:11]
	v_mfma_f32_16x16x32_bf16 v[52:55], v[180:183], v[214:217], 0
	v_mfma_f32_16x16x32_bf16 v[44:47], v[188:191], v[214:217], 0
	v_mfma_f32_16x16x32_bf16 v[36:39], v[180:183], v[222:225], 0
	v_mfma_f32_16x16x32_bf16 v[28:31], v[188:191], v[222:225], 0
	v_mfma_f32_16x16x32_bf16 v[20:23], v[180:183], v[230:233], 0
	v_mfma_f32_16x16x32_bf16 v[12:15], v[188:191], v[230:233], 0
	v_mfma_f32_16x16x32_bf16 v[4:7], v[180:183], v[238:241], 0
	v_mfma_f32_16x16x32_bf16 v[0:3], v[188:191], v[238:241], 0
	v_mfma_f32_16x16x32_bf16 v[52:55], v[184:187], v[218:221], v[52:55]
	v_mfma_f32_16x16x32_bf16 v[44:47], v[210:213], v[218:221], v[44:47]
	v_mfma_f32_16x16x32_bf16 v[36:39], v[184:187], v[226:229], v[36:39]
	v_mfma_f32_16x16x32_bf16 v[28:31], v[210:213], v[226:229], v[28:31]
	v_mfma_f32_16x16x32_bf16 v[20:23], v[184:187], v[234:237], v[20:23]
	v_mfma_f32_16x16x32_bf16 v[12:15], v[210:213], v[234:237], v[12:15]
	v_mfma_f32_16x16x32_bf16 v[4:7], v[184:187], v[242:245], v[4:7]
	v_mfma_f32_16x16x32_bf16 v[0:3], v[210:213], v[242:245], v[0:3]
	s_barrier
; #define PG8_STAGE(bufoff, gbase, voff) do { _Pragma("unroll") for (int _i = 0; _i < 2; ++_i) \
;         __builtin_amdgcn_global_load_lds((const unsigned*)((const char*)(gbase) + (voff)[_i]), (PG8_LAS unsigned*)(lds + (bufoff) + ldsw + _i * 8192), 16, 0, 0); } while (0)
; #define PG8_LDA(dst, b, h) do { _Pragma("unroll") for (int m = 0; m < 4; ++m) _Pragma("unroll") for (int k = 0; k < 2; ++k) dst[m][k] = *(const PG8_LAS bf16x8*)(lds + PG8_SA(b, h) + aoff + m * 2048 + k * 1024); } while (0)
; #define PG8_LDB(dst, b, h) do { _Pragma("unroll") for (int n = 0; n < 2; ++n) _Pragma("unroll") for (int k = 0; k < 2; ++k) dst[n][k] = *(const PG8_LAS bf16x8*)(lds + PG8_SB(b, h) + boff + n * 2048 + k * 1024); } while (0)
; #define PG8_MMA(ai, bj, At, Bt) do { __builtin_amdgcn_s_setprio(1); _Pragma("unroll") for (int m = 0; m < 4; ++m) _Pragma("unroll") for (int n = 0; n < 2; ++n) _Pragma("unroll") for (int k = 0; k < 2; ++k) \
;         acc[ai][bj][m][n] = __builtin_amdgcn_mfma_f32_16x16x32_bf16(Bt[n][k], At[m][k], acc[ai][bj][m][n], 0, 0, 0); __builtin_amdgcn_s_setprio(0); } while (0)
; #define PG8_WAIT_V(n) asm volatile("s_waitcnt vmcnt(" #n ")" ::: "memory")
; #define PG8_WAIT_L(n) asm volatile("s_waitcnt lgkmcnt(" #n ")" ::: "memory")
; #define PG8_BAR __builtin_amdgcn_s_barrier()
; #define PG8_SCHED __builtin_amdgcn_sched_barrier(0)
; template <class Epi, class Sched, bool ALIGN_EPI = false, bool SP2 = false>
; __device__ __forceinline__ void gemm_phase(PG8_LAS unsigned char* lds, const Gemm g, const Sched& S, const Epi& E) {
;     ...
;             PG8_LDB(B0, 1, 0); PG8_LDB(B1, 1, 1); PG8_SCHED; PG8_LDA(At, 1, 0); PG8_STAGE(PG8_SA(0, 1), a2 + hstep, voffA);
;             PG8_WAIT_V(8); PG8_WAIT_L(0); PG8_BAR; PG8_MMA(0, 0, At, B0); PG8_MMA(0, 1, At, B1); PG8_BAR; PG8_SCHED;
;             PG8_LDA(At, 1, 1); PG8_STAGE(PG8_SB(1, 0), b3, voffB); PG8_STAGE(PG8_SB(1, 1), b3 + hstep, voffB); PG8_STAGE(PG8_SA(1, 0), a3, voffA);
;             PG8_WAIT_V(8); PG8_WAIT_L(0); PG8_BAR; PG8_MMA(1, 0, At, B0); PG8_MMA(1, 1, At, B1); PG8_BAR; PG8_SCHED;
	ds_read_b128 v[140:143], v254 offset:32768
	ds_read_b128 v[162:165], v254 offset:33792
	ds_read_b128 v[166:169], v254 offset:34816
	ds_read_b128 v[176:179], v254 offset:35840
	ds_read_b128 v[180:183], v254 offset:49152
	ds_read_b128 v[184:187], v254 offset:50176
	ds_read_b128 v[188:191], v254 offset:51200
	ds_read_b128 v[210:213], v254 offset:52224
	s_add_u32 s4, s4, 0x40000
	s_addc_u32 s5, s5, 0
	s_mov_b32 m0, s33
	ds_read_b128 v[214:217], v173 offset:32768
	ds_read_b128 v[218:221], v173 offset:33792
	ds_read_b128 v[222:225], v173 offset:34816
	ds_read_b128 v[226:229], v173 offset:35840
	ds_read_b128 v[230:233], v173 offset:36864
	ds_read_b128 v[234:237], v173 offset:37888
	ds_read_b128 v[238:241], v173 offset:38912
	ds_read_b128 v[242:245], v173 offset:39936
	global_load_lds_dwordx4 v134, s[4:5]
	s_mov_b32 m0, s34
	s_nop 0
	global_load_lds_dwordx4 v130, s[4:5]
	s_waitcnt vmcnt(8)
	s_waitcnt lgkmcnt(0)
	s_barrier
	v_mfma_f32_16x16x32_bf16 v[124:127], v[140:143], v[214:217], v[124:127]
	v_mfma_f32_16x16x32_bf16 v[120:123], v[166:169], v[214:217], v[120:123]
	v_mfma_f32_16x16x32_bf16 v[112:115], v[140:143], v[222:225], v[112:115]
	v_mfma_f32_16x16x32_bf16 v[104:107], v[166:169], v[222:225], v[104:107]
	v_mfma_f32_16x16x32_bf16 v[96:99], v[140:143], v[230:233], v[96:99]
	v_mfma_f32_16x16x32_bf16 v[88:91], v[166:169], v[230:233], v[88:91]
	v_mfma_f32_16x16x32_bf16 v[80:83], v[140:143], v[238:241], v[80:83]
	v_mfma_f32_16x16x32_bf16 v[72:75], v[166:169], v[238:241], v[72:75]
	v_mfma_f32_16x16x32_bf16 v[124:127], v[162:165], v[218:221], v[124:127]
	v_mfma_f32_16x16x32_bf16 v[120:123], v[176:179], v[218:221], v[120:123]
	v_mfma_f32_16x16x32_bf16 v[112:115], v[162:165], v[226:229], v[112:115]
	v_mfma_f32_16x16x32_bf16 v[104:107], v[176:179], v[226:229], v[104:107]
	v_mfma_f32_16x16x32_bf16 v[96:99], v[162:165], v[234:237], v[96:99]
	v_mfma_f32_16x16x32_bf16 v[88:91], v[176:179], v[234:237], v[88:91]
	v_mfma_f32_16x16x32_bf16 v[80:83], v[162:165], v[242:245], v[80:83]
	v_mfma_f32_16x16x32_bf16 v[72:75], v[176:179], v[242:245], v[72:75]
	v_mfma_f32_16x16x32_bf16 v[116:119], v[180:183], v[214:217], v[116:119]
	v_mfma_f32_16x16x32_bf16 v[108:111], v[188:191], v[214:217], v[108:111]
	v_mfma_f32_16x16x32_bf16 v[100:103], v[180:183], v[222:225], v[100:103]
	v_mfma_f32_16x16x32_bf16 v[92:95], v[188:191], v[222:225], v[92:95]
	v_mfma_f32_16x16x32_bf16 v[84:87], v[180:183], v[230:233], v[84:87]
	v_mfma_f32_16x16x32_bf16 v[76:79], v[188:191], v[230:233], v[76:79]
	v_mfma_f32_16x16x32_bf16 v[68:71], v[180:183], v[238:241], v[68:71]
	v_mfma_f32_16x16x32_bf16 v[64:67], v[188:191], v[238:241], v[64:67]
	v_mfma_f32_16x16x32_bf16 v[116:119], v[184:187], v[218:221], v[116:119]
	v_mfma_f32_16x16x32_bf16 v[108:111], v[210:213], v[218:221], v[108:111]
	v_mfma_f32_16x16x32_bf16 v[100:103], v[184:187], v[226:229], v[100:103]
	v_mfma_f32_16x16x32_bf16 v[92:95], v[210:213], v[226:229], v[92:95]
	v_mfma_f32_16x16x32_bf16 v[84:87], v[184:187], v[234:237], v[84:87]
	v_mfma_f32_16x16x32_bf16 v[76:79], v[210:213], v[234:237], v[76:79]
	v_mfma_f32_16x16x32_bf16 v[68:71], v[184:187], v[242:245], v[68:71]
	v_mfma_f32_16x16x32_bf16 v[64:67], v[210:213], v[242:245], v[64:67]
	s_barrier
	s_mov_b32 m0, s37
	s_add_u32 s2, s2, 0x40080
	s_addc_u32 s3, s3, 0
	ds_read_b128 v[214:217], v173 offset:49152
	ds_read_b128 v[218:221], v173 offset:50176
	ds_read_b128 v[222:225], v173 offset:51200
	ds_read_b128 v[226:229], v173 offset:52224
	ds_read_b128 v[230:233], v173 offset:53248
	ds_read_b128 v[234:237], v173 offset:54272
	ds_read_b128 v[238:241], v173 offset:55296
	ds_read_b128 v[242:245], v173 offset:56320
	s_add_u32 s98, s2, 0xfffc0000
	s_addc_u32 s99, s3, -1
	global_load_lds_dwordx4 v132, s[98:99]
	s_mov_b32 m0, s38
	s_nop 0
	global_load_lds_dwordx4 v128, s[98:99]
	s_mov_b32 m0, s41
	s_nop 0
	global_load_lds_dwordx4 v132, s[2:3]
	s_mov_b32 m0, s42
	s_nop 0
	global_load_lds_dwordx4 v128, s[2:3]
	s_mov_b32 m0, s39
	s_nop 0
	s_add_u32 s100, s4, 0xfffc0080
	s_addc_u32 s101, s5, -1
	global_load_lds_dwordx4 v134, s[100:101]
	s_mov_b32 m0, s40
	s_nop 0
	global_load_lds_dwordx4 v130, s[100:101]
	s_waitcnt vmcnt(8)
	s_waitcnt lgkmcnt(0)
	s_barrier
	v_mfma_f32_16x16x32_bf16 v[60:63], v[140:143], v[214:217], v[60:63]
	v_mfma_f32_16x16x32_bf16 v[56:59], v[166:169], v[214:217], v[56:59]
	v_mfma_f32_16x16x32_bf16 v[48:51], v[140:143], v[222:225], v[48:51]
	v_mfma_f32_16x16x32_bf16 v[40:43], v[166:169], v[222:225], v[40:43]
	v_mfma_f32_16x16x32_bf16 v[32:35], v[140:143], v[230:233], v[32:35]
	v_mfma_f32_16x16x32_bf16 v[24:27], v[166:169], v[230:233], v[24:27]
	v_mfma_f32_16x16x32_bf16 v[16:19], v[140:143], v[238:241], v[16:19]
	v_mfma_f32_16x16x32_bf16 v[8:11], v[166:169], v[238:241], v[8:11]
	v_mfma_f32_16x16x32_bf16 v[60:63], v[162:165], v[218:221], v[60:63]
	v_mfma_f32_16x16x32_bf16 v[56:59], v[176:179], v[218:221], v[56:59]
	v_mfma_f32_16x16x32_bf16 v[48:51], v[162:165], v[226:229], v[48:51]
	v_mfma_f32_16x16x32_bf16 v[40:43], v[176:179], v[226:229], v[40:43]
	v_mfma_f32_16x16x32_bf16 v[32:35], v[162:165], v[234:237], v[32:35]
	v_mfma_f32_16x16x32_bf16 v[24:27], v[176:179], v[234:237], v[24:27]
	v_mfma_f32_16x16x32_bf16 v[16:19], v[162:165], v[242:245], v[16:19]
	v_mfma_f32_16x16x32_bf16 v[8:11], v[176:179], v[242:245], v[8:11]
	v_mfma_f32_16x16x32_bf16 v[52:55], v[180:183], v[214:217], v[52:55]
	v_mfma_f32_16x16x32_bf16 v[44:47], v[188:191], v[214:217], v[44:47]
	v_mfma_f32_16x16x32_bf16 v[36:39], v[180:183], v[222:225], v[36:39]
	v_mfma_f32_16x16x32_bf16 v[28:31], v[188:191], v[222:225], v[28:31]
	v_mfma_f32_16x16x32_bf16 v[20:23], v[180:183], v[230:233], v[20:23]
	v_mfma_f32_16x16x32_bf16 v[12:15], v[188:191], v[230:233], v[12:15]
	v_mfma_f32_16x16x32_bf16 v[4:7], v[180:183], v[238:241], v[4:7]
	v_mfma_f32_16x16x32_bf16 v[0:3], v[188:191], v[238:241], v[0:3]
	v_mfma_f32_16x16x32_bf16 v[52:55], v[184:187], v[218:221], v[52:55]
	v_mfma_f32_16x16x32_bf16 v[44:47], v[210:213], v[218:221], v[44:47]
	v_mfma_f32_16x16x32_bf16 v[36:39], v[184:187], v[226:229], v[36:39]
	v_mfma_f32_16x16x32_bf16 v[28:31], v[210:213], v[226:229], v[28:31]
	v_mfma_f32_16x16x32_bf16 v[20:23], v[184:187], v[234:237], v[20:23]
	v_mfma_f32_16x16x32_bf16 v[12:15], v[210:213], v[234:237], v[12:15]
	v_mfma_f32_16x16x32_bf16 v[4:7], v[184:187], v[242:245], v[4:7]
	v_mfma_f32_16x16x32_bf16 v[0:3], v[210:213], v[242:245], v[0:3]
	s_barrier
	s_add_i32 s52, s52, 2
	s_add_u32 s0, s0, 0x100
	s_addc_u32 s1, s1, 0
	s_add_u32 s50, s50, 0x100
	s_addc_u32 s51, s51, 0
	s_cmp_gt_u32 s52, 13
; #define PG8_STAGE(bufoff, gbase, voff) do { _Pragma("unroll") for (int _i = 0; _i < 2; ++_i) \
;         __builtin_amdgcn_global_load_lds((const unsigned*)((const char*)(gbase) + (voff)[_i]), (PG8_LAS unsigned*)(lds + (bufoff) + ldsw + _i * 8192), 16, 0, 0); } while (0)
; #define PG8_LDA(dst, b, h) do { _Pragma("unroll") for (int m = 0; m < 4; ++m) _Pragma("unroll") for (int k = 0; k < 2; ++k) dst[m][k] = *(const PG8_LAS bf16x8*)(lds + PG8_SA(b, h) + aoff + m * 2048 + k * 1024); } while (0)
; #define PG8_LDB(dst, b, h) do { _Pragma("unroll") for (int n = 0; n < 2; ++n) _Pragma("unroll") for (int k = 0; k < 2; ++k) dst[n][k] = *(const PG8_LAS bf16x8*)(lds + PG8_SB(b, h) + boff + n * 2048 + k * 1024); } while (0)
; #define PG8_MMA(ai, bj, At, Bt) do { __builtin_amdgcn_s_setprio(1); _Pragma("unroll") for (int m = 0; m < 4; ++m) _Pragma("unroll") for (int n = 0; n < 2; ++n) _Pragma("unroll") for (int k = 0; k < 2; ++k) \
;         acc[ai][bj][m][n] = __builtin_amdgcn_mfma_f32_16x16x32_bf16(Bt[n][k], At[m][k], acc[ai][bj][m][n], 0, 0, 0); __builtin_amdgcn_s_setprio(0); } while (0)
; #define PG8_WAIT_V(n) asm volatile("s_waitcnt vmcnt(" #n ")" ::: "memory")
; #define PG8_BAR __builtin_amdgcn_s_barrier()
; template <class Epi, class Sched, bool ALIGN_EPI = false, bool SP2 = false>
; __device__ __forceinline__ void gemm_phase(PG8_LAS unsigned char* lds, const Gemm g, const Sched& S, const Epi& E) {
;     ...
;         for (int t = 0; t < nt; t += 2) {
;             const bool last = (t == nt - 2);
;             const char* a1 = cA + (size_t)(t + 1) * kstep;
;             const char* a2 = last ? nA : cA + (size_t)(t + 2) * kstep; const char* b2 = last ? nB : cB + (size_t)(t + 2) * kstep;
;             const char* a3 = a2 + kstep; const char* b3 = b2 + kstep;
;             if (last && has_next) S.a_ready(nxt);
;             if constexpr (SP2) {
;             PG8_LDB(B0, 0, 0); PG8_LDB(B1, 0, 1); PG8_SCHED; PG8_LDA(At, 0, 0); PG8_STAGE(PG8_SA(1, 1), a1 + hstep, voffA);
;             PG8_WAIT_V(8); PG8_WAIT_L(0); PG8_BAR; PG8_MMA(0, 0, At, B0); PG8_MMA(0, 1, At, B1); PG8_BAR; PG8_SCHED;
;             PG8_LDA(At, 0, 1); PG8_STAGE(PG8_SB(0, 0), b2, voffB); PG8_STAGE(PG8_SB(0, 1), b2 + hstep, voffB); PG8_STAGE(PG8_SA(0, 0), a2, voffA);
;             PG8_WAIT_V(8); PG8_WAIT_L(0); PG8_BAR; PG8_MMA(1, 0, At, B0); PG8_MMA(1, 1, At, B1); PG8_BAR; PG8_SCHED;
.LBB0_792:
	s_waitcnt lgkmcnt(0)
	ds_read_b128 v[140:143], v254
	ds_read_b128 v[162:165], v254 offset:1024
	ds_read_b128 v[166:169], v254 offset:2048
	ds_read_b128 v[176:179], v254 offset:3072
	ds_read_b128 v[180:183], v254 offset:16384
	ds_read_b128 v[184:187], v254 offset:17408
	ds_read_b128 v[188:191], v254 offset:18432
	ds_read_b128 v[210:213], v254 offset:19456
	s_add_u32 s2, s0, 0xfffc0080
	s_addc_u32 s3, s1, -1
	s_cmp_eq_u32 s52, 12
	s_cselect_b32 s5, s17, s3
	s_cselect_b32 s4, s48, s2
	s_cselect_b32 s3, s15, s51
	s_cselect_b32 s2, s49, s50
	s_add_i32 m0, s6, 0xc000
	ds_read_b128 v[214:217], v173
	ds_read_b128 v[218:221], v173 offset:1024
	ds_read_b128 v[222:225], v173 offset:2048
	ds_read_b128 v[226:229], v173 offset:3072
	ds_read_b128 v[230:233], v173 offset:4096
	ds_read_b128 v[234:237], v173 offset:5120
	ds_read_b128 v[238:241], v173 offset:6144
	ds_read_b128 v[242:245], v173 offset:7168
	global_load_lds_dwordx4 v136, s[0:1]
	s_add_i32 m0, s6, 0xe000
	s_nop 0
	global_load_lds_dwordx4 v138, s[0:1]
	s_waitcnt vmcnt(8)
	s_waitcnt lgkmcnt(0)
	s_barrier
	v_mfma_f32_16x16x32_bf16 v[124:127], v[140:143], v[214:217], v[124:127]
	v_mfma_f32_16x16x32_bf16 v[120:123], v[166:169], v[214:217], v[120:123]
	v_mfma_f32_16x16x32_bf16 v[112:115], v[140:143], v[222:225], v[112:115]
	v_mfma_f32_16x16x32_bf16 v[104:107], v[166:169], v[222:225], v[104:107]
	v_mfma_f32_16x16x32_bf16 v[96:99], v[140:143], v[230:233], v[96:99]
	v_mfma_f32_16x16x32_bf16 v[88:91], v[166:169], v[230:233], v[88:91]
	v_mfma_f32_16x16x32_bf16 v[80:83], v[140:143], v[238:241], v[80:83]
	v_mfma_f32_16x16x32_bf16 v[72:75], v[166:169], v[238:241], v[72:75]
	v_mfma_f32_16x16x32_bf16 v[124:127], v[162:165], v[218:221], v[124:127]
	v_mfma_f32_16x16x32_bf16 v[120:123], v[176:179], v[218:221], v[120:123]
	v_mfma_f32_16x16x32_bf16 v[112:115], v[162:165], v[226:229], v[112:115]
	v_mfma_f32_16x16x32_bf16 v[104:107], v[176:179], v[226:229], v[104:107]
	v_mfma_f32_16x16x32_bf16 v[96:99], v[162:165], v[234:237], v[96:99]
	v_mfma_f32_16x16x32_bf16 v[88:91], v[176:179], v[234:237], v[88:91]
	v_mfma_f32_16x16x32_bf16 v[80:83], v[162:165], v[242:245], v[80:83]
	v_mfma_f32_16x16x32_bf16 v[72:75], v[176:179], v[242:245], v[72:75]
	v_mfma_f32_16x16x32_bf16 v[116:119], v[180:183], v[214:217], v[116:119]
	v_mfma_f32_16x16x32_bf16 v[108:111], v[188:191], v[214:217], v[108:111]
	v_mfma_f32_16x16x32_bf16 v[100:103], v[180:183], v[222:225], v[100:103]
	v_mfma_f32_16x16x32_bf16 v[92:95], v[188:191], v[222:225], v[92:95]
	v_mfma_f32_16x16x32_bf16 v[84:87], v[180:183], v[230:233], v[84:87]
	v_mfma_f32_16x16x32_bf16 v[76:79], v[188:191], v[230:233], v[76:79]
	v_mfma_f32_16x16x32_bf16 v[68:71], v[180:183], v[238:241], v[68:71]
	v_mfma_f32_16x16x32_bf16 v[64:67], v[188:191], v[238:241], v[64:67]
	v_mfma_f32_16x16x32_bf16 v[116:119], v[184:187], v[218:221], v[116:119]
	v_mfma_f32_16x16x32_bf16 v[108:111], v[210:213], v[218:221], v[108:111]
	v_mfma_f32_16x16x32_bf16 v[100:103], v[184:187], v[226:229], v[100:103]
	v_mfma_f32_16x16x32_bf16 v[92:95], v[210:213], v[226:229], v[92:95]
	v_mfma_f32_16x16x32_bf16 v[84:87], v[184:187], v[234:237], v[84:87]
	v_mfma_f32_16x16x32_bf16 v[76:79], v[210:213], v[234:237], v[76:79]
	v_mfma_f32_16x16x32_bf16 v[68:71], v[184:187], v[242:245], v[68:71]
	v_mfma_f32_16x16x32_bf16 v[64:67], v[210:213], v[242:245], v[64:67]
	s_barrier
	s_mov_b32 m0, s27
	s_add_u32 s54, s2, 0x40000
	s_addc_u32 s55, s3, 0
	ds_read_b128 v[214:217], v173 offset:16384
	ds_read_b128 v[218:221], v173 offset:17408
	ds_read_b128 v[222:225], v173 offset:18432
	ds_read_b128 v[226:229], v173 offset:19456
	ds_read_b128 v[230:233], v173 offset:20480
	ds_read_b128 v[234:237], v173 offset:21504
	ds_read_b128 v[238:241], v173 offset:22528
	ds_read_b128 v[242:245], v173 offset:23552
	global_load_lds_dwordx4 v132, s[2:3]
	s_mov_b32 m0, s28
	s_nop 0
	global_load_lds_dwordx4 v128, s[2:3]
	s_mov_b32 m0, s29
	s_nop 0
	global_load_lds_dwordx4 v132, s[54:55]
	s_mov_b32 m0, s30
	s_nop 0
	global_load_lds_dwordx4 v128, s[54:55]
	s_mov_b32 m0, s6
	s_nop 0
	global_load_lds_dwordx4 v134, s[4:5]
	s_mov_b32 m0, s31
	s_nop 0
	global_load_lds_dwordx4 v130, s[4:5]
	s_waitcnt vmcnt(8)
	s_waitcnt lgkmcnt(0)
	s_barrier
	v_mfma_f32_16x16x32_bf16 v[60:63], v[140:143], v[214:217], v[60:63]
	v_mfma_f32_16x16x32_bf16 v[56:59], v[166:169], v[214:217], v[56:59]
	v_mfma_f32_16x16x32_bf16 v[48:51], v[140:143], v[222:225], v[48:51]
	v_mfma_f32_16x16x32_bf16 v[40:43], v[166:169], v[222:225], v[40:43]
	v_mfma_f32_16x16x32_bf16 v[32:35], v[140:143], v[230:233], v[32:35]
	v_mfma_f32_16x16x32_bf16 v[24:27], v[166:169], v[230:233], v[24:27]
	v_mfma_f32_16x16x32_bf16 v[16:19], v[140:143], v[238:241], v[16:19]
	v_mfma_f32_16x16x32_bf16 v[8:11], v[166:169], v[238:241], v[8:11]
	v_mfma_f32_16x16x32_bf16 v[60:63], v[162:165], v[218:221], v[60:63]
	v_mfma_f32_16x16x32_bf16 v[56:59], v[176:179], v[218:221], v[56:59]
	v_mfma_f32_16x16x32_bf16 v[48:51], v[162:165], v[226:229], v[48:51]
	v_mfma_f32_16x16x32_bf16 v[40:43], v[176:179], v[226:229], v[40:43]
	v_mfma_f32_16x16x32_bf16 v[32:35], v[162:165], v[234:237], v[32:35]
	v_mfma_f32_16x16x32_bf16 v[24:27], v[176:179], v[234:237], v[24:27]
	v_mfma_f32_16x16x32_bf16 v[16:19], v[162:165], v[242:245], v[16:19]
	v_mfma_f32_16x16x32_bf16 v[8:11], v[176:179], v[242:245], v[8:11]
	v_mfma_f32_16x16x32_bf16 v[52:55], v[180:183], v[214:217], v[52:55]
	v_mfma_f32_16x16x32_bf16 v[44:47], v[188:191], v[214:217], v[44:47]
	v_mfma_f32_16x16x32_bf16 v[36:39], v[180:183], v[222:225], v[36:39]
	v_mfma_f32_16x16x32_bf16 v[28:31], v[188:191], v[222:225], v[28:31]
	v_mfma_f32_16x16x32_bf16 v[20:23], v[180:183], v[230:233], v[20:23]
	v_mfma_f32_16x16x32_bf16 v[12:15], v[188:191], v[230:233], v[12:15]
	v_mfma_f32_16x16x32_bf16 v[4:7], v[180:183], v[238:241], v[4:7]
	v_mfma_f32_16x16x32_bf16 v[0:3], v[188:191], v[238:241], v[0:3]
	v_mfma_f32_16x16x32_bf16 v[52:55], v[184:187], v[218:221], v[52:55]
	v_mfma_f32_16x16x32_bf16 v[44:47], v[210:213], v[218:221], v[44:47]
	v_mfma_f32_16x16x32_bf16 v[36:39], v[184:187], v[226:229], v[36:39]
	v_mfma_f32_16x16x32_bf16 v[28:31], v[210:213], v[226:229], v[28:31]
	v_mfma_f32_16x16x32_bf16 v[20:23], v[184:187], v[234:237], v[20:23]
	v_mfma_f32_16x16x32_bf16 v[12:15], v[210:213], v[234:237], v[12:15]
	v_mfma_f32_16x16x32_bf16 v[4:7], v[184:187], v[242:245], v[4:7]
	v_mfma_f32_16x16x32_bf16 v[0:3], v[210:213], v[242:245], v[0:3]
	s_barrier
; #define PG8_STAGE(bufoff, gbase, voff) do { _Pragma("unroll") for (int _i = 0; _i < 2; ++_i) \
;         __builtin_amdgcn_global_load_lds((const unsigned*)((const char*)(gbase) + (voff)[_i]), (PG8_LAS unsigned*)(lds + (bufoff) + ldsw + _i * 8192), 16, 0, 0); } while (0)
; #define PG8_BAR __builtin_amdgcn_s_barrier()
; template <class Epi, class Sched, bool ALIGN_EPI = false, bool SP2 = false>
; __device__ __forceinline__ void gemm_phase(PG8_LAS unsigned char* lds, const Gemm g, const Sched& S, const Epi& E) {
;     ...
;             PG8_LDB(B0, 1, 0); PG8_LDB(B1, 1, 1); PG8_SCHED; PG8_LDA(At, 1, 0); PG8_STAGE(PG8_SA(0, 1), a2 + hstep, voffA);
;             PG8_WAIT_V(8); PG8_WAIT_L(0); PG8_BAR; PG8_MMA(0, 0, At, B0); PG8_MMA(0, 1, At, B1); PG8_BAR; PG8_SCHED;
;             PG8_LDA(At, 1, 1); PG8_STAGE(PG8_SB(1, 0), b3, voffB); PG8_STAGE(PG8_SB(1, 1), b3 + hstep, voffB); PG8_STAGE(PG8_SA(1, 0), a3, voffA);
;             PG8_WAIT_V(8); PG8_WAIT_L(0); PG8_BAR; PG8_MMA(1, 0, At, B0); PG8_MMA(1, 1, At, B1); PG8_BAR; PG8_SCHED;
;             } else {
;             PG8_LDB(B0, 0, 0); PG8_SCHED; PG8_LDA(At, 0, 0); PG8_STAGE(PG8_SA(1, 1), a1 + hstep, voffA);
;             PG8_WAIT_L(8); PG8_BAR; PG8_WAIT_L(0); PG8_MMA(0, 0, At, B0); PG8_BAR; PG8_SCHED;
;             PG8_LDB(B1, 0, 1); PG8_STAGE(PG8_SB(0, 0), b2, voffB);
;             PG8_BAR; PG8_WAIT_L(0); PG8_MMA(0, 1, At, B1); PG8_BAR;
;             PG8_LDA(At, 0, 1); PG8_STAGE(PG8_SA(0, 0), a2, voffA);
;             PG8_BAR; PG8_WAIT_L(0); PG8_MMA(1, 0, At, B0); PG8_BAR; PG8_SCHED;
;             PG8_STAGE(PG8_SB(0, 1), b2 + hstep, voffB);
;             PG8_WAIT_V(6); PG8_BAR; PG8_MMA(1, 1, At, B1); PG8_BAR;
;             PG8_LDB(B0, 1, 0); PG8_SCHED; PG8_LDA(At, 1, 0); PG8_STAGE(PG8_SA(0, 1), a2 + hstep, voffA);
;             PG8_WAIT_L(8); PG8_BAR; PG8_WAIT_L(0); PG8_MMA(0, 0, At, B0); PG8_BAR; PG8_SCHED;
;             PG8_LDB(B1, 1, 1); PG8_STAGE(PG8_SB(1, 0), b3, voffB);
;             PG8_BAR; PG8_WAIT_L(0); PG8_MMA(0, 1, At, B1); PG8_BAR;
;             PG8_LDA(At, 1, 1); PG8_STAGE(PG8_SA(1, 0), a3, voffA);
;             PG8_BAR; PG8_WAIT_L(0); PG8_MMA(1, 0, At, B0); PG8_BAR; PG8_SCHED;
;             PG8_STAGE(PG8_SB(1, 1), b3 + hstep, voffB);
;             PG8_WAIT_V(6); PG8_BAR; PG8_MMA(1, 1, At, B1); PG8_BAR;
;             }
;         }
;         if constexpr (ALIGN_EPI) { if (wr == 0) PG8_BAR; }
	ds_read_b128 v[140:143], v254 offset:32768
	ds_read_b128 v[162:165], v254 offset:33792
	ds_read_b128 v[166:169], v254 offset:34816
	ds_read_b128 v[176:179], v254 offset:35840
	ds_read_b128 v[180:183], v254 offset:49152
	ds_read_b128 v[184:187], v254 offset:50176
	ds_read_b128 v[188:191], v254 offset:51200
	ds_read_b128 v[210:213], v254 offset:52224
	s_add_u32 s4, s4, 0x40000
	s_addc_u32 s5, s5, 0
	s_mov_b32 m0, s33
	ds_read_b128 v[214:217], v173 offset:32768
	ds_read_b128 v[218:221], v173 offset:33792
	ds_read_b128 v[222:225], v173 offset:34816
	ds_read_b128 v[226:229], v173 offset:35840
	ds_read_b128 v[230:233], v173 offset:36864
	ds_read_b128 v[234:237], v173 offset:37888
	ds_read_b128 v[238:241], v173 offset:38912
	ds_read_b128 v[242:245], v173 offset:39936
	global_load_lds_dwordx4 v134, s[4:5]
	s_mov_b32 m0, s34
	s_nop 0
	global_load_lds_dwordx4 v130, s[4:5]
	s_waitcnt vmcnt(8)
	s_waitcnt lgkmcnt(0)
	s_barrier
	v_mfma_f32_16x16x32_bf16 v[124:127], v[140:143], v[214:217], v[124:127]
	v_mfma_f32_16x16x32_bf16 v[120:123], v[166:169], v[214:217], v[120:123]
	v_mfma_f32_16x16x32_bf16 v[112:115], v[140:143], v[222:225], v[112:115]
	v_mfma_f32_16x16x32_bf16 v[104:107], v[166:169], v[222:225], v[104:107]
	v_mfma_f32_16x16x32_bf16 v[96:99], v[140:143], v[230:233], v[96:99]
	v_mfma_f32_16x16x32_bf16 v[88:91], v[166:169], v[230:233], v[88:91]
	v_mfma_f32_16x16x32_bf16 v[80:83], v[140:143], v[238:241], v[80:83]
	v_mfma_f32_16x16x32_bf16 v[72:75], v[166:169], v[238:241], v[72:75]
	v_mfma_f32_16x16x32_bf16 v[124:127], v[162:165], v[218:221], v[124:127]
	v_mfma_f32_16x16x32_bf16 v[120:123], v[176:179], v[218:221], v[120:123]
	v_mfma_f32_16x16x32_bf16 v[112:115], v[162:165], v[226:229], v[112:115]
	v_mfma_f32_16x16x32_bf16 v[104:107], v[176:179], v[226:229], v[104:107]
	v_mfma_f32_16x16x32_bf16 v[96:99], v[162:165], v[234:237], v[96:99]
	v_mfma_f32_16x16x32_bf16 v[88:91], v[176:179], v[234:237], v[88:91]
	v_mfma_f32_16x16x32_bf16 v[80:83], v[162:165], v[242:245], v[80:83]
	v_mfma_f32_16x16x32_bf16 v[72:75], v[176:179], v[242:245], v[72:75]
	v_mfma_f32_16x16x32_bf16 v[116:119], v[180:183], v[214:217], v[116:119]
	v_mfma_f32_16x16x32_bf16 v[108:111], v[188:191], v[214:217], v[108:111]
	v_mfma_f32_16x16x32_bf16 v[100:103], v[180:183], v[222:225], v[100:103]
	v_mfma_f32_16x16x32_bf16 v[92:95], v[188:191], v[222:225], v[92:95]
	v_mfma_f32_16x16x32_bf16 v[84:87], v[180:183], v[230:233], v[84:87]
	v_mfma_f32_16x16x32_bf16 v[76:79], v[188:191], v[230:233], v[76:79]
	v_mfma_f32_16x16x32_bf16 v[68:71], v[180:183], v[238:241], v[68:71]
	v_mfma_f32_16x16x32_bf16 v[64:67], v[188:191], v[238:241], v[64:67]
	v_mfma_f32_16x16x32_bf16 v[116:119], v[184:187], v[218:221], v[116:119]
	v_mfma_f32_16x16x32_bf16 v[108:111], v[210:213], v[218:221], v[108:111]
	v_mfma_f32_16x16x32_bf16 v[100:103], v[184:187], v[226:229], v[100:103]
	v_mfma_f32_16x16x32_bf16 v[92:95], v[210:213], v[226:229], v[92:95]
	v_mfma_f32_16x16x32_bf16 v[84:87], v[184:187], v[234:237], v[84:87]
	v_mfma_f32_16x16x32_bf16 v[76:79], v[210:213], v[234:237], v[76:79]
	v_mfma_f32_16x16x32_bf16 v[68:71], v[184:187], v[242:245], v[68:71]
	v_mfma_f32_16x16x32_bf16 v[64:67], v[210:213], v[242:245], v[64:67]
	s_barrier
	s_mov_b32 m0, s37
	s_add_u32 s2, s2, 0x40080
	s_addc_u32 s3, s3, 0
	ds_read_b128 v[214:217], v173 offset:49152
	ds_read_b128 v[218:221], v173 offset:50176
	ds_read_b128 v[222:225], v173 offset:51200
	ds_read_b128 v[226:229], v173 offset:52224
	ds_read_b128 v[230:233], v173 offset:53248
	ds_read_b128 v[234:237], v173 offset:54272
	ds_read_b128 v[238:241], v173 offset:55296
	ds_read_b128 v[242:245], v173 offset:56320
	s_add_u32 s98, s2, 0xfffc0000
	s_addc_u32 s99, s3, -1
	global_load_lds_dwordx4 v132, s[98:99]
	s_mov_b32 m0, s38
	s_nop 0
	global_load_lds_dwordx4 v128, s[98:99]
	s_mov_b32 m0, s41
	s_nop 0
	global_load_lds_dwordx4 v132, s[2:3]
	s_mov_b32 m0, s42
	s_nop 0
	global_load_lds_dwordx4 v128, s[2:3]
	s_mov_b32 m0, s39
	s_nop 0
	s_add_u32 s100, s4, 0xfffc0080
	s_addc_u32 s101, s5, -1
	global_load_lds_dwordx4 v134, s[100:101]
	s_mov_b32 m0, s40
	s_nop 0
	global_load_lds_dwordx4 v130, s[100:101]
	s_waitcnt vmcnt(8)
	s_waitcnt lgkmcnt(0)
	s_barrier
	v_mfma_f32_16x16x32_bf16 v[60:63], v[140:143], v[214:217], v[60:63]
	v_mfma_f32_16x16x32_bf16 v[56:59], v[166:169], v[214:217], v[56:59]
	v_mfma_f32_16x16x32_bf16 v[48:51], v[140:143], v[222:225], v[48:51]
	v_mfma_f32_16x16x32_bf16 v[40:43], v[166:169], v[222:225], v[40:43]
	v_mfma_f32_16x16x32_bf16 v[32:35], v[140:143], v[230:233], v[32:35]
	v_mfma_f32_16x16x32_bf16 v[24:27], v[166:169], v[230:233], v[24:27]
	v_mfma_f32_16x16x32_bf16 v[16:19], v[140:143], v[238:241], v[16:19]
	v_mfma_f32_16x16x32_bf16 v[8:11], v[166:169], v[238:241], v[8:11]
	v_mfma_f32_16x16x32_bf16 v[60:63], v[162:165], v[218:221], v[60:63]
	v_mfma_f32_16x16x32_bf16 v[56:59], v[176:179], v[218:221], v[56:59]
	v_mfma_f32_16x16x32_bf16 v[48:51], v[162:165], v[226:229], v[48:51]
	v_mfma_f32_16x16x32_bf16 v[40:43], v[176:179], v[226:229], v[40:43]
	v_mfma_f32_16x16x32_bf16 v[32:35], v[162:165], v[234:237], v[32:35]
	v_mfma_f32_16x16x32_bf16 v[24:27], v[176:179], v[234:237], v[24:27]
	v_mfma_f32_16x16x32_bf16 v[16:19], v[162:165], v[242:245], v[16:19]
	v_mfma_f32_16x16x32_bf16 v[8:11], v[176:179], v[242:245], v[8:11]
	v_mfma_f32_16x16x32_bf16 v[52:55], v[180:183], v[214:217], v[52:55]
	v_mfma_f32_16x16x32_bf16 v[44:47], v[188:191], v[214:217], v[44:47]
	v_mfma_f32_16x16x32_bf16 v[36:39], v[180:183], v[222:225], v[36:39]
	v_mfma_f32_16x16x32_bf16 v[28:31], v[188:191], v[222:225], v[28:31]
	v_mfma_f32_16x16x32_bf16 v[20:23], v[180:183], v[230:233], v[20:23]
	v_mfma_f32_16x16x32_bf16 v[12:15], v[188:191], v[230:233], v[12:15]
	v_mfma_f32_16x16x32_bf16 v[4:7], v[180:183], v[238:241], v[4:7]
	v_mfma_f32_16x16x32_bf16 v[0:3], v[188:191], v[238:241], v[0:3]
	v_mfma_f32_16x16x32_bf16 v[52:55], v[184:187], v[218:221], v[52:55]
	v_mfma_f32_16x16x32_bf16 v[44:47], v[210:213], v[218:221], v[44:47]
	v_mfma_f32_16x16x32_bf16 v[36:39], v[184:187], v[226:229], v[36:39]
	v_mfma_f32_16x16x32_bf16 v[28:31], v[210:213], v[226:229], v[28:31]
	v_mfma_f32_16x16x32_bf16 v[20:23], v[184:187], v[234:237], v[20:23]
	v_mfma_f32_16x16x32_bf16 v[12:15], v[210:213], v[234:237], v[12:15]
	v_mfma_f32_16x16x32_bf16 v[4:7], v[184:187], v[242:245], v[4:7]
	v_mfma_f32_16x16x32_bf16 v[0:3], v[210:213], v[242:245], v[0:3]
	s_barrier
	s_add_i32 s52, s52, 2
	s_add_u32 s0, s0, 0x100
	s_addc_u32 s1, s1, 0
	s_add_u32 s50, s50, 0x100
	s_addc_u32 s51, s51, 0
	s_cmp_gt_u32 s52, 13
	s_cbranch_scc0 .LBB0_792
	s_and_b64 vcc, exec, s[12:13]
	s_cbranch_vccz .LBB0_795
	s_barrier

; #define PG8_STAGE(bufoff, gbase, voff) do { _Pragma("unroll") for (int _i = 0; _i < 2; ++_i) \
;         __builtin_amdgcn_global_load_lds((const unsigned*)((const char*)(gbase) + (voff)[_i]), (PG8_LAS unsigned*)(lds + (bufoff) + ldsw + _i * 8192), 16, 0, 0); } while (0)
; #define PG8_LDA(dst, b, h) do { _Pragma("unroll") for (int m = 0; m < 4; ++m) _Pragma("unroll") for (int k = 0; k < 2; ++k) dst[m][k] = *(const PG8_LAS bf16x8*)(lds + PG8_SA(b, h) + aoff + m * 2048 + k * 1024); } while (0)
; #define PG8_LDB(dst, b, h) do { _Pragma("unroll") for (int n = 0; n < 2; ++n) _Pragma("unroll") for (int k = 0; k < 2; ++k) dst[n][k] = *(const PG8_LAS bf16x8*)(lds + PG8_SB(b, h) + boff + n * 2048 + k * 1024); } while (0)
; #define PG8_MMA(ai, bj, At, Bt) do { __builtin_amdgcn_s_setprio(1); _Pragma("unroll") for (int m = 0; m < 4; ++m) _Pragma("unroll") for (int n = 0; n < 2; ++n) _Pragma("unroll") for (int k = 0; k < 2; ++k) \
;         acc[ai][bj][m][n] = __builtin_amdgcn_mfma_f32_16x16x32_bf16(Bt[n][k], At[m][k], acc[ai][bj][m][n], 0, 0, 0); __builtin_amdgcn_s_setprio(0); } while (0)
; #define PG8_WAIT_V(n) asm volatile("s_waitcnt vmcnt(" #n ")" ::: "memory")
; #define PG8_BAR __builtin_amdgcn_s_barrier()
; template <class Epi, class Sched, bool ALIGN_EPI = false, bool SP2 = false>
; __device__ __forceinline__ void gemm_phase(PG8_LAS unsigned char* lds, const Gemm g, const Sched& S, const Epi& E) {
;     ...
;         for (int t = 0; t < nt; t += 2) {
;             const bool last = (t == nt - 2);
;             const char* a1 = cA + (size_t)(t + 1) * kstep;
;             const char* a2 = last ? nA : cA + (size_t)(t + 2) * kstep; const char* b2 = last ? nB : cB + (size_t)(t + 2) * kstep;
;             const char* a3 = a2 + kstep; const char* b3 = b2 + kstep;
;             if (last && has_next) S.a_ready(nxt);
;             if constexpr (SP2) {
;             PG8_LDB(B0, 0, 0); PG8_LDB(B1, 0, 1); PG8_SCHED; PG8_LDA(At, 0, 0); PG8_STAGE(PG8_SA(1, 1), a1 + hstep, voffA);
;             PG8_WAIT_V(8); PG8_WAIT_L(0); PG8_BAR; PG8_MMA(0, 0, At, B0); PG8_MMA(0, 1, At, B1); PG8_BAR; PG8_SCHED;
;             PG8_LDA(At, 0, 1); PG8_STAGE(PG8_SB(0, 0), b2, voffB); PG8_STAGE(PG8_SB(0, 1), b2 + hstep, voffB); PG8_STAGE(PG8_SA(0, 0), a2, voffA);
;             PG8_WAIT_V(8); PG8_WAIT_L(0); PG8_BAR; PG8_MMA(1, 0, At, B0); PG8_MMA(1, 1, At, B1); PG8_BAR; PG8_SCHED;
.Lsgo_peel:
	ds_read_b128 v[140:143], v254
	ds_read_b128 v[166:169], v254 offset:1024
	ds_read_b128 v[170:173], v254 offset:2048
	ds_read_b128 v[174:177], v254 offset:3072
	ds_read_b128 v[178:181], v254 offset:16384
	ds_read_b128 v[182:185], v254 offset:17408
	ds_read_b128 v[186:189], v254 offset:18432
	ds_read_b128 v[210:213], v254 offset:19456
	s_add_u32 s2, s0, 0xfffc0080
	s_addc_u32 s3, s1, -1
	s_cmp_eq_u32 s55, 12
	s_cselect_b32 s5, s23, s3
	s_cselect_b32 s4, s51, s2
	s_cselect_b32 s3, s21, s54
	s_cselect_b32 s2, s52, s53
	s_add_i32 m0, s31, 0xc000
	ds_read_b128 v[214:217], v163
	ds_read_b128 v[218:221], v163 offset:1024
	ds_read_b128 v[222:225], v163 offset:2048
	ds_read_b128 v[226:229], v163 offset:3072
	ds_read_b128 v[230:233], v163 offset:4096
	ds_read_b128 v[234:237], v163 offset:5120
	ds_read_b128 v[238:241], v163 offset:6144
	ds_read_b128 v[242:245], v163 offset:7168
	global_load_lds_dwordx4 v136, s[0:1]
	s_add_i32 m0, s31, 0xe000
	s_nop 0
	global_load_lds_dwordx4 v138, s[0:1]
	s_waitcnt vmcnt(8)
	s_waitcnt lgkmcnt(0)
	s_barrier
	v_mfma_f32_16x16x32_bf16 v[124:127], v[140:143], v[214:217], 0
	v_mfma_f32_16x16x32_bf16 v[120:123], v[170:173], v[214:217], 0
	v_mfma_f32_16x16x32_bf16 v[108:111], v[140:143], v[222:225], 0
	v_mfma_f32_16x16x32_bf16 v[104:107], v[170:173], v[222:225], 0
	v_mfma_f32_16x16x32_bf16 v[92:95], v[140:143], v[230:233], 0
	v_mfma_f32_16x16x32_bf16 v[88:91], v[170:173], v[230:233], 0
	v_mfma_f32_16x16x32_bf16 v[76:79], v[140:143], v[238:241], 0
	v_mfma_f32_16x16x32_bf16 v[72:75], v[170:173], v[238:241], 0
	v_mfma_f32_16x16x32_bf16 v[124:127], v[166:169], v[218:221], v[124:127]
	v_mfma_f32_16x16x32_bf16 v[120:123], v[174:177], v[218:221], v[120:123]
	v_mfma_f32_16x16x32_bf16 v[108:111], v[166:169], v[226:229], v[108:111]
	v_mfma_f32_16x16x32_bf16 v[104:107], v[174:177], v[226:229], v[104:107]
	v_mfma_f32_16x16x32_bf16 v[92:95], v[166:169], v[234:237], v[92:95]
	v_mfma_f32_16x16x32_bf16 v[88:91], v[174:177], v[234:237], v[88:91]
	v_mfma_f32_16x16x32_bf16 v[76:79], v[166:169], v[242:245], v[76:79]
	v_mfma_f32_16x16x32_bf16 v[72:75], v[174:177], v[242:245], v[72:75]
	v_mfma_f32_16x16x32_bf16 v[116:119], v[178:181], v[214:217], 0
	v_mfma_f32_16x16x32_bf16 v[112:115], v[186:189], v[214:217], 0
	v_mfma_f32_16x16x32_bf16 v[100:103], v[178:181], v[222:225], 0
	v_mfma_f32_16x16x32_bf16 v[96:99], v[186:189], v[222:225], 0
	v_mfma_f32_16x16x32_bf16 v[84:87], v[178:181], v[230:233], 0
	v_mfma_f32_16x16x32_bf16 v[80:83], v[186:189], v[230:233], 0
	v_mfma_f32_16x16x32_bf16 v[68:71], v[178:181], v[238:241], 0
	v_mfma_f32_16x16x32_bf16 v[64:67], v[186:189], v[238:241], 0
	v_mfma_f32_16x16x32_bf16 v[116:119], v[182:185], v[218:221], v[116:119]
	v_mfma_f32_16x16x32_bf16 v[112:115], v[210:213], v[218:221], v[112:115]
	v_mfma_f32_16x16x32_bf16 v[100:103], v[182:185], v[226:229], v[100:103]
	v_mfma_f32_16x16x32_bf16 v[96:99], v[210:213], v[226:229], v[96:99]
	v_mfma_f32_16x16x32_bf16 v[84:87], v[182:185], v[234:237], v[84:87]
	v_mfma_f32_16x16x32_bf16 v[80:83], v[210:213], v[234:237], v[80:83]
	v_mfma_f32_16x16x32_bf16 v[68:71], v[182:185], v[242:245], v[68:71]
	v_mfma_f32_16x16x32_bf16 v[64:67], v[210:213], v[242:245], v[64:67]
	s_barrier
	s_mov_b32 m0, s33
	s_add_u32 s56, s2, 0x40000
	s_addc_u32 s57, s3, 0
	ds_read_b128 v[214:217], v163 offset:16384
	ds_read_b128 v[218:221], v163 offset:17408
	ds_read_b128 v[222:225], v163 offset:18432
	ds_read_b128 v[226:229], v163 offset:19456
	ds_read_b128 v[230:233], v163 offset:20480
	ds_read_b128 v[234:237], v163 offset:21504
	ds_read_b128 v[238:241], v163 offset:22528
	ds_read_b128 v[242:245], v163 offset:23552
	global_load_lds_dwordx4 v132, s[2:3]
	s_mov_b32 m0, s34
	s_nop 0
	global_load_lds_dwordx4 v128, s[2:3]
	s_mov_b32 m0, s35
	s_nop 0
	global_load_lds_dwordx4 v132, s[56:57]
	s_mov_b32 m0, s36
	s_nop 0
	global_load_lds_dwordx4 v128, s[56:57]
	s_mov_b32 m0, s31
	s_nop 0
	global_load_lds_dwordx4 v134, s[4:5]
	s_mov_b32 m0, s37
	s_nop 0
	global_load_lds_dwordx4 v130, s[4:5]
	s_waitcnt vmcnt(8)
	s_waitcnt lgkmcnt(0)
	s_barrier
	v_mfma_f32_16x16x32_bf16 v[60:63], v[140:143], v[214:217], 0
	v_mfma_f32_16x16x32_bf16 v[56:59], v[170:173], v[214:217], 0
	v_mfma_f32_16x16x32_bf16 v[44:47], v[140:143], v[222:225], 0
	v_mfma_f32_16x16x32_bf16 v[40:43], v[170:173], v[222:225], 0
	v_mfma_f32_16x16x32_bf16 v[28:31], v[140:143], v[230:233], 0
	v_mfma_f32_16x16x32_bf16 v[24:27], v[170:173], v[230:233], 0
	v_mfma_f32_16x16x32_bf16 v[12:15], v[140:143], v[238:241], 0
	v_mfma_f32_16x16x32_bf16 v[8:11], v[170:173], v[238:241], 0
	v_mfma_f32_16x16x32_bf16 v[60:63], v[166:169], v[218:221], v[60:63]
	v_mfma_f32_16x16x32_bf16 v[56:59], v[174:177], v[218:221], v[56:59]
	v_mfma_f32_16x16x32_bf16 v[44:47], v[166:169], v[226:229], v[44:47]
	v_mfma_f32_16x16x32_bf16 v[40:43], v[174:177], v[226:229], v[40:43]
	v_mfma_f32_16x16x32_bf16 v[28:31], v[166:169], v[234:237], v[28:31]
	v_mfma_f32_16x16x32_bf16 v[24:27], v[174:177], v[234:237], v[24:27]
	v_mfma_f32_16x16x32_bf16 v[12:15], v[166:169], v[242:245], v[12:15]
	v_mfma_f32_16x16x32_bf16 v[8:11], v[174:177], v[242:245], v[8:11]
	v_mfma_f32_16x16x32_bf16 v[52:55], v[178:181], v[214:217], 0
	v_mfma_f32_16x16x32_bf16 v[48:51], v[186:189], v[214:217], 0
	v_mfma_f32_16x16x32_bf16 v[36:39], v[178:181], v[222:225], 0
	v_mfma_f32_16x16x32_bf16 v[32:35], v[186:189], v[222:225], 0
	v_mfma_f32_16x16x32_bf16 v[20:23], v[178:181], v[230:233], 0
	v_mfma_f32_16x16x32_bf16 v[16:19], v[186:189], v[230:233], 0
	v_mfma_f32_16x16x32_bf16 v[4:7], v[178:181], v[238:241], 0
	v_mfma_f32_16x16x32_bf16 v[0:3], v[186:189], v[238:241], 0
	v_mfma_f32_16x16x32_bf16 v[52:55], v[182:185], v[218:221], v[52:55]
	v_mfma_f32_16x16x32_bf16 v[48:51], v[210:213], v[218:221], v[48:51]
	v_mfma_f32_16x16x32_bf16 v[36:39], v[182:185], v[226:229], v[36:39]
	v_mfma_f32_16x16x32_bf16 v[32:35], v[210:213], v[226:229], v[32:35]
	v_mfma_f32_16x16x32_bf16 v[20:23], v[182:185], v[234:237], v[20:23]
	v_mfma_f32_16x16x32_bf16 v[16:19], v[210:213], v[234:237], v[16:19]
	v_mfma_f32_16x16x32_bf16 v[4:7], v[182:185], v[242:245], v[4:7]
	v_mfma_f32_16x16x32_bf16 v[0:3], v[210:213], v[242:245], v[0:3]
	s_barrier
; #define PG8_STAGE(bufoff, gbase, voff) do { _Pragma("unroll") for (int _i = 0; _i < 2; ++_i) \
;         __builtin_amdgcn_global_load_lds((const unsigned*)((const char*)(gbase) + (voff)[_i]), (PG8_LAS unsigned*)(lds + (bufoff) + ldsw + _i * 8192), 16, 0, 0); } while (0)
; #define PG8_LDA(dst, b, h) do { _Pragma("unroll") for (int m = 0; m < 4; ++m) _Pragma("unroll") for (int k = 0; k < 2; ++k) dst[m][k] = *(const PG8_LAS bf16x8*)(lds + PG8_SA(b, h) + aoff + m * 2048 + k * 1024); } while (0)
; #define PG8_LDB(dst, b, h) do { _Pragma("unroll") for (int n = 0; n < 2; ++n) _Pragma("unroll") for (int k = 0; k < 2; ++k) dst[n][k] = *(const PG8_LAS bf16x8*)(lds + PG8_SB(b, h) + boff + n * 2048 + k * 1024); } while (0)
; #define PG8_MMA(ai, bj, At, Bt) do { __builtin_amdgcn_s_setprio(1); _Pragma("unroll") for (int m = 0; m < 4; ++m) _Pragma("unroll") for (int n = 0; n < 2; ++n) _Pragma("unroll") for (int k = 0; k < 2; ++k) \
;         acc[ai][bj][m][n] = __builtin_amdgcn_mfma_f32_16x16x32_bf16(Bt[n][k], At[m][k], acc[ai][bj][m][n], 0, 0, 0); __builtin_amdgcn_s_setprio(0); } while (0)
; #define PG8_WAIT_V(n) asm volatile("s_waitcnt vmcnt(" #n ")" ::: "memory")
; #define PG8_WAIT_L(n) asm volatile("s_waitcnt lgkmcnt(" #n ")" ::: "memory")
; #define PG8_BAR __builtin_amdgcn_s_barrier()
; #define PG8_SCHED __builtin_amdgcn_sched_barrier(0)
; template <class Epi, class Sched, bool ALIGN_EPI = false, bool SP2 = false>
; __device__ __forceinline__ void gemm_phase(PG8_LAS unsigned char* lds, const Gemm g, const Sched& S, const Epi& E) {
;     ...
;             PG8_LDB(B0, 1, 0); PG8_LDB(B1, 1, 1); PG8_SCHED; PG8_LDA(At, 1, 0); PG8_STAGE(PG8_SA(0, 1), a2 + hstep, voffA);
;             PG8_WAIT_V(8); PG8_WAIT_L(0); PG8_BAR; PG8_MMA(0, 0, At, B0); PG8_MMA(0, 1, At, B1); PG8_BAR; PG8_SCHED;
;             PG8_LDA(At, 1, 1); PG8_STAGE(PG8_SB(1, 0), b3, voffB); PG8_STAGE(PG8_SB(1, 1), b3 + hstep, voffB); PG8_STAGE(PG8_SA(1, 0), a3, voffA);
;             PG8_WAIT_V(8); PG8_WAIT_L(0); PG8_BAR; PG8_MMA(1, 0, At, B0); PG8_MMA(1, 1, At, B1); PG8_BAR; PG8_SCHED;
	ds_read_b128 v[140:143], v254 offset:32768
	ds_read_b128 v[166:169], v254 offset:33792
	ds_read_b128 v[170:173], v254 offset:34816
	ds_read_b128 v[174:177], v254 offset:35840
	ds_read_b128 v[178:181], v254 offset:49152
	ds_read_b128 v[182:185], v254 offset:50176
	ds_read_b128 v[186:189], v254 offset:51200
	ds_read_b128 v[210:213], v254 offset:52224
	s_add_u32 s4, s4, 0x40000
	s_addc_u32 s5, s5, 0
	s_mov_b32 m0, s38
	ds_read_b128 v[214:217], v163 offset:32768
	ds_read_b128 v[218:221], v163 offset:33792
	ds_read_b128 v[222:225], v163 offset:34816
	ds_read_b128 v[226:229], v163 offset:35840
	ds_read_b128 v[230:233], v163 offset:36864
	ds_read_b128 v[234:237], v163 offset:37888
	ds_read_b128 v[238:241], v163 offset:38912
	ds_read_b128 v[242:245], v163 offset:39936
	global_load_lds_dwordx4 v134, s[4:5]
	s_mov_b32 m0, s39
	s_nop 0
	global_load_lds_dwordx4 v130, s[4:5]
	s_waitcnt vmcnt(8)
	s_waitcnt lgkmcnt(0)
	s_barrier
	v_mfma_f32_16x16x32_bf16 v[124:127], v[140:143], v[214:217], v[124:127]
	v_mfma_f32_16x16x32_bf16 v[120:123], v[170:173], v[214:217], v[120:123]
	v_mfma_f32_16x16x32_bf16 v[108:111], v[140:143], v[222:225], v[108:111]
	v_mfma_f32_16x16x32_bf16 v[104:107], v[170:173], v[222:225], v[104:107]
	v_mfma_f32_16x16x32_bf16 v[92:95], v[140:143], v[230:233], v[92:95]
	v_mfma_f32_16x16x32_bf16 v[88:91], v[170:173], v[230:233], v[88:91]
	v_mfma_f32_16x16x32_bf16 v[76:79], v[140:143], v[238:241], v[76:79]
	v_mfma_f32_16x16x32_bf16 v[72:75], v[170:173], v[238:241], v[72:75]
	v_mfma_f32_16x16x32_bf16 v[124:127], v[166:169], v[218:221], v[124:127]
	v_mfma_f32_16x16x32_bf16 v[120:123], v[174:177], v[218:221], v[120:123]
	v_mfma_f32_16x16x32_bf16 v[108:111], v[166:169], v[226:229], v[108:111]
	v_mfma_f32_16x16x32_bf16 v[104:107], v[174:177], v[226:229], v[104:107]
	v_mfma_f32_16x16x32_bf16 v[92:95], v[166:169], v[234:237], v[92:95]
	v_mfma_f32_16x16x32_bf16 v[88:91], v[174:177], v[234:237], v[88:91]
	v_mfma_f32_16x16x32_bf16 v[76:79], v[166:169], v[242:245], v[76:79]
	v_mfma_f32_16x16x32_bf16 v[72:75], v[174:177], v[242:245], v[72:75]
	v_mfma_f32_16x16x32_bf16 v[116:119], v[178:181], v[214:217], v[116:119]
	v_mfma_f32_16x16x32_bf16 v[112:115], v[186:189], v[214:217], v[112:115]
	v_mfma_f32_16x16x32_bf16 v[100:103], v[178:181], v[222:225], v[100:103]
	v_mfma_f32_16x16x32_bf16 v[96:99], v[186:189], v[222:225], v[96:99]
	v_mfma_f32_16x16x32_bf16 v[84:87], v[178:181], v[230:233], v[84:87]
	v_mfma_f32_16x16x32_bf16 v[80:83], v[186:189], v[230:233], v[80:83]
	v_mfma_f32_16x16x32_bf16 v[68:71], v[178:181], v[238:241], v[68:71]
	v_mfma_f32_16x16x32_bf16 v[64:67], v[186:189], v[238:241], v[64:67]
	v_mfma_f32_16x16x32_bf16 v[116:119], v[182:185], v[218:221], v[116:119]
	v_mfma_f32_16x16x32_bf16 v[112:115], v[210:213], v[218:221], v[112:115]
	v_mfma_f32_16x16x32_bf16 v[100:103], v[182:185], v[226:229], v[100:103]
	v_mfma_f32_16x16x32_bf16 v[96:99], v[210:213], v[226:229], v[96:99]
	v_mfma_f32_16x16x32_bf16 v[84:87], v[182:185], v[234:237], v[84:87]
	v_mfma_f32_16x16x32_bf16 v[80:83], v[210:213], v[234:237], v[80:83]
	v_mfma_f32_16x16x32_bf16 v[68:71], v[182:185], v[242:245], v[68:71]
	v_mfma_f32_16x16x32_bf16 v[64:67], v[210:213], v[242:245], v[64:67]
	s_barrier
	s_mov_b32 m0, s43
	s_add_u32 s2, s2, 0x40080
	s_addc_u32 s3, s3, 0
	ds_read_b128 v[214:217], v163 offset:49152
	ds_read_b128 v[218:221], v163 offset:50176
	ds_read_b128 v[222:225], v163 offset:51200
	ds_read_b128 v[226:229], v163 offset:52224
	ds_read_b128 v[230:233], v163 offset:53248
	ds_read_b128 v[234:237], v163 offset:54272
	ds_read_b128 v[238:241], v163 offset:55296
	ds_read_b128 v[242:245], v163 offset:56320
	s_add_u32 s98, s2, 0xfffc0000
	s_addc_u32 s99, s3, -1
	global_load_lds_dwordx4 v132, s[98:99]
	s_mov_b32 m0, s44
	s_nop 0
	global_load_lds_dwordx4 v128, s[98:99]
	s_mov_b32 m0, s48
	s_nop 0
	global_load_lds_dwordx4 v132, s[2:3]
	s_mov_b32 m0, s49
	s_nop 0
	global_load_lds_dwordx4 v128, s[2:3]
	s_mov_b32 m0, s45
	s_nop 0
	s_add_u32 s100, s4, 0xfffc0080
	s_addc_u32 s101, s5, -1
	global_load_lds_dwordx4 v134, s[100:101]
	s_mov_b32 m0, s47
	s_nop 0
	global_load_lds_dwordx4 v130, s[100:101]
	s_waitcnt vmcnt(8)
	s_waitcnt lgkmcnt(0)
	s_barrier
	v_mfma_f32_16x16x32_bf16 v[60:63], v[140:143], v[214:217], v[60:63]
	v_mfma_f32_16x16x32_bf16 v[56:59], v[170:173], v[214:217], v[56:59]
	v_mfma_f32_16x16x32_bf16 v[44:47], v[140:143], v[222:225], v[44:47]
	v_mfma_f32_16x16x32_bf16 v[40:43], v[170:173], v[222:225], v[40:43]
	v_mfma_f32_16x16x32_bf16 v[28:31], v[140:143], v[230:233], v[28:31]
	v_mfma_f32_16x16x32_bf16 v[24:27], v[170:173], v[230:233], v[24:27]
	v_mfma_f32_16x16x32_bf16 v[12:15], v[140:143], v[238:241], v[12:15]
	v_mfma_f32_16x16x32_bf16 v[8:11], v[170:173], v[238:241], v[8:11]
	v_mfma_f32_16x16x32_bf16 v[60:63], v[166:169], v[218:221], v[60:63]
	v_mfma_f32_16x16x32_bf16 v[56:59], v[174:177], v[218:221], v[56:59]
	v_mfma_f32_16x16x32_bf16 v[44:47], v[166:169], v[226:229], v[44:47]
	v_mfma_f32_16x16x32_bf16 v[40:43], v[174:177], v[226:229], v[40:43]
	v_mfma_f32_16x16x32_bf16 v[28:31], v[166:169], v[234:237], v[28:31]
	v_mfma_f32_16x16x32_bf16 v[24:27], v[174:177], v[234:237], v[24:27]
	v_mfma_f32_16x16x32_bf16 v[12:15], v[166:169], v[242:245], v[12:15]
	v_mfma_f32_16x16x32_bf16 v[8:11], v[174:177], v[242:245], v[8:11]
	v_mfma_f32_16x16x32_bf16 v[52:55], v[178:181], v[214:217], v[52:55]
	v_mfma_f32_16x16x32_bf16 v[48:51], v[186:189], v[214:217], v[48:51]
	v_mfma_f32_16x16x32_bf16 v[36:39], v[178:181], v[222:225], v[36:39]
	v_mfma_f32_16x16x32_bf16 v[32:35], v[186:189], v[222:225], v[32:35]
	v_mfma_f32_16x16x32_bf16 v[20:23], v[178:181], v[230:233], v[20:23]
	v_mfma_f32_16x16x32_bf16 v[16:19], v[186:189], v[230:233], v[16:19]
	v_mfma_f32_16x16x32_bf16 v[4:7], v[178:181], v[238:241], v[4:7]
	v_mfma_f32_16x16x32_bf16 v[0:3], v[186:189], v[238:241], v[0:3]
	v_mfma_f32_16x16x32_bf16 v[52:55], v[182:185], v[218:221], v[52:55]
	v_mfma_f32_16x16x32_bf16 v[48:51], v[210:213], v[218:221], v[48:51]
	v_mfma_f32_16x16x32_bf16 v[36:39], v[182:185], v[226:229], v[36:39]
	v_mfma_f32_16x16x32_bf16 v[32:35], v[210:213], v[226:229], v[32:35]
	v_mfma_f32_16x16x32_bf16 v[20:23], v[182:185], v[234:237], v[20:23]
	v_mfma_f32_16x16x32_bf16 v[16:19], v[210:213], v[234:237], v[16:19]
	v_mfma_f32_16x16x32_bf16 v[4:7], v[182:185], v[242:245], v[4:7]
	v_mfma_f32_16x16x32_bf16 v[0:3], v[210:213], v[242:245], v[0:3]
	s_barrier
	s_add_i32 s55, s55, 2
	s_add_u32 s0, s0, 0x100
	s_addc_u32 s1, s1, 0
	s_add_u32 s53, s53, 0x100
	s_addc_u32 s54, s54, 0
	s_cmp_gt_u32 s55, 13
; #define PG8_STAGE(bufoff, gbase, voff) do { _Pragma("unroll") for (int _i = 0; _i < 2; ++_i) \
;         __builtin_amdgcn_global_load_lds((const unsigned*)((const char*)(gbase) + (voff)[_i]), (PG8_LAS unsigned*)(lds + (bufoff) + ldsw + _i * 8192), 16, 0, 0); } while (0)
; #define PG8_LDA(dst, b, h) do { _Pragma("unroll") for (int m = 0; m < 4; ++m) _Pragma("unroll") for (int k = 0; k < 2; ++k) dst[m][k] = *(const PG8_LAS bf16x8*)(lds + PG8_SA(b, h) + aoff + m * 2048 + k * 1024); } while (0)
; #define PG8_LDB(dst, b, h) do { _Pragma("unroll") for (int n = 0; n < 2; ++n) _Pragma("unroll") for (int k = 0; k < 2; ++k) dst[n][k] = *(const PG8_LAS bf16x8*)(lds + PG8_SB(b, h) + boff + n * 2048 + k * 1024); } while (0)
; #define PG8_MMA(ai, bj, At, Bt) do { __builtin_amdgcn_s_setprio(1); _Pragma("unroll") for (int m = 0; m < 4; ++m) _Pragma("unroll") for (int n = 0; n < 2; ++n) _Pragma("unroll") for (int k = 0; k < 2; ++k) \
;         acc[ai][bj][m][n] = __builtin_amdgcn_mfma_f32_16x16x32_bf16(Bt[n][k], At[m][k], acc[ai][bj][m][n], 0, 0, 0); __builtin_amdgcn_s_setprio(0); } while (0)
; #define PG8_WAIT_V(n) asm volatile("s_waitcnt vmcnt(" #n ")" ::: "memory")
; #define PG8_BAR __builtin_amdgcn_s_barrier()
; template <class Epi, class Sched, bool ALIGN_EPI = false, bool SP2 = false>
; __device__ __forceinline__ void gemm_phase(PG8_LAS unsigned char* lds, const Gemm g, const Sched& S, const Epi& E) {
;     ...
;         for (int t = 0; t < nt; t += 2) {
;             const bool last = (t == nt - 2);
;             const char* a1 = cA + (size_t)(t + 1) * kstep;
;             const char* a2 = last ? nA : cA + (size_t)(t + 2) * kstep; const char* b2 = last ? nB : cB + (size_t)(t + 2) * kstep;
;             const char* a3 = a2 + kstep; const char* b3 = b2 + kstep;
;             if (last && has_next) S.a_ready(nxt);
;             if constexpr (SP2) {
;             PG8_LDB(B0, 0, 0); PG8_LDB(B1, 0, 1); PG8_SCHED; PG8_LDA(At, 0, 0); PG8_STAGE(PG8_SA(1, 1), a1 + hstep, voffA);
;             PG8_WAIT_V(8); PG8_WAIT_L(0); PG8_BAR; PG8_MMA(0, 0, At, B0); PG8_MMA(0, 1, At, B1); PG8_BAR; PG8_SCHED;
;             PG8_LDA(At, 0, 1); PG8_STAGE(PG8_SB(0, 0), b2, voffB); PG8_STAGE(PG8_SB(0, 1), b2 + hstep, voffB); PG8_STAGE(PG8_SA(0, 0), a2, voffA);
;             PG8_WAIT_V(8); PG8_WAIT_L(0); PG8_BAR; PG8_MMA(1, 0, At, B0); PG8_MMA(1, 1, At, B1); PG8_BAR; PG8_SCHED;
.LBB0_1042:
	ds_read_b128 v[140:143], v254
	ds_read_b128 v[166:169], v254 offset:1024
	ds_read_b128 v[170:173], v254 offset:2048
	ds_read_b128 v[174:177], v254 offset:3072
	ds_read_b128 v[178:181], v254 offset:16384
	ds_read_b128 v[182:185], v254 offset:17408
	ds_read_b128 v[186:189], v254 offset:18432
	ds_read_b128 v[210:213], v254 offset:19456
	s_add_u32 s2, s0, 0xfffc0080
	s_addc_u32 s3, s1, -1
	s_cmp_eq_u32 s55, 12
	s_cselect_b32 s5, s23, s3
	s_cselect_b32 s4, s51, s2
	s_cselect_b32 s3, s21, s54
	s_cselect_b32 s2, s52, s53
	s_add_i32 m0, s31, 0xc000
	ds_read_b128 v[214:217], v163
	ds_read_b128 v[218:221], v163 offset:1024
	ds_read_b128 v[222:225], v163 offset:2048
	ds_read_b128 v[226:229], v163 offset:3072
	ds_read_b128 v[230:233], v163 offset:4096
	ds_read_b128 v[234:237], v163 offset:5120
	ds_read_b128 v[238:241], v163 offset:6144
	ds_read_b128 v[242:245], v163 offset:7168
	global_load_lds_dwordx4 v136, s[0:1]
	s_add_i32 m0, s31, 0xe000
	s_nop 0
	global_load_lds_dwordx4 v138, s[0:1]
	s_waitcnt vmcnt(8)
	s_waitcnt lgkmcnt(0)
	s_barrier
	v_mfma_f32_16x16x32_bf16 v[124:127], v[140:143], v[214:217], v[124:127]
	v_mfma_f32_16x16x32_bf16 v[120:123], v[170:173], v[214:217], v[120:123]
	v_mfma_f32_16x16x32_bf16 v[108:111], v[140:143], v[222:225], v[108:111]
	v_mfma_f32_16x16x32_bf16 v[104:107], v[170:173], v[222:225], v[104:107]
	v_mfma_f32_16x16x32_bf16 v[92:95], v[140:143], v[230:233], v[92:95]
	v_mfma_f32_16x16x32_bf16 v[88:91], v[170:173], v[230:233], v[88:91]
	v_mfma_f32_16x16x32_bf16 v[76:79], v[140:143], v[238:241], v[76:79]
	v_mfma_f32_16x16x32_bf16 v[72:75], v[170:173], v[238:241], v[72:75]
	v_mfma_f32_16x16x32_bf16 v[124:127], v[166:169], v[218:221], v[124:127]
	v_mfma_f32_16x16x32_bf16 v[120:123], v[174:177], v[218:221], v[120:123]
	v_mfma_f32_16x16x32_bf16 v[108:111], v[166:169], v[226:229], v[108:111]
	v_mfma_f32_16x16x32_bf16 v[104:107], v[174:177], v[226:229], v[104:107]
	v_mfma_f32_16x16x32_bf16 v[92:95], v[166:169], v[234:237], v[92:95]
	v_mfma_f32_16x16x32_bf16 v[88:91], v[174:177], v[234:237], v[88:91]
	v_mfma_f32_16x16x32_bf16 v[76:79], v[166:169], v[242:245], v[76:79]
	v_mfma_f32_16x16x32_bf16 v[72:75], v[174:177], v[242:245], v[72:75]
	v_mfma_f32_16x16x32_bf16 v[116:119], v[178:181], v[214:217], v[116:119]
	v_mfma_f32_16x16x32_bf16 v[112:115], v[186:189], v[214:217], v[112:115]
	v_mfma_f32_16x16x32_bf16 v[100:103], v[178:181], v[222:225], v[100:103]
	v_mfma_f32_16x16x32_bf16 v[96:99], v[186:189], v[222:225], v[96:99]
	v_mfma_f32_16x16x32_bf16 v[84:87], v[178:181], v[230:233], v[84:87]
	v_mfma_f32_16x16x32_bf16 v[80:83], v[186:189], v[230:233], v[80:83]
	v_mfma_f32_16x16x32_bf16 v[68:71], v[178:181], v[238:241], v[68:71]
	v_mfma_f32_16x16x32_bf16 v[64:67], v[186:189], v[238:241], v[64:67]
	v_mfma_f32_16x16x32_bf16 v[116:119], v[182:185], v[218:221], v[116:119]
	v_mfma_f32_16x16x32_bf16 v[112:115], v[210:213], v[218:221], v[112:115]
	v_mfma_f32_16x16x32_bf16 v[100:103], v[182:185], v[226:229], v[100:103]
	v_mfma_f32_16x16x32_bf16 v[96:99], v[210:213], v[226:229], v[96:99]
	v_mfma_f32_16x16x32_bf16 v[84:87], v[182:185], v[234:237], v[84:87]
	v_mfma_f32_16x16x32_bf16 v[80:83], v[210:213], v[234:237], v[80:83]
	v_mfma_f32_16x16x32_bf16 v[68:71], v[182:185], v[242:245], v[68:71]
	v_mfma_f32_16x16x32_bf16 v[64:67], v[210:213], v[242:245], v[64:67]
	s_barrier
	s_mov_b32 m0, s33
	s_add_u32 s56, s2, 0x40000
	s_addc_u32 s57, s3, 0
	ds_read_b128 v[214:217], v163 offset:16384
	ds_read_b128 v[218:221], v163 offset:17408
	ds_read_b128 v[222:225], v163 offset:18432
	ds_read_b128 v[226:229], v163 offset:19456
	ds_read_b128 v[230:233], v163 offset:20480
	ds_read_b128 v[234:237], v163 offset:21504
	ds_read_b128 v[238:241], v163 offset:22528
	ds_read_b128 v[242:245], v163 offset:23552
	global_load_lds_dwordx4 v132, s[2:3]
	s_mov_b32 m0, s34
	s_nop 0
	global_load_lds_dwordx4 v128, s[2:3]
	s_mov_b32 m0, s35
	s_nop 0
	global_load_lds_dwordx4 v132, s[56:57]
	s_mov_b32 m0, s36
	s_nop 0
	global_load_lds_dwordx4 v128, s[56:57]
	s_mov_b32 m0, s31
	s_nop 0
	global_load_lds_dwordx4 v134, s[4:5]
	s_mov_b32 m0, s37
	s_nop 0
	global_load_lds_dwordx4 v130, s[4:5]
	s_waitcnt vmcnt(8)
	s_waitcnt lgkmcnt(0)
	s_barrier
	v_mfma_f32_16x16x32_bf16 v[60:63], v[140:143], v[214:217], v[60:63]
	v_mfma_f32_16x16x32_bf16 v[56:59], v[170:173], v[214:217], v[56:59]
	v_mfma_f32_16x16x32_bf16 v[44:47], v[140:143], v[222:225], v[44:47]
	v_mfma_f32_16x16x32_bf16 v[40:43], v[170:173], v[222:225], v[40:43]
	v_mfma_f32_16x16x32_bf16 v[28:31], v[140:143], v[230:233], v[28:31]
	v_mfma_f32_16x16x32_bf16 v[24:27], v[170:173], v[230:233], v[24:27]
	v_mfma_f32_16x16x32_bf16 v[12:15], v[140:143], v[238:241], v[12:15]
	v_mfma_f32_16x16x32_bf16 v[8:11], v[170:173], v[238:241], v[8:11]
	v_mfma_f32_16x16x32_bf16 v[60:63], v[166:169], v[218:221], v[60:63]
	v_mfma_f32_16x16x32_bf16 v[56:59], v[174:177], v[218:221], v[56:59]
	v_mfma_f32_16x16x32_bf16 v[44:47], v[166:169], v[226:229], v[44:47]
	v_mfma_f32_16x16x32_bf16 v[40:43], v[174:177], v[226:229], v[40:43]
	v_mfma_f32_16x16x32_bf16 v[28:31], v[166:169], v[234:237], v[28:31]
	v_mfma_f32_16x16x32_bf16 v[24:27], v[174:177], v[234:237], v[24:27]
	v_mfma_f32_16x16x32_bf16 v[12:15], v[166:169], v[242:245], v[12:15]
	v_mfma_f32_16x16x32_bf16 v[8:11], v[174:177], v[242:245], v[8:11]
	v_mfma_f32_16x16x32_bf16 v[52:55], v[178:181], v[214:217], v[52:55]
	v_mfma_f32_16x16x32_bf16 v[48:51], v[186:189], v[214:217], v[48:51]
	v_mfma_f32_16x16x32_bf16 v[36:39], v[178:181], v[222:225], v[36:39]
	v_mfma_f32_16x16x32_bf16 v[32:35], v[186:189], v[222:225], v[32:35]
	v_mfma_f32_16x16x32_bf16 v[20:23], v[178:181], v[230:233], v[20:23]
	v_mfma_f32_16x16x32_bf16 v[16:19], v[186:189], v[230:233], v[16:19]
	v_mfma_f32_16x16x32_bf16 v[4:7], v[178:181], v[238:241], v[4:7]
	v_mfma_f32_16x16x32_bf16 v[0:3], v[186:189], v[238:241], v[0:3]
	v_mfma_f32_16x16x32_bf16 v[52:55], v[182:185], v[218:221], v[52:55]
	v_mfma_f32_16x16x32_bf16 v[48:51], v[210:213], v[218:221], v[48:51]
	v_mfma_f32_16x16x32_bf16 v[36:39], v[182:185], v[226:229], v[36:39]
	v_mfma_f32_16x16x32_bf16 v[32:35], v[210:213], v[226:229], v[32:35]
	v_mfma_f32_16x16x32_bf16 v[20:23], v[182:185], v[234:237], v[20:23]
	v_mfma_f32_16x16x32_bf16 v[16:19], v[210:213], v[234:237], v[16:19]
	v_mfma_f32_16x16x32_bf16 v[4:7], v[182:185], v[242:245], v[4:7]
	v_mfma_f32_16x16x32_bf16 v[0:3], v[210:213], v[242:245], v[0:3]
	s_barrier
; #define PG8_STAGE(bufoff, gbase, voff) do { _Pragma("unroll") for (int _i = 0; _i < 2; ++_i) \
;         __builtin_amdgcn_global_load_lds((const unsigned*)((const char*)(gbase) + (voff)[_i]), (PG8_LAS unsigned*)(lds + (bufoff) + ldsw + _i * 8192), 16, 0, 0); } while (0)
; #define PG8_BAR __builtin_amdgcn_s_barrier()
; template <class Epi, class Sched, bool ALIGN_EPI = false, bool SP2 = false>
; __device__ __forceinline__ void gemm_phase(PG8_LAS unsigned char* lds, const Gemm g, const Sched& S, const Epi& E) {
;     ...
;             PG8_LDB(B0, 1, 0); PG8_LDB(B1, 1, 1); PG8_SCHED; PG8_LDA(At, 1, 0); PG8_STAGE(PG8_SA(0, 1), a2 + hstep, voffA);
;             PG8_WAIT_V(8); PG8_WAIT_L(0); PG8_BAR; PG8_MMA(0, 0, At, B0); PG8_MMA(0, 1, At, B1); PG8_BAR; PG8_SCHED;
;             PG8_LDA(At, 1, 1); PG8_STAGE(PG8_SB(1, 0), b3, voffB); PG8_STAGE(PG8_SB(1, 1), b3 + hstep, voffB); PG8_STAGE(PG8_SA(1, 0), a3, voffA);
;             PG8_WAIT_V(8); PG8_WAIT_L(0); PG8_BAR; PG8_MMA(1, 0, At, B0); PG8_MMA(1, 1, At, B1); PG8_BAR; PG8_SCHED;
;             } else {
;             PG8_LDB(B0, 0, 0); PG8_SCHED; PG8_LDA(At, 0, 0); PG8_STAGE(PG8_SA(1, 1), a1 + hstep, voffA);
;             PG8_WAIT_L(8); PG8_BAR; PG8_WAIT_L(0); PG8_MMA(0, 0, At, B0); PG8_BAR; PG8_SCHED;
;             PG8_LDB(B1, 0, 1); PG8_STAGE(PG8_SB(0, 0), b2, voffB);
;             PG8_BAR; PG8_WAIT_L(0); PG8_MMA(0, 1, At, B1); PG8_BAR;
;             PG8_LDA(At, 0, 1); PG8_STAGE(PG8_SA(0, 0), a2, voffA);
;             PG8_BAR; PG8_WAIT_L(0); PG8_MMA(1, 0, At, B0); PG8_BAR; PG8_SCHED;
;             PG8_STAGE(PG8_SB(0, 1), b2 + hstep, voffB);
;             PG8_WAIT_V(6); PG8_BAR; PG8_MMA(1, 1, At, B1); PG8_BAR;
;             PG8_LDB(B0, 1, 0); PG8_SCHED; PG8_LDA(At, 1, 0); PG8_STAGE(PG8_SA(0, 1), a2 + hstep, voffA);
;             PG8_WAIT_L(8); PG8_BAR; PG8_WAIT_L(0); PG8_MMA(0, 0, At, B0); PG8_BAR; PG8_SCHED;
;             PG8_LDB(B1, 1, 1); PG8_STAGE(PG8_SB(1, 0), b3, voffB);
;             PG8_BAR; PG8_WAIT_L(0); PG8_MMA(0, 1, At, B1); PG8_BAR;
;             PG8_LDA(At, 1, 1); PG8_STAGE(PG8_SA(1, 0), a3, voffA);
;             PG8_BAR; PG8_WAIT_L(0); PG8_MMA(1, 0, At, B0); PG8_BAR; PG8_SCHED;
;             PG8_STAGE(PG8_SB(1, 1), b3 + hstep, voffB);
;             PG8_WAIT_V(6); PG8_BAR; PG8_MMA(1, 1, At, B1); PG8_BAR;
;             }
;         }
;         if constexpr (ALIGN_EPI) { if (wr == 0) PG8_BAR; }
	ds_read_b128 v[140:143], v254 offset:32768
	ds_read_b128 v[166:169], v254 offset:33792
	ds_read_b128 v[170:173], v254 offset:34816
	ds_read_b128 v[174:177], v254 offset:35840
	ds_read_b128 v[178:181], v254 offset:49152
	ds_read_b128 v[182:185], v254 offset:50176
	ds_read_b128 v[186:189], v254 offset:51200
	ds_read_b128 v[210:213], v254 offset:52224
	s_add_u32 s4, s4, 0x40000
	s_addc_u32 s5, s5, 0
	s_mov_b32 m0, s38
	ds_read_b128 v[214:217], v163 offset:32768
	ds_read_b128 v[218:221], v163 offset:33792
	ds_read_b128 v[222:225], v163 offset:34816
	ds_read_b128 v[226:229], v163 offset:35840
	ds_read_b128 v[230:233], v163 offset:36864
	ds_read_b128 v[234:237], v163 offset:37888
	ds_read_b128 v[238:241], v163 offset:38912
	ds_read_b128 v[242:245], v163 offset:39936
	global_load_lds_dwordx4 v134, s[4:5]
	s_mov_b32 m0, s39
	s_nop 0
	global_load_lds_dwordx4 v130, s[4:5]
	s_waitcnt vmcnt(8)
	s_waitcnt lgkmcnt(0)
	s_barrier
	v_mfma_f32_16x16x32_bf16 v[124:127], v[140:143], v[214:217], v[124:127]
	v_mfma_f32_16x16x32_bf16 v[120:123], v[170:173], v[214:217], v[120:123]
	v_mfma_f32_16x16x32_bf16 v[108:111], v[140:143], v[222:225], v[108:111]
	v_mfma_f32_16x16x32_bf16 v[104:107], v[170:173], v[222:225], v[104:107]
	v_mfma_f32_16x16x32_bf16 v[92:95], v[140:143], v[230:233], v[92:95]
	v_mfma_f32_16x16x32_bf16 v[88:91], v[170:173], v[230:233], v[88:91]
	v_mfma_f32_16x16x32_bf16 v[76:79], v[140:143], v[238:241], v[76:79]
	v_mfma_f32_16x16x32_bf16 v[72:75], v[170:173], v[238:241], v[72:75]
	v_mfma_f32_16x16x32_bf16 v[124:127], v[166:169], v[218:221], v[124:127]
	v_mfma_f32_16x16x32_bf16 v[120:123], v[174:177], v[218:221], v[120:123]
	v_mfma_f32_16x16x32_bf16 v[108:111], v[166:169], v[226:229], v[108:111]
	v_mfma_f32_16x16x32_bf16 v[104:107], v[174:177], v[226:229], v[104:107]
	v_mfma_f32_16x16x32_bf16 v[92:95], v[166:169], v[234:237], v[92:95]
	v_mfma_f32_16x16x32_bf16 v[88:91], v[174:177], v[234:237], v[88:91]
	v_mfma_f32_16x16x32_bf16 v[76:79], v[166:169], v[242:245], v[76:79]
	v_mfma_f32_16x16x32_bf16 v[72:75], v[174:177], v[242:245], v[72:75]
	v_mfma_f32_16x16x32_bf16 v[116:119], v[178:181], v[214:217], v[116:119]
	v_mfma_f32_16x16x32_bf16 v[112:115], v[186:189], v[214:217], v[112:115]
	v_mfma_f32_16x16x32_bf16 v[100:103], v[178:181], v[222:225], v[100:103]
	v_mfma_f32_16x16x32_bf16 v[96:99], v[186:189], v[222:225], v[96:99]
	v_mfma_f32_16x16x32_bf16 v[84:87], v[178:181], v[230:233], v[84:87]
	v_mfma_f32_16x16x32_bf16 v[80:83], v[186:189], v[230:233], v[80:83]
	v_mfma_f32_16x16x32_bf16 v[68:71], v[178:181], v[238:241], v[68:71]
	v_mfma_f32_16x16x32_bf16 v[64:67], v[186:189], v[238:241], v[64:67]
	v_mfma_f32_16x16x32_bf16 v[116:119], v[182:185], v[218:221], v[116:119]
	v_mfma_f32_16x16x32_bf16 v[112:115], v[210:213], v[218:221], v[112:115]
	v_mfma_f32_16x16x32_bf16 v[100:103], v[182:185], v[226:229], v[100:103]
	v_mfma_f32_16x16x32_bf16 v[96:99], v[210:213], v[226:229], v[96:99]
	v_mfma_f32_16x16x32_bf16 v[84:87], v[182:185], v[234:237], v[84:87]
	v_mfma_f32_16x16x32_bf16 v[80:83], v[210:213], v[234:237], v[80:83]
	v_mfma_f32_16x16x32_bf16 v[68:71], v[182:185], v[242:245], v[68:71]
	v_mfma_f32_16x16x32_bf16 v[64:67], v[210:213], v[242:245], v[64:67]
	s_barrier
	s_mov_b32 m0, s43
	s_add_u32 s2, s2, 0x40080
	s_addc_u32 s3, s3, 0
	ds_read_b128 v[214:217], v163 offset:49152
	ds_read_b128 v[218:221], v163 offset:50176
	ds_read_b128 v[222:225], v163 offset:51200
	ds_read_b128 v[226:229], v163 offset:52224
	ds_read_b128 v[230:233], v163 offset:53248
	ds_read_b128 v[234:237], v163 offset:54272
	ds_read_b128 v[238:241], v163 offset:55296
	ds_read_b128 v[242:245], v163 offset:56320
	s_add_u32 s98, s2, 0xfffc0000
	s_addc_u32 s99, s3, -1
	global_load_lds_dwordx4 v132, s[98:99]
	s_mov_b32 m0, s44
	s_nop 0
	global_load_lds_dwordx4 v128, s[98:99]
	s_mov_b32 m0, s48
	s_nop 0
	global_load_lds_dwordx4 v132, s[2:3]
	s_mov_b32 m0, s49
	s_nop 0
	global_load_lds_dwordx4 v128, s[2:3]
	s_mov_b32 m0, s45
	s_nop 0
	s_add_u32 s100, s4, 0xfffc0080
	s_addc_u32 s101, s5, -1
	global_load_lds_dwordx4 v134, s[100:101]
	s_mov_b32 m0, s47
	s_nop 0
	global_load_lds_dwordx4 v130, s[100:101]
	s_waitcnt vmcnt(8)
	s_waitcnt lgkmcnt(0)
	s_barrier
	v_mfma_f32_16x16x32_bf16 v[60:63], v[140:143], v[214:217], v[60:63]
	v_mfma_f32_16x16x32_bf16 v[56:59], v[170:173], v[214:217], v[56:59]
	v_mfma_f32_16x16x32_bf16 v[44:47], v[140:143], v[222:225], v[44:47]
	v_mfma_f32_16x16x32_bf16 v[40:43], v[170:173], v[222:225], v[40:43]
	v_mfma_f32_16x16x32_bf16 v[28:31], v[140:143], v[230:233], v[28:31]
	v_mfma_f32_16x16x32_bf16 v[24:27], v[170:173], v[230:233], v[24:27]
	v_mfma_f32_16x16x32_bf16 v[12:15], v[140:143], v[238:241], v[12:15]
	v_mfma_f32_16x16x32_bf16 v[8:11], v[170:173], v[238:241], v[8:11]
	v_mfma_f32_16x16x32_bf16 v[60:63], v[166:169], v[218:221], v[60:63]
	v_mfma_f32_16x16x32_bf16 v[56:59], v[174:177], v[218:221], v[56:59]
	v_mfma_f32_16x16x32_bf16 v[44:47], v[166:169], v[226:229], v[44:47]
	v_mfma_f32_16x16x32_bf16 v[40:43], v[174:177], v[226:229], v[40:43]
	v_mfma_f32_16x16x32_bf16 v[28:31], v[166:169], v[234:237], v[28:31]
	v_mfma_f32_16x16x32_bf16 v[24:27], v[174:177], v[234:237], v[24:27]
	v_mfma_f32_16x16x32_bf16 v[12:15], v[166:169], v[242:245], v[12:15]
	v_mfma_f32_16x16x32_bf16 v[8:11], v[174:177], v[242:245], v[8:11]
	v_mfma_f32_16x16x32_bf16 v[52:55], v[178:181], v[214:217], v[52:55]
	v_mfma_f32_16x16x32_bf16 v[48:51], v[186:189], v[214:217], v[48:51]
	v_mfma_f32_16x16x32_bf16 v[36:39], v[178:181], v[222:225], v[36:39]
	v_mfma_f32_16x16x32_bf16 v[32:35], v[186:189], v[222:225], v[32:35]
	v_mfma_f32_16x16x32_bf16 v[20:23], v[178:181], v[230:233], v[20:23]
	v_mfma_f32_16x16x32_bf16 v[16:19], v[186:189], v[230:233], v[16:19]
	v_mfma_f32_16x16x32_bf16 v[4:7], v[178:181], v[238:241], v[4:7]
	v_mfma_f32_16x16x32_bf16 v[0:3], v[186:189], v[238:241], v[0:3]
	v_mfma_f32_16x16x32_bf16 v[52:55], v[182:185], v[218:221], v[52:55]
	v_mfma_f32_16x16x32_bf16 v[48:51], v[210:213], v[218:221], v[48:51]
	v_mfma_f32_16x16x32_bf16 v[36:39], v[182:185], v[226:229], v[36:39]
	v_mfma_f32_16x16x32_bf16 v[32:35], v[210:213], v[226:229], v[32:35]
	v_mfma_f32_16x16x32_bf16 v[20:23], v[182:185], v[234:237], v[20:23]
	v_mfma_f32_16x16x32_bf16 v[16:19], v[210:213], v[234:237], v[16:19]
	v_mfma_f32_16x16x32_bf16 v[4:7], v[182:185], v[242:245], v[4:7]
	v_mfma_f32_16x16x32_bf16 v[0:3], v[210:213], v[242:245], v[0:3]
	s_barrier
	s_add_i32 s55, s55, 2
	s_add_u32 s0, s0, 0x100
	s_addc_u32 s1, s1, 0
	s_add_u32 s53, s53, 0x100
	s_addc_u32 s54, s54, 0
	s_cmp_gt_u32 s55, 13
	s_cbranch_scc0 .LBB0_1042
	s_and_b64 vcc, exec, s[18:19]
	s_cbranch_vccz .LBB0_1045
	s_barrier
